# GEMM K-loops: LDS-DMA loads in saddr form (SGPR base + lane offset) where the 64-bit VGPR address was used once; 6 of 16 v_lshl_add_u64 per iteration removed
# speedup vs baseline: 1.0076x; 1.0076x over previous
.LBB0_187:
	s_ashr_i32 s15, s14, 31
	s_lshl_b64 s[16:17], s[14:15], 19
	s_add_u32 s16, s30, s16
	s_addc_u32 s17, s31, s17
	s_and_b64 s[18:19], s[0:1], exec
	s_cselect_b32 s3, s17, s25
	s_cselect_b32 s15, s16, s24
	s_ashr_i32 s13, s12, 31
	s_lshl_b64 s[18:19], s[12:13], 19
	s_add_u32 s18, s34, s18
	s_addc_u32 s19, s35, s19
	s_and_b64 s[26:27], s[0:1], exec
	s_cselect_b32 s13, s19, s23
	s_cselect_b32 s21, s18, s22
	s_add_u32 s48, s22, 0x100
	s_addc_u32 s49, s23, 0
	s_add_u32 s22, s24, 0x40080
	s_addc_u32 s23, s25, 0
	s_mov_b32 s50, -2
	s_waitcnt vmcnt(0)
	s_add_u32 s24, s22, 0xfffc0080
	s_addc_u32 s25, s23, -1
	s_add_i32 s51, 0, 0x10000
	s_cmp_eq_u32 s50, 12
	s_cselect_b32 s27, s3, s25
	s_cselect_b32 s26, s15, s24
	v_add_u32_e32 v142, s51, v144
	s_cselect_b32 s25, s13, s49
	s_cselect_b32 s24, s21, s48
	s_add_i32 s54, 0, 0x14000
	ds_read_b128 v[138:141], v142
	ds_read_b128 v[146:149], v142 offset:1024
	ds_read_b128 v[150:153], v142 offset:2048
	ds_read_b128 v[154:157], v142 offset:3072
	v_add_u32_e32 v142, s54, v144
	ds_read_b128 v[158:161], v142
	ds_read_b128 v[162:165], v142 offset:1024
	ds_read_b128 v[166:169], v142 offset:2048
	ds_read_b128 v[170:173], v142 offset:3072
	v_lshl_add_u64 v[142:143], s[22:23], 0, v[136:137]
	s_add_i32 m0, s37, 0xc000
	ds_read_b128 v[174:177], v145
	ds_read_b128 v[178:181], v145 offset:1024
	ds_read_b128 v[182:185], v145 offset:2048
	ds_read_b128 v[186:189], v145 offset:3072
	ds_read_b128 v[190:193], v145 offset:4096
	ds_read_b128 v[194:197], v145 offset:5120
	ds_read_b128 v[198:201], v145 offset:6144
	ds_read_b128 v[202:205], v145 offset:7168
	global_load_lds_dwordx4 v136, s[22:23]
	v_lshl_add_u64 v[142:143], s[22:23], 0, v[134:135]
	s_add_i32 m0, s37, 0xe000
	s_nop 0
	global_load_lds_dwordx4 v134, s[22:23]
	s_waitcnt vmcnt(8)
	s_waitcnt lgkmcnt(0)
	s_barrier
	s_setprio 1
	s_waitcnt lgkmcnt(0)
	v_mfma_f32_16x16x32_bf16 v[124:127], v[138:141], v[174:177], 0
	v_mfma_f32_16x16x32_bf16 v[120:123], v[150:153], v[174:177], 0
	v_mfma_f32_16x16x32_bf16 v[112:115], v[138:141], v[182:185], 0
	v_mfma_f32_16x16x32_bf16 v[104:107], v[150:153], v[182:185], 0
	v_mfma_f32_16x16x32_bf16 v[96:99], v[138:141], v[190:193], 0
	v_mfma_f32_16x16x32_bf16 v[88:91], v[150:153], v[190:193], 0
	v_mfma_f32_16x16x32_bf16 v[80:83], v[138:141], v[198:201], 0
	v_mfma_f32_16x16x32_bf16 v[72:75], v[150:153], v[198:201], 0
	v_mfma_f32_16x16x32_bf16 v[124:127], v[146:149], v[178:181], v[124:127]
	v_mfma_f32_16x16x32_bf16 v[120:123], v[154:157], v[178:181], v[120:123]
	v_mfma_f32_16x16x32_bf16 v[112:115], v[146:149], v[186:189], v[112:115]
	v_mfma_f32_16x16x32_bf16 v[104:107], v[154:157], v[186:189], v[104:107]
	v_mfma_f32_16x16x32_bf16 v[96:99], v[146:149], v[194:197], v[96:99]
	v_mfma_f32_16x16x32_bf16 v[88:91], v[154:157], v[194:197], v[88:91]
	v_mfma_f32_16x16x32_bf16 v[80:83], v[146:149], v[202:205], v[80:83]
	v_mfma_f32_16x16x32_bf16 v[72:75], v[154:157], v[202:205], v[72:75]
	s_setprio 0
	s_setprio 1
	v_mfma_f32_16x16x32_bf16 v[116:119], v[158:161], v[174:177], 0
	v_mfma_f32_16x16x32_bf16 v[108:111], v[166:169], v[174:177], 0
	v_mfma_f32_16x16x32_bf16 v[100:103], v[158:161], v[182:185], 0
	v_mfma_f32_16x16x32_bf16 v[92:95], v[166:169], v[182:185], 0
	v_mfma_f32_16x16x32_bf16 v[84:87], v[158:161], v[190:193], 0
	v_mfma_f32_16x16x32_bf16 v[76:79], v[166:169], v[190:193], 0
	v_mfma_f32_16x16x32_bf16 v[68:71], v[158:161], v[198:201], 0
	v_mfma_f32_16x16x32_bf16 v[64:67], v[166:169], v[198:201], 0
	v_mfma_f32_16x16x32_bf16 v[116:119], v[162:165], v[178:181], v[116:119]
	v_mfma_f32_16x16x32_bf16 v[108:111], v[170:173], v[178:181], v[108:111]
	v_mfma_f32_16x16x32_bf16 v[100:103], v[162:165], v[186:189], v[100:103]
	v_mfma_f32_16x16x32_bf16 v[92:95], v[170:173], v[186:189], v[92:95]
	v_mfma_f32_16x16x32_bf16 v[84:87], v[162:165], v[194:197], v[84:87]
	v_mfma_f32_16x16x32_bf16 v[76:79], v[170:173], v[194:197], v[76:79]
	v_mfma_f32_16x16x32_bf16 v[68:71], v[162:165], v[202:205], v[68:71]
	v_mfma_f32_16x16x32_bf16 v[64:67], v[170:173], v[202:205], v[64:67]
	s_setprio 0
	s_barrier
	s_add_i32 s51, s51, s36
	v_lshl_add_u64 v[142:143], s[24:25], 0, v[232:233]
	s_mov_b32 m0, s51
	ds_read_b128 v[174:177], v145 offset:16384
	ds_read_b128 v[178:181], v145 offset:17408
	ds_read_b128 v[182:185], v145 offset:18432
	ds_read_b128 v[186:189], v145 offset:19456
	ds_read_b128 v[190:193], v145 offset:20480
	ds_read_b128 v[194:197], v145 offset:21504
	ds_read_b128 v[198:201], v145 offset:22528
	ds_read_b128 v[202:205], v145 offset:23552
	global_load_lds_dwordx4 v232, s[24:25]
	s_add_i32 m0, s51, 0x2000
	s_add_u32 s52, s24, 0x40000
	v_lshl_add_u64 v[206:207], s[24:25], 0, v[132:133]
	s_addc_u32 s53, s25, 0
	s_add_i32 s51, s54, s36
	global_load_lds_dwordx4 v132, s[24:25]
	s_mov_b32 m0, s51
	v_lshl_add_u64 v[210:211], s[26:27], 0, v[130:131]
	global_load_lds_dwordx4 v232, s[52:53]
	s_add_i32 m0, s51, 0x2000
	s_nop 0
	global_load_lds_dwordx4 v132, s[52:53]
	v_lshl_add_u64 v[208:209], s[26:27], 0, v[128:129]
	s_waitcnt vmcnt(6)
	s_waitcnt lgkmcnt(0)
	s_barrier
	s_setprio 1
	s_waitcnt lgkmcnt(0)
	v_mfma_f32_16x16x32_bf16 v[60:63], v[138:141], v[174:177], 0
	v_mfma_f32_16x16x32_bf16 v[56:59], v[150:153], v[174:177], 0
	v_mfma_f32_16x16x32_bf16 v[48:51], v[138:141], v[182:185], 0
	v_mfma_f32_16x16x32_bf16 v[40:43], v[150:153], v[182:185], 0
	v_mfma_f32_16x16x32_bf16 v[32:35], v[138:141], v[190:193], 0
	v_mfma_f32_16x16x32_bf16 v[24:27], v[150:153], v[190:193], 0
	v_mfma_f32_16x16x32_bf16 v[16:19], v[138:141], v[198:201], 0
	v_mfma_f32_16x16x32_bf16 v[8:11], v[150:153], v[198:201], 0
	v_mfma_f32_16x16x32_bf16 v[60:63], v[146:149], v[178:181], v[60:63]
	v_mfma_f32_16x16x32_bf16 v[56:59], v[154:157], v[178:181], v[56:59]
	v_mfma_f32_16x16x32_bf16 v[48:51], v[146:149], v[186:189], v[48:51]
	v_mfma_f32_16x16x32_bf16 v[40:43], v[154:157], v[186:189], v[40:43]
	v_mfma_f32_16x16x32_bf16 v[32:35], v[146:149], v[194:197], v[32:35]
	v_mfma_f32_16x16x32_bf16 v[24:27], v[154:157], v[194:197], v[24:27]
	v_mfma_f32_16x16x32_bf16 v[16:19], v[146:149], v[202:205], v[16:19]
	v_mfma_f32_16x16x32_bf16 v[8:11], v[154:157], v[202:205], v[8:11]
	s_setprio 0
	s_setprio 1
	v_mfma_f32_16x16x32_bf16 v[52:55], v[158:161], v[174:177], 0
	v_mfma_f32_16x16x32_bf16 v[44:47], v[166:169], v[174:177], 0
	v_mfma_f32_16x16x32_bf16 v[36:39], v[158:161], v[182:185], 0
	v_mfma_f32_16x16x32_bf16 v[28:31], v[166:169], v[182:185], 0
	v_mfma_f32_16x16x32_bf16 v[20:23], v[158:161], v[190:193], 0
	v_mfma_f32_16x16x32_bf16 v[12:15], v[166:169], v[190:193], 0
	v_mfma_f32_16x16x32_bf16 v[4:7], v[158:161], v[198:201], 0
	v_mfma_f32_16x16x32_bf16 v[0:3], v[166:169], v[198:201], 0
	v_mfma_f32_16x16x32_bf16 v[52:55], v[162:165], v[178:181], v[52:55]
	v_mfma_f32_16x16x32_bf16 v[44:47], v[170:173], v[178:181], v[44:47]
	v_mfma_f32_16x16x32_bf16 v[36:39], v[162:165], v[186:189], v[36:39]
	v_mfma_f32_16x16x32_bf16 v[28:31], v[170:173], v[186:189], v[28:31]
	v_mfma_f32_16x16x32_bf16 v[20:23], v[162:165], v[194:197], v[20:23]
	v_mfma_f32_16x16x32_bf16 v[12:15], v[170:173], v[194:197], v[12:15]
	v_mfma_f32_16x16x32_bf16 v[4:7], v[162:165], v[202:205], v[4:7]
	v_mfma_f32_16x16x32_bf16 v[0:3], v[170:173], v[202:205], v[0:3]
	s_setprio 0
	s_barrier
	s_branch .Lzmid_1
.LBB0_188:
	s_add_u32 s24, s22, 0xfffc0080
	s_addc_u32 s25, s23, -1
	s_add_i32 s51, 0, 0x10000
	s_cmp_eq_u32 s50, 12
	s_cselect_b32 s27, s3, s25
	s_cselect_b32 s26, s15, s24
	v_add_u32_e32 v142, s51, v144
	s_cselect_b32 s25, s13, s49
	s_cselect_b32 s24, s21, s48
	s_add_i32 s54, 0, 0x14000
	ds_read_b128 v[138:141], v142
	ds_read_b128 v[146:149], v142 offset:1024
	ds_read_b128 v[150:153], v142 offset:2048
	ds_read_b128 v[154:157], v142 offset:3072
	v_add_u32_e32 v142, s54, v144
	ds_read_b128 v[158:161], v142
	ds_read_b128 v[162:165], v142 offset:1024
	ds_read_b128 v[166:169], v142 offset:2048
	ds_read_b128 v[170:173], v142 offset:3072
	v_lshl_add_u64 v[142:143], s[22:23], 0, v[136:137]
	s_add_i32 m0, s37, 0xc000
	ds_read_b128 v[174:177], v145
	ds_read_b128 v[178:181], v145 offset:1024
	ds_read_b128 v[182:185], v145 offset:2048
	ds_read_b128 v[186:189], v145 offset:3072
	ds_read_b128 v[190:193], v145 offset:4096
	ds_read_b128 v[194:197], v145 offset:5120
	ds_read_b128 v[198:201], v145 offset:6144
	ds_read_b128 v[202:205], v145 offset:7168
	global_load_lds_dwordx4 v136, s[22:23]
	v_lshl_add_u64 v[142:143], s[22:23], 0, v[134:135]
	s_add_i32 m0, s37, 0xe000
	s_nop 0
	global_load_lds_dwordx4 v134, s[22:23]
	s_waitcnt vmcnt(8)
	s_waitcnt lgkmcnt(0)
	s_barrier
	s_setprio 1
	s_waitcnt lgkmcnt(0)
	v_mfma_f32_16x16x32_bf16 v[124:127], v[138:141], v[174:177], v[124:127]
	v_mfma_f32_16x16x32_bf16 v[120:123], v[150:153], v[174:177], v[120:123]
	v_mfma_f32_16x16x32_bf16 v[112:115], v[138:141], v[182:185], v[112:115]
	v_mfma_f32_16x16x32_bf16 v[104:107], v[150:153], v[182:185], v[104:107]
	v_mfma_f32_16x16x32_bf16 v[96:99], v[138:141], v[190:193], v[96:99]
	v_mfma_f32_16x16x32_bf16 v[88:91], v[150:153], v[190:193], v[88:91]
	v_mfma_f32_16x16x32_bf16 v[80:83], v[138:141], v[198:201], v[80:83]
	v_mfma_f32_16x16x32_bf16 v[72:75], v[150:153], v[198:201], v[72:75]
	v_mfma_f32_16x16x32_bf16 v[124:127], v[146:149], v[178:181], v[124:127]
	v_mfma_f32_16x16x32_bf16 v[120:123], v[154:157], v[178:181], v[120:123]
	v_mfma_f32_16x16x32_bf16 v[112:115], v[146:149], v[186:189], v[112:115]
	v_mfma_f32_16x16x32_bf16 v[104:107], v[154:157], v[186:189], v[104:107]
	v_mfma_f32_16x16x32_bf16 v[96:99], v[146:149], v[194:197], v[96:99]
	v_mfma_f32_16x16x32_bf16 v[88:91], v[154:157], v[194:197], v[88:91]
	v_mfma_f32_16x16x32_bf16 v[80:83], v[146:149], v[202:205], v[80:83]
	v_mfma_f32_16x16x32_bf16 v[72:75], v[154:157], v[202:205], v[72:75]
	s_setprio 0
	s_setprio 1
	v_mfma_f32_16x16x32_bf16 v[116:119], v[158:161], v[174:177], v[116:119]
	v_mfma_f32_16x16x32_bf16 v[108:111], v[166:169], v[174:177], v[108:111]
	v_mfma_f32_16x16x32_bf16 v[100:103], v[158:161], v[182:185], v[100:103]
	v_mfma_f32_16x16x32_bf16 v[92:95], v[166:169], v[182:185], v[92:95]
	v_mfma_f32_16x16x32_bf16 v[84:87], v[158:161], v[190:193], v[84:87]
	v_mfma_f32_16x16x32_bf16 v[76:79], v[166:169], v[190:193], v[76:79]
	v_mfma_f32_16x16x32_bf16 v[68:71], v[158:161], v[198:201], v[68:71]
	v_mfma_f32_16x16x32_bf16 v[64:67], v[166:169], v[198:201], v[64:67]
	v_mfma_f32_16x16x32_bf16 v[116:119], v[162:165], v[178:181], v[116:119]
	v_mfma_f32_16x16x32_bf16 v[108:111], v[170:173], v[178:181], v[108:111]
	v_mfma_f32_16x16x32_bf16 v[100:103], v[162:165], v[186:189], v[100:103]
	v_mfma_f32_16x16x32_bf16 v[92:95], v[170:173], v[186:189], v[92:95]
	v_mfma_f32_16x16x32_bf16 v[84:87], v[162:165], v[194:197], v[84:87]
	v_mfma_f32_16x16x32_bf16 v[76:79], v[170:173], v[194:197], v[76:79]
	v_mfma_f32_16x16x32_bf16 v[68:71], v[162:165], v[202:205], v[68:71]
	v_mfma_f32_16x16x32_bf16 v[64:67], v[170:173], v[202:205], v[64:67]
	s_setprio 0
	s_barrier
	s_add_i32 s51, s51, s36
	v_lshl_add_u64 v[142:143], s[24:25], 0, v[232:233]
	s_mov_b32 m0, s51
	ds_read_b128 v[174:177], v145 offset:16384
	ds_read_b128 v[178:181], v145 offset:17408
	ds_read_b128 v[182:185], v145 offset:18432
	ds_read_b128 v[186:189], v145 offset:19456
	ds_read_b128 v[190:193], v145 offset:20480
	ds_read_b128 v[194:197], v145 offset:21504
	ds_read_b128 v[198:201], v145 offset:22528
	ds_read_b128 v[202:205], v145 offset:23552
	global_load_lds_dwordx4 v232, s[24:25]
	s_add_i32 m0, s51, 0x2000
	s_add_u32 s52, s24, 0x40000
	v_lshl_add_u64 v[206:207], s[24:25], 0, v[132:133]
	s_addc_u32 s53, s25, 0
	s_add_i32 s51, s54, s36
	global_load_lds_dwordx4 v132, s[24:25]
	s_mov_b32 m0, s51
	v_lshl_add_u64 v[210:211], s[26:27], 0, v[130:131]
	global_load_lds_dwordx4 v232, s[52:53]
	s_add_i32 m0, s51, 0x2000
	s_nop 0
	global_load_lds_dwordx4 v132, s[52:53]
	v_lshl_add_u64 v[208:209], s[26:27], 0, v[128:129]
	s_waitcnt vmcnt(6)
	s_waitcnt lgkmcnt(0)
	s_barrier
	s_setprio 1
	s_waitcnt lgkmcnt(0)
	v_mfma_f32_16x16x32_bf16 v[60:63], v[138:141], v[174:177], v[60:63]
	v_mfma_f32_16x16x32_bf16 v[56:59], v[150:153], v[174:177], v[56:59]
	v_mfma_f32_16x16x32_bf16 v[48:51], v[138:141], v[182:185], v[48:51]
	v_mfma_f32_16x16x32_bf16 v[40:43], v[150:153], v[182:185], v[40:43]
	v_mfma_f32_16x16x32_bf16 v[32:35], v[138:141], v[190:193], v[32:35]
	v_mfma_f32_16x16x32_bf16 v[24:27], v[150:153], v[190:193], v[24:27]
	v_mfma_f32_16x16x32_bf16 v[16:19], v[138:141], v[198:201], v[16:19]
	v_mfma_f32_16x16x32_bf16 v[8:11], v[150:153], v[198:201], v[8:11]
	v_mfma_f32_16x16x32_bf16 v[60:63], v[146:149], v[178:181], v[60:63]
	v_mfma_f32_16x16x32_bf16 v[56:59], v[154:157], v[178:181], v[56:59]
	v_mfma_f32_16x16x32_bf16 v[48:51], v[146:149], v[186:189], v[48:51]
	v_mfma_f32_16x16x32_bf16 v[40:43], v[154:157], v[186:189], v[40:43]
	v_mfma_f32_16x16x32_bf16 v[32:35], v[146:149], v[194:197], v[32:35]
	v_mfma_f32_16x16x32_bf16 v[24:27], v[154:157], v[194:197], v[24:27]
	v_mfma_f32_16x16x32_bf16 v[16:19], v[146:149], v[202:205], v[16:19]
	v_mfma_f32_16x16x32_bf16 v[8:11], v[154:157], v[202:205], v[8:11]
	s_setprio 0
	s_setprio 1
	v_mfma_f32_16x16x32_bf16 v[52:55], v[158:161], v[174:177], v[52:55]
	v_mfma_f32_16x16x32_bf16 v[44:47], v[166:169], v[174:177], v[44:47]
	v_mfma_f32_16x16x32_bf16 v[36:39], v[158:161], v[182:185], v[36:39]
	v_mfma_f32_16x16x32_bf16 v[28:31], v[166:169], v[182:185], v[28:31]
	v_mfma_f32_16x16x32_bf16 v[20:23], v[158:161], v[190:193], v[20:23]
	v_mfma_f32_16x16x32_bf16 v[12:15], v[166:169], v[190:193], v[12:15]
	v_mfma_f32_16x16x32_bf16 v[4:7], v[158:161], v[198:201], v[4:7]
	v_mfma_f32_16x16x32_bf16 v[0:3], v[166:169], v[198:201], v[0:3]
	v_mfma_f32_16x16x32_bf16 v[52:55], v[162:165], v[178:181], v[52:55]
	v_mfma_f32_16x16x32_bf16 v[44:47], v[170:173], v[178:181], v[44:47]
	v_mfma_f32_16x16x32_bf16 v[36:39], v[162:165], v[186:189], v[36:39]
	v_mfma_f32_16x16x32_bf16 v[28:31], v[170:173], v[186:189], v[28:31]
	v_mfma_f32_16x16x32_bf16 v[20:23], v[162:165], v[194:197], v[20:23]
	v_mfma_f32_16x16x32_bf16 v[12:15], v[170:173], v[194:197], v[12:15]
	v_mfma_f32_16x16x32_bf16 v[4:7], v[162:165], v[202:205], v[4:7]
	v_mfma_f32_16x16x32_bf16 v[0:3], v[170:173], v[202:205], v[0:3]
	s_setprio 0
	s_barrier
.Lzmid_1:
	s_add_i32 s51, 0, 0x18000
	s_add_i32 s52, 0, 0x1c000
	v_add_u32_e32 v154, s51, v144
	v_add_u32_e32 v170, s52, v144
	ds_read_b128 v[138:141], v154
	ds_read_b128 v[146:149], v154 offset:1024
	ds_read_b128 v[150:153], v154 offset:2048
	ds_read_b128 v[154:157], v154 offset:3072
	ds_read_b128 v[158:161], v170
	ds_read_b128 v[162:165], v170 offset:1024
	ds_read_b128 v[166:169], v170 offset:2048
	ds_read_b128 v[170:173], v170 offset:3072
	s_add_u32 s26, s26, 0x40000
	s_addc_u32 s27, s27, 0
	s_mov_b32 m0, s37
	s_nop 0
	global_load_lds_dwordx4 v[208:209], off
	s_mov_b32 m0, s38
	s_nop 0
	global_load_lds_dwordx4 v[210:211], off
	s_mov_b32 m0, s39
	ds_read_b128 v[174:177], v145 offset:32768
	ds_read_b128 v[178:181], v145 offset:33792
	ds_read_b128 v[182:185], v145 offset:34816
	ds_read_b128 v[186:189], v145 offset:35840
	ds_read_b128 v[190:193], v145 offset:36864
	ds_read_b128 v[194:197], v145 offset:37888
	ds_read_b128 v[198:201], v145 offset:38912
	ds_read_b128 v[202:205], v145 offset:39936
	global_load_lds_dwordx4 v128, s[26:27]
	s_mov_b32 m0, s40
	s_nop 0
	global_load_lds_dwordx4 v130, s[26:27]
	s_waitcnt vmcnt(8)
	s_waitcnt lgkmcnt(0)
	s_barrier
	s_setprio 1
	s_waitcnt lgkmcnt(0)
	v_mfma_f32_16x16x32_bf16 v[124:127], v[138:141], v[174:177], v[124:127]
	v_mfma_f32_16x16x32_bf16 v[120:123], v[150:153], v[174:177], v[120:123]
	v_mfma_f32_16x16x32_bf16 v[112:115], v[138:141], v[182:185], v[112:115]
	v_mfma_f32_16x16x32_bf16 v[104:107], v[150:153], v[182:185], v[104:107]
	v_mfma_f32_16x16x32_bf16 v[96:99], v[138:141], v[190:193], v[96:99]
	v_mfma_f32_16x16x32_bf16 v[88:91], v[150:153], v[190:193], v[88:91]
	v_mfma_f32_16x16x32_bf16 v[80:83], v[138:141], v[198:201], v[80:83]
	v_mfma_f32_16x16x32_bf16 v[72:75], v[150:153], v[198:201], v[72:75]
	v_mfma_f32_16x16x32_bf16 v[124:127], v[146:149], v[178:181], v[124:127]
	v_mfma_f32_16x16x32_bf16 v[120:123], v[154:157], v[178:181], v[120:123]
	v_mfma_f32_16x16x32_bf16 v[112:115], v[146:149], v[186:189], v[112:115]
	v_mfma_f32_16x16x32_bf16 v[104:107], v[154:157], v[186:189], v[104:107]
	v_mfma_f32_16x16x32_bf16 v[96:99], v[146:149], v[194:197], v[96:99]
	v_mfma_f32_16x16x32_bf16 v[88:91], v[154:157], v[194:197], v[88:91]
	v_mfma_f32_16x16x32_bf16 v[80:83], v[146:149], v[202:205], v[80:83]
	v_mfma_f32_16x16x32_bf16 v[72:75], v[154:157], v[202:205], v[72:75]
	s_setprio 0
	s_setprio 1
	v_mfma_f32_16x16x32_bf16 v[116:119], v[158:161], v[174:177], v[116:119]
	v_mfma_f32_16x16x32_bf16 v[108:111], v[166:169], v[174:177], v[108:111]
	v_mfma_f32_16x16x32_bf16 v[100:103], v[158:161], v[182:185], v[100:103]
	v_mfma_f32_16x16x32_bf16 v[92:95], v[166:169], v[182:185], v[92:95]
	v_mfma_f32_16x16x32_bf16 v[84:87], v[158:161], v[190:193], v[84:87]
	v_mfma_f32_16x16x32_bf16 v[76:79], v[166:169], v[190:193], v[76:79]
	v_mfma_f32_16x16x32_bf16 v[68:71], v[158:161], v[198:201], v[68:71]
	v_mfma_f32_16x16x32_bf16 v[64:67], v[166:169], v[198:201], v[64:67]
	v_mfma_f32_16x16x32_bf16 v[116:119], v[162:165], v[178:181], v[116:119]
	v_mfma_f32_16x16x32_bf16 v[108:111], v[170:173], v[178:181], v[108:111]
	v_mfma_f32_16x16x32_bf16 v[100:103], v[162:165], v[186:189], v[100:103]
	v_mfma_f32_16x16x32_bf16 v[92:95], v[170:173], v[186:189], v[92:95]
	v_mfma_f32_16x16x32_bf16 v[84:87], v[162:165], v[194:197], v[84:87]
	v_mfma_f32_16x16x32_bf16 v[76:79], v[170:173], v[194:197], v[76:79]
	v_mfma_f32_16x16x32_bf16 v[68:71], v[162:165], v[202:205], v[68:71]
	v_mfma_f32_16x16x32_bf16 v[64:67], v[170:173], v[202:205], v[64:67]
	s_setprio 0
	s_barrier
	s_add_i32 s26, s51, s36
	v_lshl_add_u64 v[142:143], v[142:143], 0, s[94:95]
	s_mov_b32 m0, s26
	ds_read_b128 v[174:177], v145 offset:49152
	ds_read_b128 v[178:181], v145 offset:50176
	ds_read_b128 v[182:185], v145 offset:51200
	ds_read_b128 v[186:189], v145 offset:52224
	ds_read_b128 v[190:193], v145 offset:53248
	ds_read_b128 v[194:197], v145 offset:54272
	ds_read_b128 v[198:201], v145 offset:55296
	ds_read_b128 v[202:205], v145 offset:56320
	global_load_lds_dwordx4 v[142:143], off
	s_add_i32 m0, s26, 0x2000
	s_add_u32 s24, s24, 0x40080
	v_lshl_add_u64 v[142:143], v[206:207], 0, s[94:95]
	s_addc_u32 s25, s25, 0
	s_add_i32 s26, s52, s36
	global_load_lds_dwordx4 v[142:143], off
	s_mov_b32 m0, s26
	s_nop 0
	global_load_lds_dwordx4 v232, s[24:25]
	s_add_i32 m0, s26, 0x2000
	s_nop 0
	global_load_lds_dwordx4 v132, s[24:25]
	v_lshl_add_u64 v[142:143], v[208:209], 0, s[94:95]
	s_mov_b32 m0, s43
	s_nop 0
	global_load_lds_dwordx4 v[142:143], off
	v_lshl_add_u64 v[142:143], v[210:211], 0, s[94:95]
	s_mov_b32 m0, s44
	s_nop 0
	global_load_lds_dwordx4 v[142:143], off
	s_waitcnt vmcnt(8)
	s_waitcnt lgkmcnt(0)
	s_barrier
	s_setprio 1
	s_waitcnt lgkmcnt(0)
	v_mfma_f32_16x16x32_bf16 v[60:63], v[138:141], v[174:177], v[60:63]
	v_mfma_f32_16x16x32_bf16 v[56:59], v[150:153], v[174:177], v[56:59]
	v_mfma_f32_16x16x32_bf16 v[48:51], v[138:141], v[182:185], v[48:51]
	v_mfma_f32_16x16x32_bf16 v[40:43], v[150:153], v[182:185], v[40:43]
	v_mfma_f32_16x16x32_bf16 v[32:35], v[138:141], v[190:193], v[32:35]
	v_mfma_f32_16x16x32_bf16 v[24:27], v[150:153], v[190:193], v[24:27]
	v_mfma_f32_16x16x32_bf16 v[16:19], v[138:141], v[198:201], v[16:19]
	v_mfma_f32_16x16x32_bf16 v[8:11], v[150:153], v[198:201], v[8:11]
	v_mfma_f32_16x16x32_bf16 v[60:63], v[146:149], v[178:181], v[60:63]
	v_mfma_f32_16x16x32_bf16 v[56:59], v[154:157], v[178:181], v[56:59]
	v_mfma_f32_16x16x32_bf16 v[48:51], v[146:149], v[186:189], v[48:51]
	v_mfma_f32_16x16x32_bf16 v[40:43], v[154:157], v[186:189], v[40:43]
	v_mfma_f32_16x16x32_bf16 v[32:35], v[146:149], v[194:197], v[32:35]
	v_mfma_f32_16x16x32_bf16 v[24:27], v[154:157], v[194:197], v[24:27]
	v_mfma_f32_16x16x32_bf16 v[16:19], v[146:149], v[202:205], v[16:19]
	v_mfma_f32_16x16x32_bf16 v[8:11], v[154:157], v[202:205], v[8:11]
	s_setprio 0
	s_setprio 1
	v_mfma_f32_16x16x32_bf16 v[52:55], v[158:161], v[174:177], v[52:55]
	v_mfma_f32_16x16x32_bf16 v[44:47], v[166:169], v[174:177], v[44:47]
	v_mfma_f32_16x16x32_bf16 v[36:39], v[158:161], v[182:185], v[36:39]
	v_mfma_f32_16x16x32_bf16 v[28:31], v[166:169], v[182:185], v[28:31]
	v_mfma_f32_16x16x32_bf16 v[20:23], v[158:161], v[190:193], v[20:23]
	v_mfma_f32_16x16x32_bf16 v[12:15], v[166:169], v[190:193], v[12:15]
	v_mfma_f32_16x16x32_bf16 v[4:7], v[158:161], v[198:201], v[4:7]
	v_mfma_f32_16x16x32_bf16 v[0:3], v[166:169], v[198:201], v[0:3]
	v_mfma_f32_16x16x32_bf16 v[52:55], v[162:165], v[178:181], v[52:55]
	v_mfma_f32_16x16x32_bf16 v[44:47], v[170:173], v[178:181], v[44:47]
	v_mfma_f32_16x16x32_bf16 v[36:39], v[162:165], v[186:189], v[36:39]
	v_mfma_f32_16x16x32_bf16 v[28:31], v[170:173], v[186:189], v[28:31]
	v_mfma_f32_16x16x32_bf16 v[20:23], v[162:165], v[194:197], v[20:23]
	v_mfma_f32_16x16x32_bf16 v[12:15], v[170:173], v[194:197], v[12:15]
	v_mfma_f32_16x16x32_bf16 v[4:7], v[162:165], v[202:205], v[4:7]
	v_mfma_f32_16x16x32_bf16 v[0:3], v[170:173], v[202:205], v[0:3]
	s_setprio 0
	s_barrier
	s_add_i32 s50, s50, 2
	s_add_u32 s48, s48, 0x100
	s_addc_u32 s49, s49, 0
	s_add_u32 s22, s22, 0x100
	s_addc_u32 s23, s23, 0
	s_cmp_gt_u32 s50, 13
	s_cbranch_scc0 .LBB0_188
	s_and_b64 vcc, exec, s[10:11]
	s_cbranch_vccz .LBB0_191
	s_barrier

.LBB0_911:
	s_ashr_i32 s15, s14, 31
	s_lshl_b64 s[16:17], s[14:15], 19
	s_add_u32 s16, s30, s16
	s_addc_u32 s17, s31, s17
	s_and_b64 s[18:19], s[2:3], exec
	s_cselect_b32 s5, s17, s25
	s_cselect_b32 s15, s16, s24
	s_ashr_i32 s13, s12, 31
	s_lshl_b64 s[18:19], s[12:13], 19
	s_add_u32 s18, s34, s18
	s_addc_u32 s19, s35, s19
	s_and_b64 s[26:27], s[2:3], exec
	s_cselect_b32 s13, s19, s23
	s_cselect_b32 s21, s18, s22
	s_add_u32 s48, s22, 0x100
	s_addc_u32 s49, s23, 0
	s_add_u32 s22, s24, 0x40080
	s_addc_u32 s23, s25, 0
	s_mov_b32 s50, -2
	s_add_u32 s24, s22, 0xfffc0080
	s_addc_u32 s25, s23, -1
	s_add_i32 s51, 0, 0x10000
	s_cmp_eq_u32 s50, 12
	s_cselect_b32 s27, s5, s25
	s_cselect_b32 s26, s15, s24
	v_add_u32_e32 v142, s51, v144
	s_cselect_b32 s25, s13, s49
	s_cselect_b32 s24, s21, s48
	s_add_i32 s54, 0, 0x14000
	ds_read_b128 v[138:141], v142
	ds_read_b128 v[146:149], v142 offset:1024
	ds_read_b128 v[150:153], v142 offset:2048
	ds_read_b128 v[154:157], v142 offset:3072
	v_add_u32_e32 v142, s54, v144
	ds_read_b128 v[158:161], v142
	ds_read_b128 v[162:165], v142 offset:1024
	ds_read_b128 v[166:169], v142 offset:2048
	ds_read_b128 v[170:173], v142 offset:3072
	v_lshl_add_u64 v[142:143], s[22:23], 0, v[136:137]
	s_add_i32 m0, s37, 0xc000
	ds_read_b128 v[174:177], v145
	ds_read_b128 v[178:181], v145 offset:1024
	ds_read_b128 v[182:185], v145 offset:2048
	ds_read_b128 v[186:189], v145 offset:3072
	ds_read_b128 v[190:193], v145 offset:4096
	ds_read_b128 v[194:197], v145 offset:5120
	ds_read_b128 v[198:201], v145 offset:6144
	ds_read_b128 v[202:205], v145 offset:7168
	global_load_lds_dwordx4 v136, s[22:23]
	v_lshl_add_u64 v[142:143], s[22:23], 0, v[134:135]
	s_add_i32 m0, s37, 0xe000
	s_nop 0
	global_load_lds_dwordx4 v134, s[22:23]
	s_waitcnt vmcnt(8)
	s_waitcnt lgkmcnt(0)
	s_barrier
	s_setprio 1
	s_waitcnt lgkmcnt(0)
	v_mfma_f32_16x16x32_bf16 v[124:127], v[138:141], v[174:177], 0
	v_mfma_f32_16x16x32_bf16 v[120:123], v[150:153], v[174:177], 0
	v_mfma_f32_16x16x32_bf16 v[108:111], v[138:141], v[182:185], 0
	v_mfma_f32_16x16x32_bf16 v[104:107], v[150:153], v[182:185], 0
	v_mfma_f32_16x16x32_bf16 v[92:95], v[138:141], v[190:193], 0
	v_mfma_f32_16x16x32_bf16 v[88:91], v[150:153], v[190:193], 0
	v_mfma_f32_16x16x32_bf16 v[76:79], v[138:141], v[198:201], 0
	v_mfma_f32_16x16x32_bf16 v[72:75], v[150:153], v[198:201], 0
	v_mfma_f32_16x16x32_bf16 v[124:127], v[146:149], v[178:181], v[124:127]
	v_mfma_f32_16x16x32_bf16 v[120:123], v[154:157], v[178:181], v[120:123]
	v_mfma_f32_16x16x32_bf16 v[108:111], v[146:149], v[186:189], v[108:111]
	v_mfma_f32_16x16x32_bf16 v[104:107], v[154:157], v[186:189], v[104:107]
	v_mfma_f32_16x16x32_bf16 v[92:95], v[146:149], v[194:197], v[92:95]
	v_mfma_f32_16x16x32_bf16 v[88:91], v[154:157], v[194:197], v[88:91]
	v_mfma_f32_16x16x32_bf16 v[76:79], v[146:149], v[202:205], v[76:79]
	v_mfma_f32_16x16x32_bf16 v[72:75], v[154:157], v[202:205], v[72:75]
	s_setprio 0
	s_setprio 1
	v_mfma_f32_16x16x32_bf16 v[116:119], v[158:161], v[174:177], 0
	v_mfma_f32_16x16x32_bf16 v[112:115], v[166:169], v[174:177], 0
	v_mfma_f32_16x16x32_bf16 v[100:103], v[158:161], v[182:185], 0
	v_mfma_f32_16x16x32_bf16 v[96:99], v[166:169], v[182:185], 0
	v_mfma_f32_16x16x32_bf16 v[84:87], v[158:161], v[190:193], 0
	v_mfma_f32_16x16x32_bf16 v[80:83], v[166:169], v[190:193], 0
	v_mfma_f32_16x16x32_bf16 v[68:71], v[158:161], v[198:201], 0
	v_mfma_f32_16x16x32_bf16 v[64:67], v[166:169], v[198:201], 0
	v_mfma_f32_16x16x32_bf16 v[116:119], v[162:165], v[178:181], v[116:119]
	v_mfma_f32_16x16x32_bf16 v[112:115], v[170:173], v[178:181], v[112:115]
	v_mfma_f32_16x16x32_bf16 v[100:103], v[162:165], v[186:189], v[100:103]
	v_mfma_f32_16x16x32_bf16 v[96:99], v[170:173], v[186:189], v[96:99]
	v_mfma_f32_16x16x32_bf16 v[84:87], v[162:165], v[194:197], v[84:87]
	v_mfma_f32_16x16x32_bf16 v[80:83], v[170:173], v[194:197], v[80:83]
	v_mfma_f32_16x16x32_bf16 v[68:71], v[162:165], v[202:205], v[68:71]
	v_mfma_f32_16x16x32_bf16 v[64:67], v[170:173], v[202:205], v[64:67]
	s_setprio 0
	s_barrier
	s_add_i32 s51, s51, s36
	v_lshl_add_u64 v[142:143], s[24:25], 0, v[232:233]
	s_mov_b32 m0, s51
	ds_read_b128 v[174:177], v145 offset:16384
	ds_read_b128 v[178:181], v145 offset:17408
	ds_read_b128 v[182:185], v145 offset:18432
	ds_read_b128 v[186:189], v145 offset:19456
	ds_read_b128 v[190:193], v145 offset:20480
	ds_read_b128 v[194:197], v145 offset:21504
	ds_read_b128 v[198:201], v145 offset:22528
	ds_read_b128 v[202:205], v145 offset:23552
	global_load_lds_dwordx4 v232, s[24:25]
	s_add_i32 m0, s51, 0x2000
	s_add_u32 s52, s24, 0x40000
	v_lshl_add_u64 v[206:207], s[24:25], 0, v[132:133]
	s_addc_u32 s53, s25, 0
	s_add_i32 s51, s54, s36
	global_load_lds_dwordx4 v132, s[24:25]
	s_mov_b32 m0, s51
	v_lshl_add_u64 v[210:211], s[26:27], 0, v[130:131]
	global_load_lds_dwordx4 v232, s[52:53]
	s_add_i32 m0, s51, 0x2000
	s_nop 0
	global_load_lds_dwordx4 v132, s[52:53]
	v_lshl_add_u64 v[208:209], s[26:27], 0, v[128:129]
	s_waitcnt vmcnt(6)
	s_waitcnt lgkmcnt(0)
	s_barrier
	s_setprio 1
	s_waitcnt lgkmcnt(0)
	v_mfma_f32_16x16x32_bf16 v[60:63], v[138:141], v[174:177], 0
	v_mfma_f32_16x16x32_bf16 v[56:59], v[150:153], v[174:177], 0
	v_mfma_f32_16x16x32_bf16 v[44:47], v[138:141], v[182:185], 0
	v_mfma_f32_16x16x32_bf16 v[40:43], v[150:153], v[182:185], 0
	v_mfma_f32_16x16x32_bf16 v[28:31], v[138:141], v[190:193], 0
	v_mfma_f32_16x16x32_bf16 v[24:27], v[150:153], v[190:193], 0
	v_mfma_f32_16x16x32_bf16 v[12:15], v[138:141], v[198:201], 0
	v_mfma_f32_16x16x32_bf16 v[8:11], v[150:153], v[198:201], 0
	v_mfma_f32_16x16x32_bf16 v[60:63], v[146:149], v[178:181], v[60:63]
	v_mfma_f32_16x16x32_bf16 v[56:59], v[154:157], v[178:181], v[56:59]
	v_mfma_f32_16x16x32_bf16 v[44:47], v[146:149], v[186:189], v[44:47]
	v_mfma_f32_16x16x32_bf16 v[40:43], v[154:157], v[186:189], v[40:43]
	v_mfma_f32_16x16x32_bf16 v[28:31], v[146:149], v[194:197], v[28:31]
	v_mfma_f32_16x16x32_bf16 v[24:27], v[154:157], v[194:197], v[24:27]
	v_mfma_f32_16x16x32_bf16 v[12:15], v[146:149], v[202:205], v[12:15]
	v_mfma_f32_16x16x32_bf16 v[8:11], v[154:157], v[202:205], v[8:11]
	s_setprio 0
	s_setprio 1
	v_mfma_f32_16x16x32_bf16 v[52:55], v[158:161], v[174:177], 0
	v_mfma_f32_16x16x32_bf16 v[48:51], v[166:169], v[174:177], 0
	v_mfma_f32_16x16x32_bf16 v[36:39], v[158:161], v[182:185], 0
	v_mfma_f32_16x16x32_bf16 v[32:35], v[166:169], v[182:185], 0
	v_mfma_f32_16x16x32_bf16 v[20:23], v[158:161], v[190:193], 0
	v_mfma_f32_16x16x32_bf16 v[16:19], v[166:169], v[190:193], 0
	v_mfma_f32_16x16x32_bf16 v[4:7], v[158:161], v[198:201], 0
	v_mfma_f32_16x16x32_bf16 v[0:3], v[166:169], v[198:201], 0
	v_mfma_f32_16x16x32_bf16 v[52:55], v[162:165], v[178:181], v[52:55]
	v_mfma_f32_16x16x32_bf16 v[48:51], v[170:173], v[178:181], v[48:51]
	v_mfma_f32_16x16x32_bf16 v[36:39], v[162:165], v[186:189], v[36:39]
	v_mfma_f32_16x16x32_bf16 v[32:35], v[170:173], v[186:189], v[32:35]
	v_mfma_f32_16x16x32_bf16 v[20:23], v[162:165], v[194:197], v[20:23]
	v_mfma_f32_16x16x32_bf16 v[16:19], v[170:173], v[194:197], v[16:19]
	v_mfma_f32_16x16x32_bf16 v[4:7], v[162:165], v[202:205], v[4:7]
	v_mfma_f32_16x16x32_bf16 v[0:3], v[170:173], v[202:205], v[0:3]
	s_setprio 0
	s_barrier
	s_branch .Lzmid_2
.LBB0_912:
	s_add_u32 s24, s22, 0xfffc0080
	s_addc_u32 s25, s23, -1
	s_add_i32 s51, 0, 0x10000
	s_cmp_eq_u32 s50, 12
	s_cselect_b32 s27, s5, s25
	s_cselect_b32 s26, s15, s24
	v_add_u32_e32 v142, s51, v144
	s_cselect_b32 s25, s13, s49
	s_cselect_b32 s24, s21, s48
	s_add_i32 s54, 0, 0x14000
	ds_read_b128 v[138:141], v142
	ds_read_b128 v[146:149], v142 offset:1024
	ds_read_b128 v[150:153], v142 offset:2048
	ds_read_b128 v[154:157], v142 offset:3072
	v_add_u32_e32 v142, s54, v144
	ds_read_b128 v[158:161], v142
	ds_read_b128 v[162:165], v142 offset:1024
	ds_read_b128 v[166:169], v142 offset:2048
	ds_read_b128 v[170:173], v142 offset:3072
	v_lshl_add_u64 v[142:143], s[22:23], 0, v[136:137]
	s_add_i32 m0, s37, 0xc000
	ds_read_b128 v[174:177], v145
	ds_read_b128 v[178:181], v145 offset:1024
	ds_read_b128 v[182:185], v145 offset:2048
	ds_read_b128 v[186:189], v145 offset:3072
	ds_read_b128 v[190:193], v145 offset:4096
	ds_read_b128 v[194:197], v145 offset:5120
	ds_read_b128 v[198:201], v145 offset:6144
	ds_read_b128 v[202:205], v145 offset:7168
	global_load_lds_dwordx4 v136, s[22:23]
	v_lshl_add_u64 v[142:143], s[22:23], 0, v[134:135]
	s_add_i32 m0, s37, 0xe000
	s_nop 0
	global_load_lds_dwordx4 v134, s[22:23]
	s_waitcnt vmcnt(8)
	s_waitcnt lgkmcnt(0)
	s_barrier
	s_setprio 1
	s_waitcnt lgkmcnt(0)
	v_mfma_f32_16x16x32_bf16 v[124:127], v[138:141], v[174:177], v[124:127]
	v_mfma_f32_16x16x32_bf16 v[120:123], v[150:153], v[174:177], v[120:123]
	v_mfma_f32_16x16x32_bf16 v[108:111], v[138:141], v[182:185], v[108:111]
	v_mfma_f32_16x16x32_bf16 v[104:107], v[150:153], v[182:185], v[104:107]
	v_mfma_f32_16x16x32_bf16 v[92:95], v[138:141], v[190:193], v[92:95]
	v_mfma_f32_16x16x32_bf16 v[88:91], v[150:153], v[190:193], v[88:91]
	v_mfma_f32_16x16x32_bf16 v[76:79], v[138:141], v[198:201], v[76:79]
	v_mfma_f32_16x16x32_bf16 v[72:75], v[150:153], v[198:201], v[72:75]
	v_mfma_f32_16x16x32_bf16 v[124:127], v[146:149], v[178:181], v[124:127]
	v_mfma_f32_16x16x32_bf16 v[120:123], v[154:157], v[178:181], v[120:123]
	v_mfma_f32_16x16x32_bf16 v[108:111], v[146:149], v[186:189], v[108:111]
	v_mfma_f32_16x16x32_bf16 v[104:107], v[154:157], v[186:189], v[104:107]
	v_mfma_f32_16x16x32_bf16 v[92:95], v[146:149], v[194:197], v[92:95]
	v_mfma_f32_16x16x32_bf16 v[88:91], v[154:157], v[194:197], v[88:91]
	v_mfma_f32_16x16x32_bf16 v[76:79], v[146:149], v[202:205], v[76:79]
	v_mfma_f32_16x16x32_bf16 v[72:75], v[154:157], v[202:205], v[72:75]
	s_setprio 0
	s_setprio 1
	v_mfma_f32_16x16x32_bf16 v[116:119], v[158:161], v[174:177], v[116:119]
	v_mfma_f32_16x16x32_bf16 v[112:115], v[166:169], v[174:177], v[112:115]
	v_mfma_f32_16x16x32_bf16 v[100:103], v[158:161], v[182:185], v[100:103]
	v_mfma_f32_16x16x32_bf16 v[96:99], v[166:169], v[182:185], v[96:99]
	v_mfma_f32_16x16x32_bf16 v[84:87], v[158:161], v[190:193], v[84:87]
	v_mfma_f32_16x16x32_bf16 v[80:83], v[166:169], v[190:193], v[80:83]
	v_mfma_f32_16x16x32_bf16 v[68:71], v[158:161], v[198:201], v[68:71]
	v_mfma_f32_16x16x32_bf16 v[64:67], v[166:169], v[198:201], v[64:67]
	v_mfma_f32_16x16x32_bf16 v[116:119], v[162:165], v[178:181], v[116:119]
	v_mfma_f32_16x16x32_bf16 v[112:115], v[170:173], v[178:181], v[112:115]
	v_mfma_f32_16x16x32_bf16 v[100:103], v[162:165], v[186:189], v[100:103]
	v_mfma_f32_16x16x32_bf16 v[96:99], v[170:173], v[186:189], v[96:99]
	v_mfma_f32_16x16x32_bf16 v[84:87], v[162:165], v[194:197], v[84:87]
	v_mfma_f32_16x16x32_bf16 v[80:83], v[170:173], v[194:197], v[80:83]
	v_mfma_f32_16x16x32_bf16 v[68:71], v[162:165], v[202:205], v[68:71]
	v_mfma_f32_16x16x32_bf16 v[64:67], v[170:173], v[202:205], v[64:67]
	s_setprio 0
	s_barrier
	s_add_i32 s51, s51, s36
	v_lshl_add_u64 v[142:143], s[24:25], 0, v[232:233]
	s_mov_b32 m0, s51
	ds_read_b128 v[174:177], v145 offset:16384
	ds_read_b128 v[178:181], v145 offset:17408
	ds_read_b128 v[182:185], v145 offset:18432
	ds_read_b128 v[186:189], v145 offset:19456
	ds_read_b128 v[190:193], v145 offset:20480
	ds_read_b128 v[194:197], v145 offset:21504
	ds_read_b128 v[198:201], v145 offset:22528
	ds_read_b128 v[202:205], v145 offset:23552
	global_load_lds_dwordx4 v232, s[24:25]
	s_add_i32 m0, s51, 0x2000
	s_add_u32 s52, s24, 0x40000
	v_lshl_add_u64 v[206:207], s[24:25], 0, v[132:133]
	s_addc_u32 s53, s25, 0
	s_add_i32 s51, s54, s36
	global_load_lds_dwordx4 v132, s[24:25]
	s_mov_b32 m0, s51
	v_lshl_add_u64 v[210:211], s[26:27], 0, v[130:131]
	global_load_lds_dwordx4 v232, s[52:53]
	s_add_i32 m0, s51, 0x2000
	s_nop 0
	global_load_lds_dwordx4 v132, s[52:53]
	v_lshl_add_u64 v[208:209], s[26:27], 0, v[128:129]
	s_waitcnt vmcnt(6)
	s_waitcnt lgkmcnt(0)
	s_barrier
	s_setprio 1
	s_waitcnt lgkmcnt(0)
	v_mfma_f32_16x16x32_bf16 v[60:63], v[138:141], v[174:177], v[60:63]
	v_mfma_f32_16x16x32_bf16 v[56:59], v[150:153], v[174:177], v[56:59]
	v_mfma_f32_16x16x32_bf16 v[44:47], v[138:141], v[182:185], v[44:47]
	v_mfma_f32_16x16x32_bf16 v[40:43], v[150:153], v[182:185], v[40:43]
	v_mfma_f32_16x16x32_bf16 v[28:31], v[138:141], v[190:193], v[28:31]
	v_mfma_f32_16x16x32_bf16 v[24:27], v[150:153], v[190:193], v[24:27]
	v_mfma_f32_16x16x32_bf16 v[12:15], v[138:141], v[198:201], v[12:15]
	v_mfma_f32_16x16x32_bf16 v[8:11], v[150:153], v[198:201], v[8:11]
	v_mfma_f32_16x16x32_bf16 v[60:63], v[146:149], v[178:181], v[60:63]
	v_mfma_f32_16x16x32_bf16 v[56:59], v[154:157], v[178:181], v[56:59]
	v_mfma_f32_16x16x32_bf16 v[44:47], v[146:149], v[186:189], v[44:47]
	v_mfma_f32_16x16x32_bf16 v[40:43], v[154:157], v[186:189], v[40:43]
	v_mfma_f32_16x16x32_bf16 v[28:31], v[146:149], v[194:197], v[28:31]
	v_mfma_f32_16x16x32_bf16 v[24:27], v[154:157], v[194:197], v[24:27]
	v_mfma_f32_16x16x32_bf16 v[12:15], v[146:149], v[202:205], v[12:15]
	v_mfma_f32_16x16x32_bf16 v[8:11], v[154:157], v[202:205], v[8:11]
	s_setprio 0
	s_setprio 1
	v_mfma_f32_16x16x32_bf16 v[52:55], v[158:161], v[174:177], v[52:55]
	v_mfma_f32_16x16x32_bf16 v[48:51], v[166:169], v[174:177], v[48:51]
	v_mfma_f32_16x16x32_bf16 v[36:39], v[158:161], v[182:185], v[36:39]
	v_mfma_f32_16x16x32_bf16 v[32:35], v[166:169], v[182:185], v[32:35]
	v_mfma_f32_16x16x32_bf16 v[20:23], v[158:161], v[190:193], v[20:23]
	v_mfma_f32_16x16x32_bf16 v[16:19], v[166:169], v[190:193], v[16:19]
	v_mfma_f32_16x16x32_bf16 v[4:7], v[158:161], v[198:201], v[4:7]
	v_mfma_f32_16x16x32_bf16 v[0:3], v[166:169], v[198:201], v[0:3]
	v_mfma_f32_16x16x32_bf16 v[52:55], v[162:165], v[178:181], v[52:55]
	v_mfma_f32_16x16x32_bf16 v[48:51], v[170:173], v[178:181], v[48:51]
	v_mfma_f32_16x16x32_bf16 v[36:39], v[162:165], v[186:189], v[36:39]
	v_mfma_f32_16x16x32_bf16 v[32:35], v[170:173], v[186:189], v[32:35]
	v_mfma_f32_16x16x32_bf16 v[20:23], v[162:165], v[194:197], v[20:23]
	v_mfma_f32_16x16x32_bf16 v[16:19], v[170:173], v[194:197], v[16:19]
	v_mfma_f32_16x16x32_bf16 v[4:7], v[162:165], v[202:205], v[4:7]
	v_mfma_f32_16x16x32_bf16 v[0:3], v[170:173], v[202:205], v[0:3]
	s_setprio 0
	s_barrier
.Lzmid_2:
	s_add_i32 s51, 0, 0x18000
	s_add_i32 s52, 0, 0x1c000
	v_add_u32_e32 v154, s51, v144
	v_add_u32_e32 v170, s52, v144
	ds_read_b128 v[138:141], v154
	ds_read_b128 v[146:149], v154 offset:1024
	ds_read_b128 v[150:153], v154 offset:2048
	ds_read_b128 v[154:157], v154 offset:3072
	ds_read_b128 v[158:161], v170
	ds_read_b128 v[162:165], v170 offset:1024
	ds_read_b128 v[166:169], v170 offset:2048
	ds_read_b128 v[170:173], v170 offset:3072
	s_add_u32 s26, s26, 0x40000
	s_addc_u32 s27, s27, 0
	s_mov_b32 m0, s37
	s_nop 0
	global_load_lds_dwordx4 v[208:209], off
	s_mov_b32 m0, s38
	s_nop 0
	global_load_lds_dwordx4 v[210:211], off
	s_mov_b32 m0, s39
	ds_read_b128 v[174:177], v145 offset:32768
	ds_read_b128 v[178:181], v145 offset:33792
	ds_read_b128 v[182:185], v145 offset:34816
	ds_read_b128 v[186:189], v145 offset:35840
	ds_read_b128 v[190:193], v145 offset:36864
	ds_read_b128 v[194:197], v145 offset:37888
	ds_read_b128 v[198:201], v145 offset:38912
	ds_read_b128 v[202:205], v145 offset:39936
	global_load_lds_dwordx4 v128, s[26:27]
	s_mov_b32 m0, s40
	s_nop 0
	global_load_lds_dwordx4 v130, s[26:27]
	s_waitcnt vmcnt(8)
	s_waitcnt lgkmcnt(0)
	s_barrier
	s_setprio 1
	s_waitcnt lgkmcnt(0)
	v_mfma_f32_16x16x32_bf16 v[124:127], v[138:141], v[174:177], v[124:127]
	v_mfma_f32_16x16x32_bf16 v[120:123], v[150:153], v[174:177], v[120:123]
	v_mfma_f32_16x16x32_bf16 v[108:111], v[138:141], v[182:185], v[108:111]
	v_mfma_f32_16x16x32_bf16 v[104:107], v[150:153], v[182:185], v[104:107]
	v_mfma_f32_16x16x32_bf16 v[92:95], v[138:141], v[190:193], v[92:95]
	v_mfma_f32_16x16x32_bf16 v[88:91], v[150:153], v[190:193], v[88:91]
	v_mfma_f32_16x16x32_bf16 v[76:79], v[138:141], v[198:201], v[76:79]
	v_mfma_f32_16x16x32_bf16 v[72:75], v[150:153], v[198:201], v[72:75]
	v_mfma_f32_16x16x32_bf16 v[124:127], v[146:149], v[178:181], v[124:127]
	v_mfma_f32_16x16x32_bf16 v[120:123], v[154:157], v[178:181], v[120:123]
	v_mfma_f32_16x16x32_bf16 v[108:111], v[146:149], v[186:189], v[108:111]
	v_mfma_f32_16x16x32_bf16 v[104:107], v[154:157], v[186:189], v[104:107]
	v_mfma_f32_16x16x32_bf16 v[92:95], v[146:149], v[194:197], v[92:95]
	v_mfma_f32_16x16x32_bf16 v[88:91], v[154:157], v[194:197], v[88:91]
	v_mfma_f32_16x16x32_bf16 v[76:79], v[146:149], v[202:205], v[76:79]
	v_mfma_f32_16x16x32_bf16 v[72:75], v[154:157], v[202:205], v[72:75]
	s_setprio 0
	s_setprio 1
	v_mfma_f32_16x16x32_bf16 v[116:119], v[158:161], v[174:177], v[116:119]
	v_mfma_f32_16x16x32_bf16 v[112:115], v[166:169], v[174:177], v[112:115]
	v_mfma_f32_16x16x32_bf16 v[100:103], v[158:161], v[182:185], v[100:103]
	v_mfma_f32_16x16x32_bf16 v[96:99], v[166:169], v[182:185], v[96:99]
	v_mfma_f32_16x16x32_bf16 v[84:87], v[158:161], v[190:193], v[84:87]
	v_mfma_f32_16x16x32_bf16 v[80:83], v[166:169], v[190:193], v[80:83]
	v_mfma_f32_16x16x32_bf16 v[68:71], v[158:161], v[198:201], v[68:71]
	v_mfma_f32_16x16x32_bf16 v[64:67], v[166:169], v[198:201], v[64:67]
	v_mfma_f32_16x16x32_bf16 v[116:119], v[162:165], v[178:181], v[116:119]
	v_mfma_f32_16x16x32_bf16 v[112:115], v[170:173], v[178:181], v[112:115]
	v_mfma_f32_16x16x32_bf16 v[100:103], v[162:165], v[186:189], v[100:103]
	v_mfma_f32_16x16x32_bf16 v[96:99], v[170:173], v[186:189], v[96:99]
	v_mfma_f32_16x16x32_bf16 v[84:87], v[162:165], v[194:197], v[84:87]
	v_mfma_f32_16x16x32_bf16 v[80:83], v[170:173], v[194:197], v[80:83]
	v_mfma_f32_16x16x32_bf16 v[68:71], v[162:165], v[202:205], v[68:71]
	v_mfma_f32_16x16x32_bf16 v[64:67], v[170:173], v[202:205], v[64:67]
	s_setprio 0
	s_barrier
	s_add_i32 s26, s51, s36
	v_lshl_add_u64 v[142:143], v[142:143], 0, s[94:95]
	s_mov_b32 m0, s26
	ds_read_b128 v[174:177], v145 offset:49152
	ds_read_b128 v[178:181], v145 offset:50176
	ds_read_b128 v[182:185], v145 offset:51200
	ds_read_b128 v[186:189], v145 offset:52224
	ds_read_b128 v[190:193], v145 offset:53248
	ds_read_b128 v[194:197], v145 offset:54272
	ds_read_b128 v[198:201], v145 offset:55296
	ds_read_b128 v[202:205], v145 offset:56320
	global_load_lds_dwordx4 v[142:143], off
	s_add_i32 m0, s26, 0x2000
	s_add_u32 s24, s24, 0x40080
	v_lshl_add_u64 v[142:143], v[206:207], 0, s[94:95]
	s_addc_u32 s25, s25, 0
	s_add_i32 s26, s52, s36
	global_load_lds_dwordx4 v[142:143], off
	s_mov_b32 m0, s26
	s_nop 0
	global_load_lds_dwordx4 v232, s[24:25]
	s_add_i32 m0, s26, 0x2000
	s_nop 0
	global_load_lds_dwordx4 v132, s[24:25]
	v_lshl_add_u64 v[142:143], v[208:209], 0, s[94:95]
	s_mov_b32 m0, s43
	s_nop 0
	global_load_lds_dwordx4 v[142:143], off
	v_lshl_add_u64 v[142:143], v[210:211], 0, s[94:95]
	s_mov_b32 m0, s44
	s_nop 0
	global_load_lds_dwordx4 v[142:143], off
	s_waitcnt vmcnt(8)
	s_waitcnt lgkmcnt(0)
	s_barrier
	s_setprio 1
	s_waitcnt lgkmcnt(0)
	v_mfma_f32_16x16x32_bf16 v[60:63], v[138:141], v[174:177], v[60:63]
	v_mfma_f32_16x16x32_bf16 v[56:59], v[150:153], v[174:177], v[56:59]
	v_mfma_f32_16x16x32_bf16 v[44:47], v[138:141], v[182:185], v[44:47]
	v_mfma_f32_16x16x32_bf16 v[40:43], v[150:153], v[182:185], v[40:43]
	v_mfma_f32_16x16x32_bf16 v[28:31], v[138:141], v[190:193], v[28:31]
	v_mfma_f32_16x16x32_bf16 v[24:27], v[150:153], v[190:193], v[24:27]
	v_mfma_f32_16x16x32_bf16 v[12:15], v[138:141], v[198:201], v[12:15]
	v_mfma_f32_16x16x32_bf16 v[8:11], v[150:153], v[198:201], v[8:11]
	v_mfma_f32_16x16x32_bf16 v[60:63], v[146:149], v[178:181], v[60:63]
	v_mfma_f32_16x16x32_bf16 v[56:59], v[154:157], v[178:181], v[56:59]
	v_mfma_f32_16x16x32_bf16 v[44:47], v[146:149], v[186:189], v[44:47]
	v_mfma_f32_16x16x32_bf16 v[40:43], v[154:157], v[186:189], v[40:43]
	v_mfma_f32_16x16x32_bf16 v[28:31], v[146:149], v[194:197], v[28:31]
	v_mfma_f32_16x16x32_bf16 v[24:27], v[154:157], v[194:197], v[24:27]
	v_mfma_f32_16x16x32_bf16 v[12:15], v[146:149], v[202:205], v[12:15]
	v_mfma_f32_16x16x32_bf16 v[8:11], v[154:157], v[202:205], v[8:11]
	s_setprio 0
	s_setprio 1
	v_mfma_f32_16x16x32_bf16 v[52:55], v[158:161], v[174:177], v[52:55]
	v_mfma_f32_16x16x32_bf16 v[48:51], v[166:169], v[174:177], v[48:51]
	v_mfma_f32_16x16x32_bf16 v[36:39], v[158:161], v[182:185], v[36:39]
	v_mfma_f32_16x16x32_bf16 v[32:35], v[166:169], v[182:185], v[32:35]
	v_mfma_f32_16x16x32_bf16 v[20:23], v[158:161], v[190:193], v[20:23]
	v_mfma_f32_16x16x32_bf16 v[16:19], v[166:169], v[190:193], v[16:19]
	v_mfma_f32_16x16x32_bf16 v[4:7], v[158:161], v[198:201], v[4:7]
	v_mfma_f32_16x16x32_bf16 v[0:3], v[166:169], v[198:201], v[0:3]
	v_mfma_f32_16x16x32_bf16 v[52:55], v[162:165], v[178:181], v[52:55]
	v_mfma_f32_16x16x32_bf16 v[48:51], v[170:173], v[178:181], v[48:51]
	v_mfma_f32_16x16x32_bf16 v[36:39], v[162:165], v[186:189], v[36:39]
	v_mfma_f32_16x16x32_bf16 v[32:35], v[170:173], v[186:189], v[32:35]
	v_mfma_f32_16x16x32_bf16 v[20:23], v[162:165], v[194:197], v[20:23]
	v_mfma_f32_16x16x32_bf16 v[16:19], v[170:173], v[194:197], v[16:19]
	v_mfma_f32_16x16x32_bf16 v[4:7], v[162:165], v[202:205], v[4:7]
	v_mfma_f32_16x16x32_bf16 v[0:3], v[170:173], v[202:205], v[0:3]
	s_setprio 0
	s_barrier
	s_add_i32 s50, s50, 2
	s_add_u32 s48, s48, 0x100
	s_addc_u32 s49, s49, 0
	s_add_u32 s22, s22, 0x100
	s_addc_u32 s23, s23, 0
	s_cmp_gt_u32 s50, 13
	s_cbranch_scc0 .LBB0_912
	s_and_b64 vcc, exec, s[10:11]
	s_cbranch_vccz .LBB0_915
	s_barrier

.LBB0_1018:
	s_ashr_i32 s15, s14, 31
	s_ashr_i32 s13, s12, 31
	s_lshl_b64 s[16:17], s[14:15], 19
	s_lshl_b64 s[18:19], s[12:13], 9
	s_add_u32 s13, s34, s16
	s_addc_u32 s15, s35, s17
	s_add_u32 s16, s13, s18
	s_addc_u32 s17, s15, s19
	s_and_b64 s[18:19], s[2:3], exec
	s_cselect_b32 s29, s17, s23
	s_cselect_b32 s28, s16, s22
	s_lshl_b32 s13, s12, 2
	s_add_i32 s18, s13, s51
	s_ashr_i32 s19, s18, 31
	s_lshl_b64 s[18:19], s[18:19], 17
	s_add_u32 s18, s36, s18
	s_addc_u32 s19, s37, s19
	s_and_b64 s[26:27], s[2:3], exec
	s_cselect_b32 s27, s19, s25
	s_cselect_b32 s26, s18, s24
	s_add_i32 s15, 0, 0x10000
	s_add_i32 s21, 0, 0x14000
	v_add_u32_e32 v253, 0x10000, v174
	v_add_u32_e32 v252, 0x14000, v174
	ds_read_b128 v[128:131], v253
	ds_read_b128 v[132:135], v253 offset:1024
	ds_read_b128 v[136:139], v253 offset:2048
	ds_read_b128 v[140:143], v253 offset:3072
	ds_read_b128 v[144:147], v252
	ds_read_b128 v[148:151], v252 offset:1024
	ds_read_b128 v[152:155], v252 offset:2048
	ds_read_b128 v[156:159], v252 offset:3072
	s_add_u32 s52, s22, 0x40080
	s_addc_u32 s53, s23, 0
	s_add_i32 s55, s39, 0xc000
	s_waitcnt vmcnt(0)
	s_mov_b32 m0, s55
	s_add_i32 s13, s39, 0xe000
	ds_read_b128 v[168:171], v175
	ds_read_b128 v[176:179], v175 offset:1024
	ds_read_b128 v[180:183], v175 offset:2048
	ds_read_b128 v[184:187], v175 offset:3072
	ds_read_b128 v[188:191], v175 offset:4096
	ds_read_b128 v[192:195], v175 offset:5120
	ds_read_b128 v[196:199], v175 offset:6144
	ds_read_b128 v[200:203], v175 offset:7168
	global_load_lds_dwordx4 v160, s[52:53]
	s_mov_b32 m0, s13
	s_nop 0
	global_load_lds_dwordx4 v162, s[52:53]
	s_waitcnt vmcnt(8)
	s_waitcnt lgkmcnt(0)
	s_barrier
	s_setprio 1
	s_waitcnt lgkmcnt(0)
	v_mfma_f32_16x16x32_bf16 v[0:3], v[128:131], v[168:171], 0
	v_mfma_f32_16x16x32_bf16 v[4:7], v[136:139], v[168:171], 0
	v_mfma_f32_16x16x32_bf16 v[16:19], v[128:131], v[180:183], 0
	v_mfma_f32_16x16x32_bf16 v[20:23], v[136:139], v[180:183], 0
	v_mfma_f32_16x16x32_bf16 v[32:35], v[128:131], v[188:191], 0
	v_mfma_f32_16x16x32_bf16 v[36:39], v[136:139], v[188:191], 0
	v_mfma_f32_16x16x32_bf16 v[48:51], v[128:131], v[196:199], 0
	v_mfma_f32_16x16x32_bf16 v[52:55], v[136:139], v[196:199], 0
	v_mfma_f32_16x16x32_bf16 v[0:3], v[132:135], v[176:179], v[0:3]
	v_mfma_f32_16x16x32_bf16 v[4:7], v[140:143], v[176:179], v[4:7]
	v_mfma_f32_16x16x32_bf16 v[16:19], v[132:135], v[184:187], v[16:19]
	v_mfma_f32_16x16x32_bf16 v[20:23], v[140:143], v[184:187], v[20:23]
	v_mfma_f32_16x16x32_bf16 v[32:35], v[132:135], v[192:195], v[32:35]
	v_mfma_f32_16x16x32_bf16 v[36:39], v[140:143], v[192:195], v[36:39]
	v_mfma_f32_16x16x32_bf16 v[48:51], v[132:135], v[200:203], v[48:51]
	v_mfma_f32_16x16x32_bf16 v[52:55], v[140:143], v[200:203], v[52:55]
	s_setprio 0
	s_setprio 1
	v_mfma_f32_16x16x32_bf16 v[8:11], v[144:147], v[168:171], 0
	v_mfma_f32_16x16x32_bf16 v[12:15], v[152:155], v[168:171], 0
	v_mfma_f32_16x16x32_bf16 v[8:11], v[148:151], v[176:179], v[8:11]
	v_mfma_f32_16x16x32_bf16 v[12:15], v[156:159], v[176:179], v[12:15]
	v_mfma_f32_16x16x32_bf16 v[24:27], v[144:147], v[180:183], 0
	v_mfma_f32_16x16x32_bf16 v[28:31], v[152:155], v[180:183], 0
	v_mfma_f32_16x16x32_bf16 v[24:27], v[148:151], v[184:187], v[24:27]
	v_mfma_f32_16x16x32_bf16 v[28:31], v[156:159], v[184:187], v[28:31]
	v_mfma_f32_16x16x32_bf16 v[40:43], v[144:147], v[188:191], 0
	v_mfma_f32_16x16x32_bf16 v[44:47], v[152:155], v[188:191], 0
	v_mfma_f32_16x16x32_bf16 v[40:43], v[148:151], v[192:195], v[40:43]
	v_mfma_f32_16x16x32_bf16 v[44:47], v[156:159], v[192:195], v[44:47]
	v_mfma_f32_16x16x32_bf16 v[56:59], v[144:147], v[196:199], 0
	v_mfma_f32_16x16x32_bf16 v[60:63], v[152:155], v[196:199], 0
	v_mfma_f32_16x16x32_bf16 v[56:59], v[148:151], v[200:203], v[56:59]
	v_mfma_f32_16x16x32_bf16 v[60:63], v[156:159], v[200:203], v[60:63]
	s_setprio 0
	s_barrier
	s_add_i32 s53, s15, s38
	s_mov_b64 s[58:59], 0x100
	s_add_i32 s15, s53, 0x2000
	s_add_u32 s68, s24, s58
	s_addc_u32 s69, s25, s59
	s_mov_b32 m0, s53
	s_add_u32 s70, s24, s58
	s_addc_u32 s71, s25, s59
	s_add_u32 s56, s24, 0x10100
	ds_read_b128 v[168:171], v175 offset:16384
	ds_read_b128 v[176:179], v175 offset:17408
	ds_read_b128 v[180:183], v175 offset:18432
	ds_read_b128 v[184:187], v175 offset:19456
	ds_read_b128 v[188:191], v175 offset:20480
	ds_read_b128 v[192:195], v175 offset:21504
	ds_read_b128 v[196:199], v175 offset:22528
	ds_read_b128 v[200:203], v175 offset:23552
	global_load_lds_dwordx4 v232, s[68:69]
	s_mov_b32 m0, s15
	s_addc_u32 s57, s25, 0
	s_add_i32 s21, s21, s38
	global_load_lds_dwordx4 v164, s[70:71]
	s_mov_b32 m0, s21
	s_add_i32 s52, s21, 0x2000
	global_load_lds_dwordx4 v232, s[56:57]
	s_mov_b32 m0, s52
	s_nop 0
	global_load_lds_dwordx4 v164, s[56:57]
	s_add_u32 s68, s22, s58
	s_addc_u32 s69, s23, s59
	s_mov_b32 m0, s39
	s_nop 0
	global_load_lds_dwordx4 v160, s[68:69]
	s_add_u32 s68, s22, s58
	s_addc_u32 s69, s23, s59
	s_mov_b32 m0, s40
	s_nop 0
	global_load_lds_dwordx4 v162, s[68:69]
	s_waitcnt vmcnt(8)
	s_waitcnt lgkmcnt(0)
	s_barrier
	s_setprio 1
	s_waitcnt lgkmcnt(0)
	v_mfma_f32_16x16x32_bf16 v[64:67], v[128:131], v[168:171], 0
	v_mfma_f32_16x16x32_bf16 v[80:83], v[128:131], v[180:183], 0
	v_mfma_f32_16x16x32_bf16 v[96:99], v[128:131], v[188:191], 0
	v_mfma_f32_16x16x32_bf16 v[112:115], v[128:131], v[196:199], 0
	v_mfma_f32_16x16x32_bf16 v[64:67], v[132:135], v[176:179], v[64:67]
	v_mfma_f32_16x16x32_bf16 v[68:71], v[136:139], v[168:171], 0
	v_mfma_f32_16x16x32_bf16 v[80:83], v[132:135], v[184:187], v[80:83]
	v_mfma_f32_16x16x32_bf16 v[84:87], v[136:139], v[180:183], 0
	v_mfma_f32_16x16x32_bf16 v[96:99], v[132:135], v[192:195], v[96:99]
	v_mfma_f32_16x16x32_bf16 v[112:115], v[132:135], v[200:203], v[112:115]
	v_mfma_f32_16x16x32_bf16 v[116:119], v[136:139], v[196:199], 0
	v_mfma_f32_16x16x32_bf16 v[68:71], v[140:143], v[176:179], v[68:71]
	v_mfma_f32_16x16x32_bf16 v[84:87], v[140:143], v[184:187], v[84:87]
	v_mfma_f32_16x16x32_bf16 v[100:103], v[136:139], v[188:191], 0
	v_mfma_f32_16x16x32_bf16 v[116:119], v[140:143], v[200:203], v[116:119]
	v_mfma_f32_16x16x32_bf16 v[100:103], v[140:143], v[192:195], v[100:103]
	s_setprio 0
	s_setprio 1
	v_mfma_f32_16x16x32_bf16 v[72:75], v[144:147], v[168:171], 0
	v_mfma_f32_16x16x32_bf16 v[76:79], v[152:155], v[168:171], 0
	v_mfma_f32_16x16x32_bf16 v[72:75], v[148:151], v[176:179], v[72:75]
	v_mfma_f32_16x16x32_bf16 v[76:79], v[156:159], v[176:179], v[76:79]
	v_mfma_f32_16x16x32_bf16 v[88:91], v[144:147], v[180:183], 0
	v_mfma_f32_16x16x32_bf16 v[92:95], v[152:155], v[180:183], 0
	v_mfma_f32_16x16x32_bf16 v[104:107], v[144:147], v[188:191], 0
	v_mfma_f32_16x16x32_bf16 v[120:123], v[144:147], v[196:199], 0
	v_mfma_f32_16x16x32_bf16 v[88:91], v[148:151], v[184:187], v[88:91]
	v_mfma_f32_16x16x32_bf16 v[92:95], v[156:159], v[184:187], v[92:95]
	v_mfma_f32_16x16x32_bf16 v[104:107], v[148:151], v[192:195], v[104:107]
	v_mfma_f32_16x16x32_bf16 v[108:111], v[152:155], v[188:191], 0
	v_mfma_f32_16x16x32_bf16 v[120:123], v[148:151], v[200:203], v[120:123]
	v_mfma_f32_16x16x32_bf16 v[124:127], v[152:155], v[196:199], 0
	v_mfma_f32_16x16x32_bf16 v[108:111], v[156:159], v[192:195], v[108:111]
	v_mfma_f32_16x16x32_bf16 v[124:127], v[156:159], v[200:203], v[124:127]
	s_setprio 0
	s_barrier
	s_add_i32 s54, 0, 0x18000
	s_add_i32 s60, 0, 0x1c000
	v_add_u32_e32 v253, 0x18000, v174
	v_add_u32_e32 v252, 0x1c000, v174
	ds_read_b128 v[128:131], v253
	ds_read_b128 v[132:135], v253 offset:1024
	ds_read_b128 v[136:139], v253 offset:2048
	ds_read_b128 v[140:143], v253 offset:3072
	ds_read_b128 v[144:147], v252
	ds_read_b128 v[148:151], v252 offset:1024
	ds_read_b128 v[152:155], v252 offset:2048
	ds_read_b128 v[156:159], v252 offset:3072
	s_add_u32 s56, s22, 0x40100
	s_addc_u32 s57, s23, 0
	s_mov_b32 m0, s41
	ds_read_b128 v[168:171], v175 offset:32768
	ds_read_b128 v[176:179], v175 offset:33792
	ds_read_b128 v[180:183], v175 offset:34816
	ds_read_b128 v[184:187], v175 offset:35840
	ds_read_b128 v[188:191], v175 offset:36864
	ds_read_b128 v[192:195], v175 offset:37888
	ds_read_b128 v[196:199], v175 offset:38912
	ds_read_b128 v[200:203], v175 offset:39936
	global_load_lds_dwordx4 v160, s[56:57]
	s_mov_b32 m0, s42
	s_nop 0
	global_load_lds_dwordx4 v162, s[56:57]
	s_waitcnt vmcnt(8)
	s_waitcnt lgkmcnt(0)
	s_barrier
	s_setprio 1
	s_waitcnt lgkmcnt(0)
	v_mfma_f32_16x16x32_bf16 v[0:3], v[128:131], v[168:171], v[0:3]
	v_mfma_f32_16x16x32_bf16 v[4:7], v[136:139], v[168:171], v[4:7]
	v_mfma_f32_16x16x32_bf16 v[16:19], v[128:131], v[180:183], v[16:19]
	v_mfma_f32_16x16x32_bf16 v[20:23], v[136:139], v[180:183], v[20:23]
	v_mfma_f32_16x16x32_bf16 v[32:35], v[128:131], v[188:191], v[32:35]
	v_mfma_f32_16x16x32_bf16 v[36:39], v[136:139], v[188:191], v[36:39]
	v_mfma_f32_16x16x32_bf16 v[48:51], v[128:131], v[196:199], v[48:51]
	v_mfma_f32_16x16x32_bf16 v[52:55], v[136:139], v[196:199], v[52:55]
	v_mfma_f32_16x16x32_bf16 v[0:3], v[132:135], v[176:179], v[0:3]
	v_mfma_f32_16x16x32_bf16 v[4:7], v[140:143], v[176:179], v[4:7]
	v_mfma_f32_16x16x32_bf16 v[16:19], v[132:135], v[184:187], v[16:19]
	v_mfma_f32_16x16x32_bf16 v[20:23], v[140:143], v[184:187], v[20:23]
	v_mfma_f32_16x16x32_bf16 v[32:35], v[132:135], v[192:195], v[32:35]
	v_mfma_f32_16x16x32_bf16 v[36:39], v[140:143], v[192:195], v[36:39]
	v_mfma_f32_16x16x32_bf16 v[48:51], v[132:135], v[200:203], v[48:51]
	v_mfma_f32_16x16x32_bf16 v[52:55], v[140:143], v[200:203], v[52:55]
	s_setprio 0
	s_setprio 1
	v_mfma_f32_16x16x32_bf16 v[8:11], v[144:147], v[168:171], v[8:11]
	v_mfma_f32_16x16x32_bf16 v[24:27], v[144:147], v[180:183], v[24:27]
	v_mfma_f32_16x16x32_bf16 v[28:31], v[152:155], v[180:183], v[28:31]
	v_mfma_f32_16x16x32_bf16 v[44:47], v[152:155], v[188:191], v[44:47]
	v_mfma_f32_16x16x32_bf16 v[56:59], v[144:147], v[196:199], v[56:59]
	v_mfma_f32_16x16x32_bf16 v[60:63], v[152:155], v[196:199], v[60:63]
	v_mfma_f32_16x16x32_bf16 v[8:11], v[148:151], v[176:179], v[8:11]
	v_mfma_f32_16x16x32_bf16 v[12:15], v[152:155], v[168:171], v[12:15]
	v_mfma_f32_16x16x32_bf16 v[24:27], v[148:151], v[184:187], v[24:27]
	v_mfma_f32_16x16x32_bf16 v[28:31], v[156:159], v[184:187], v[28:31]
	v_mfma_f32_16x16x32_bf16 v[40:43], v[144:147], v[188:191], v[40:43]
	v_mfma_f32_16x16x32_bf16 v[44:47], v[156:159], v[192:195], v[44:47]
	v_mfma_f32_16x16x32_bf16 v[56:59], v[148:151], v[200:203], v[56:59]
	v_mfma_f32_16x16x32_bf16 v[60:63], v[156:159], v[200:203], v[60:63]
	v_mfma_f32_16x16x32_bf16 v[12:15], v[156:159], v[176:179], v[12:15]
	v_mfma_f32_16x16x32_bf16 v[40:43], v[148:151], v[192:195], v[40:43]
	s_setprio 0
	s_barrier
	s_add_i32 s56, s54, s38
	s_mov_b64 s[62:63], 0x180
	s_add_i32 s54, s56, 0x2000
	s_add_u32 s68, s24, s62
	s_addc_u32 s69, s25, s63
	s_mov_b32 m0, s56
	s_add_u32 s70, s24, s62
	s_addc_u32 s71, s25, s63
	s_add_u32 s58, s24, 0x10180
	ds_read_b128 v[168:171], v175 offset:49152
	ds_read_b128 v[176:179], v175 offset:50176
	ds_read_b128 v[180:183], v175 offset:51200
	ds_read_b128 v[184:187], v175 offset:52224
	ds_read_b128 v[188:191], v175 offset:53248
	ds_read_b128 v[192:195], v175 offset:54272
	ds_read_b128 v[196:199], v175 offset:55296
	ds_read_b128 v[200:203], v175 offset:56320
	global_load_lds_dwordx4 v232, s[68:69]
	s_mov_b32 m0, s54
	s_addc_u32 s59, s25, 0
	s_add_i32 s24, s60, s38
	global_load_lds_dwordx4 v164, s[70:71]
	s_mov_b32 m0, s24
	s_add_i32 s25, s24, 0x2000
	global_load_lds_dwordx4 v232, s[58:59]
	s_mov_b32 m0, s25
	s_nop 0
	global_load_lds_dwordx4 v164, s[58:59]
	s_add_u32 s68, s22, s62
	s_addc_u32 s69, s23, s63
	s_mov_b32 m0, s47
	s_nop 0
	global_load_lds_dwordx4 v160, s[68:69]
	s_add_u32 s68, s22, s62
	s_addc_u32 s69, s23, s63
	s_mov_b32 m0, s48
	s_nop 0
	global_load_lds_dwordx4 v162, s[68:69]
	s_waitcnt vmcnt(8)
	s_waitcnt lgkmcnt(0)
	s_barrier
	s_setprio 1
	s_waitcnt lgkmcnt(0)
	v_mfma_f32_16x16x32_bf16 v[64:67], v[128:131], v[168:171], v[64:67]
	v_mfma_f32_16x16x32_bf16 v[68:71], v[136:139], v[168:171], v[68:71]
	v_mfma_f32_16x16x32_bf16 v[84:87], v[136:139], v[180:183], v[84:87]
	v_mfma_f32_16x16x32_bf16 v[96:99], v[128:131], v[188:191], v[96:99]
	v_mfma_f32_16x16x32_bf16 v[112:115], v[128:131], v[196:199], v[112:115]
	v_mfma_f32_16x16x32_bf16 v[116:119], v[136:139], v[196:199], v[116:119]
	v_mfma_f32_16x16x32_bf16 v[64:67], v[132:135], v[176:179], v[64:67]
	v_mfma_f32_16x16x32_bf16 v[68:71], v[140:143], v[176:179], v[68:71]
	v_mfma_f32_16x16x32_bf16 v[80:83], v[128:131], v[180:183], v[80:83]
	v_mfma_f32_16x16x32_bf16 v[84:87], v[140:143], v[184:187], v[84:87]
	v_mfma_f32_16x16x32_bf16 v[96:99], v[132:135], v[192:195], v[96:99]
	v_mfma_f32_16x16x32_bf16 v[100:103], v[136:139], v[188:191], v[100:103]
	v_mfma_f32_16x16x32_bf16 v[112:115], v[132:135], v[200:203], v[112:115]
	v_mfma_f32_16x16x32_bf16 v[116:119], v[140:143], v[200:203], v[116:119]
	v_mfma_f32_16x16x32_bf16 v[80:83], v[132:135], v[184:187], v[80:83]
	v_mfma_f32_16x16x32_bf16 v[100:103], v[140:143], v[192:195], v[100:103]
	s_setprio 0
	s_setprio 1
	v_mfma_f32_16x16x32_bf16 v[72:75], v[144:147], v[168:171], v[72:75]
	v_mfma_f32_16x16x32_bf16 v[76:79], v[152:155], v[168:171], v[76:79]
	v_mfma_f32_16x16x32_bf16 v[88:91], v[144:147], v[180:183], v[88:91]
	v_mfma_f32_16x16x32_bf16 v[92:95], v[152:155], v[180:183], v[92:95]
	v_mfma_f32_16x16x32_bf16 v[104:107], v[144:147], v[188:191], v[104:107]
	v_mfma_f32_16x16x32_bf16 v[108:111], v[152:155], v[188:191], v[108:111]
	v_mfma_f32_16x16x32_bf16 v[124:127], v[152:155], v[196:199], v[124:127]
	v_mfma_f32_16x16x32_bf16 v[72:75], v[148:151], v[176:179], v[72:75]
	v_mfma_f32_16x16x32_bf16 v[76:79], v[156:159], v[176:179], v[76:79]
	v_mfma_f32_16x16x32_bf16 v[92:95], v[156:159], v[184:187], v[92:95]
	v_mfma_f32_16x16x32_bf16 v[104:107], v[148:151], v[192:195], v[104:107]
	v_mfma_f32_16x16x32_bf16 v[108:111], v[156:159], v[192:195], v[108:111]
	v_mfma_f32_16x16x32_bf16 v[120:123], v[144:147], v[196:199], v[120:123]
	v_mfma_f32_16x16x32_bf16 v[124:127], v[156:159], v[200:203], v[124:127]
	v_mfma_f32_16x16x32_bf16 v[88:91], v[148:151], v[184:187], v[88:91]
	v_mfma_f32_16x16x32_bf16 v[120:123], v[148:151], v[200:203], v[120:123]
	s_setprio 0
	s_barrier
	v_add_u32_e32 v253, 0x10000, v174
	ds_read_b128 v[128:131], v253
	ds_read_b128 v[132:135], v253 offset:1024
	ds_read_b128 v[136:139], v253 offset:2048
	ds_read_b128 v[140:143], v253 offset:3072
	v_add_u32_e32 v253, 0x14000, v174
	ds_read_b128 v[144:147], v253
	ds_read_b128 v[148:151], v253 offset:1024
	ds_read_b128 v[152:155], v253 offset:2048
	ds_read_b128 v[156:159], v253 offset:3072
	s_add_u32 s22, s22, 0x40180
	s_addc_u32 s23, s23, 0
	s_mov_b32 m0, s55
	ds_read_b128 v[168:171], v175
	ds_read_b128 v[176:179], v175 offset:1024
	ds_read_b128 v[180:183], v175 offset:2048
	ds_read_b128 v[184:187], v175 offset:3072
	ds_read_b128 v[188:191], v175 offset:4096
	ds_read_b128 v[192:195], v175 offset:5120
	ds_read_b128 v[196:199], v175 offset:6144
	ds_read_b128 v[200:203], v175 offset:7168
	global_load_lds_dwordx4 v160, s[22:23]
	s_mov_b32 m0, s13
	s_nop 0
	global_load_lds_dwordx4 v162, s[22:23]
	s_waitcnt vmcnt(8)
	s_waitcnt lgkmcnt(0)
	s_barrier
	s_setprio 1
	s_waitcnt lgkmcnt(0)
	v_mfma_f32_16x16x32_bf16 v[0:3], v[128:131], v[168:171], v[0:3]
	v_mfma_f32_16x16x32_bf16 v[4:7], v[136:139], v[168:171], v[4:7]
	v_mfma_f32_16x16x32_bf16 v[16:19], v[128:131], v[180:183], v[16:19]
	v_mfma_f32_16x16x32_bf16 v[20:23], v[136:139], v[180:183], v[20:23]
	v_mfma_f32_16x16x32_bf16 v[32:35], v[128:131], v[188:191], v[32:35]
	v_mfma_f32_16x16x32_bf16 v[36:39], v[136:139], v[188:191], v[36:39]
	v_mfma_f32_16x16x32_bf16 v[48:51], v[128:131], v[196:199], v[48:51]
	v_mfma_f32_16x16x32_bf16 v[0:3], v[132:135], v[176:179], v[0:3]
	v_mfma_f32_16x16x32_bf16 v[4:7], v[140:143], v[176:179], v[4:7]
	v_mfma_f32_16x16x32_bf16 v[16:19], v[132:135], v[184:187], v[16:19]
	v_mfma_f32_16x16x32_bf16 v[20:23], v[140:143], v[184:187], v[20:23]
	v_mfma_f32_16x16x32_bf16 v[32:35], v[132:135], v[192:195], v[32:35]
	v_mfma_f32_16x16x32_bf16 v[36:39], v[140:143], v[192:195], v[36:39]
	v_mfma_f32_16x16x32_bf16 v[48:51], v[132:135], v[200:203], v[48:51]
	v_mfma_f32_16x16x32_bf16 v[52:55], v[136:139], v[196:199], v[52:55]
	v_mfma_f32_16x16x32_bf16 v[52:55], v[140:143], v[200:203], v[52:55]
	s_setprio 0
	s_setprio 1
	v_mfma_f32_16x16x32_bf16 v[8:11], v[144:147], v[168:171], v[8:11]
	v_mfma_f32_16x16x32_bf16 v[24:27], v[144:147], v[180:183], v[24:27]
	v_mfma_f32_16x16x32_bf16 v[28:31], v[152:155], v[180:183], v[28:31]
	v_mfma_f32_16x16x32_bf16 v[44:47], v[152:155], v[188:191], v[44:47]
	v_mfma_f32_16x16x32_bf16 v[56:59], v[144:147], v[196:199], v[56:59]
	v_mfma_f32_16x16x32_bf16 v[60:63], v[152:155], v[196:199], v[60:63]
	v_mfma_f32_16x16x32_bf16 v[8:11], v[148:151], v[176:179], v[8:11]
	v_mfma_f32_16x16x32_bf16 v[12:15], v[152:155], v[168:171], v[12:15]
	v_mfma_f32_16x16x32_bf16 v[24:27], v[148:151], v[184:187], v[24:27]
	v_mfma_f32_16x16x32_bf16 v[28:31], v[156:159], v[184:187], v[28:31]
	v_mfma_f32_16x16x32_bf16 v[40:43], v[144:147], v[188:191], v[40:43]
	v_mfma_f32_16x16x32_bf16 v[44:47], v[156:159], v[192:195], v[44:47]
	v_mfma_f32_16x16x32_bf16 v[56:59], v[148:151], v[200:203], v[56:59]
	v_mfma_f32_16x16x32_bf16 v[60:63], v[156:159], v[200:203], v[60:63]
	v_mfma_f32_16x16x32_bf16 v[12:15], v[156:159], v[176:179], v[12:15]
	v_mfma_f32_16x16x32_bf16 v[40:43], v[148:151], v[192:195], v[40:43]
	s_setprio 0
	s_barrier
	s_mov_b32 m0, s53
	s_add_u32 s22, s26, 0x10000
	ds_read_b128 v[168:171], v175 offset:16384
	ds_read_b128 v[176:179], v175 offset:17408
	ds_read_b128 v[180:183], v175 offset:18432
	ds_read_b128 v[184:187], v175 offset:19456
	ds_read_b128 v[188:191], v175 offset:20480
	ds_read_b128 v[192:195], v175 offset:21504
	ds_read_b128 v[196:199], v175 offset:22528
	ds_read_b128 v[200:203], v175 offset:23552
	global_load_lds_dwordx4 v232, s[26:27]
	s_mov_b32 m0, s15
	s_addc_u32 s23, s27, 0
	global_load_lds_dwordx4 v164, s[26:27]
	s_mov_b32 m0, s21
	s_nop 0
	global_load_lds_dwordx4 v232, s[22:23]
	s_mov_b32 m0, s52
	s_nop 0
	global_load_lds_dwordx4 v164, s[22:23]
	s_mov_b32 m0, s39
	s_nop 0
	global_load_lds_dwordx4 v160, s[28:29]
	s_mov_b32 m0, s40
	s_nop 0
	global_load_lds_dwordx4 v162, s[28:29]
	s_waitcnt vmcnt(8)
	s_waitcnt lgkmcnt(0)
	s_barrier
	s_setprio 1
	s_waitcnt lgkmcnt(0)
	v_mfma_f32_16x16x32_bf16 v[64:67], v[128:131], v[168:171], v[64:67]
	v_mfma_f32_16x16x32_bf16 v[64:67], v[132:135], v[176:179], v[64:67]
	v_mfma_f32_16x16x32_bf16 v[68:71], v[136:139], v[168:171], v[68:71]
	v_mfma_f32_16x16x32_bf16 v[68:71], v[140:143], v[176:179], v[68:71]
	v_mfma_f32_16x16x32_bf16 v[80:83], v[128:131], v[180:183], v[80:83]
	v_mfma_f32_16x16x32_bf16 v[80:83], v[132:135], v[184:187], v[80:83]
	v_mfma_f32_16x16x32_bf16 v[84:87], v[136:139], v[180:183], v[84:87]
	v_mfma_f32_16x16x32_bf16 v[84:87], v[140:143], v[184:187], v[84:87]
	v_mfma_f32_16x16x32_bf16 v[96:99], v[128:131], v[188:191], v[96:99]
	v_mfma_f32_16x16x32_bf16 v[112:115], v[128:131], v[196:199], v[112:115]
	v_mfma_f32_16x16x32_bf16 v[116:119], v[136:139], v[196:199], v[116:119]
	v_mfma_f32_16x16x32_bf16 v[96:99], v[132:135], v[192:195], v[96:99]
	v_mfma_f32_16x16x32_bf16 v[100:103], v[136:139], v[188:191], v[100:103]
	v_mfma_f32_16x16x32_bf16 v[112:115], v[132:135], v[200:203], v[112:115]
	v_mfma_f32_16x16x32_bf16 v[116:119], v[140:143], v[200:203], v[116:119]
	v_mfma_f32_16x16x32_bf16 v[100:103], v[140:143], v[192:195], v[100:103]
	s_setprio 0
	s_setprio 1
	v_mfma_f32_16x16x32_bf16 v[72:75], v[144:147], v[168:171], v[72:75]
	v_mfma_f32_16x16x32_bf16 v[72:75], v[148:151], v[176:179], v[72:75]
	v_mfma_f32_16x16x32_bf16 v[76:79], v[152:155], v[168:171], v[76:79]
	v_mfma_f32_16x16x32_bf16 v[76:79], v[156:159], v[176:179], v[76:79]
	v_mfma_f32_16x16x32_bf16 v[88:91], v[144:147], v[180:183], v[88:91]
	v_mfma_f32_16x16x32_bf16 v[88:91], v[148:151], v[184:187], v[88:91]
	v_mfma_f32_16x16x32_bf16 v[92:95], v[152:155], v[180:183], v[92:95]
	v_mfma_f32_16x16x32_bf16 v[92:95], v[156:159], v[184:187], v[92:95]
	v_mfma_f32_16x16x32_bf16 v[104:107], v[144:147], v[188:191], v[104:107]
	v_mfma_f32_16x16x32_bf16 v[104:107], v[148:151], v[192:195], v[104:107]
	v_mfma_f32_16x16x32_bf16 v[108:111], v[152:155], v[188:191], v[108:111]
	v_mfma_f32_16x16x32_bf16 v[108:111], v[156:159], v[192:195], v[108:111]
	v_mfma_f32_16x16x32_bf16 v[120:123], v[144:147], v[196:199], v[120:123]
	v_mfma_f32_16x16x32_bf16 v[120:123], v[148:151], v[200:203], v[120:123]
	v_mfma_f32_16x16x32_bf16 v[124:127], v[152:155], v[196:199], v[124:127]
	v_mfma_f32_16x16x32_bf16 v[124:127], v[156:159], v[200:203], v[124:127]
	s_setprio 0
	s_barrier
	s_nop 4
	v_add_u32_e32 v253, 0x18000, v174
	ds_read_b128 v[128:131], v253
	ds_read_b128 v[132:135], v253 offset:1024
	ds_read_b128 v[136:139], v253 offset:2048
	ds_read_b128 v[140:143], v253 offset:3072
	v_add_u32_e32 v253, 0x1c000, v174
	ds_read_b128 v[144:147], v253
	ds_read_b128 v[148:151], v253 offset:1024
	ds_read_b128 v[152:155], v253 offset:2048
	ds_read_b128 v[156:159], v253 offset:3072
	s_add_u32 s22, s28, 0x40000
	s_addc_u32 s23, s29, 0
	s_mov_b32 m0, s41
	ds_read_b128 v[168:171], v175 offset:32768
	ds_read_b128 v[176:179], v175 offset:33792
	ds_read_b128 v[180:183], v175 offset:34816
	ds_read_b128 v[184:187], v175 offset:35840
	ds_read_b128 v[188:191], v175 offset:36864
	ds_read_b128 v[192:195], v175 offset:37888
	ds_read_b128 v[196:199], v175 offset:38912
	ds_read_b128 v[200:203], v175 offset:39936
	global_load_lds_dwordx4 v160, s[22:23]
	s_mov_b32 m0, s42
	s_nop 0
	global_load_lds_dwordx4 v162, s[22:23]
	s_waitcnt vmcnt(8)
	s_waitcnt lgkmcnt(0)
	s_barrier
	s_setprio 1
	s_waitcnt lgkmcnt(0)
	v_mfma_f32_16x16x32_bf16 v[0:3], v[128:131], v[168:171], v[0:3]
	v_mfma_f32_16x16x32_bf16 v[0:3], v[132:135], v[176:179], v[0:3]
	v_mfma_f32_16x16x32_bf16 v[4:7], v[136:139], v[168:171], v[4:7]
	v_mfma_f32_16x16x32_bf16 v[4:7], v[140:143], v[176:179], v[4:7]
	v_mfma_f32_16x16x32_bf16 v[16:19], v[128:131], v[180:183], v[16:19]
	v_mfma_f32_16x16x32_bf16 v[16:19], v[132:135], v[184:187], v[16:19]
	v_mfma_f32_16x16x32_bf16 v[20:23], v[136:139], v[180:183], v[20:23]
	v_mfma_f32_16x16x32_bf16 v[20:23], v[140:143], v[184:187], v[20:23]
	v_mfma_f32_16x16x32_bf16 v[32:35], v[128:131], v[188:191], v[32:35]
	v_mfma_f32_16x16x32_bf16 v[32:35], v[132:135], v[192:195], v[32:35]
	v_mfma_f32_16x16x32_bf16 v[36:39], v[136:139], v[188:191], v[36:39]
	v_mfma_f32_16x16x32_bf16 v[36:39], v[140:143], v[192:195], v[36:39]
	v_mfma_f32_16x16x32_bf16 v[48:51], v[128:131], v[196:199], v[48:51]
	v_mfma_f32_16x16x32_bf16 v[48:51], v[132:135], v[200:203], v[48:51]
	v_mfma_f32_16x16x32_bf16 v[52:55], v[136:139], v[196:199], v[52:55]
	v_mfma_f32_16x16x32_bf16 v[52:55], v[140:143], v[200:203], v[52:55]
	s_setprio 0
	s_setprio 1
	v_mfma_f32_16x16x32_bf16 v[12:15], v[152:155], v[168:171], v[12:15]
	v_mfma_f32_16x16x32_bf16 v[12:15], v[156:159], v[176:179], v[12:15]
	v_mfma_f32_16x16x32_bf16 v[24:27], v[144:147], v[180:183], v[24:27]
	v_mfma_f32_16x16x32_bf16 v[24:27], v[148:151], v[184:187], v[24:27]
	v_mfma_f32_16x16x32_bf16 v[28:31], v[152:155], v[180:183], v[28:31]
	v_mfma_f32_16x16x32_bf16 v[8:11], v[144:147], v[168:171], v[8:11]
	v_mfma_f32_16x16x32_bf16 v[28:31], v[156:159], v[184:187], v[28:31]
	v_mfma_f32_16x16x32_bf16 v[40:43], v[144:147], v[188:191], v[40:43]
	v_mfma_f32_16x16x32_bf16 v[8:11], v[148:151], v[176:179], v[8:11]
	v_mfma_f32_16x16x32_bf16 v[40:43], v[148:151], v[192:195], v[40:43]
	v_mfma_f32_16x16x32_bf16 v[44:47], v[152:155], v[188:191], v[44:47]
	v_mfma_f32_16x16x32_bf16 v[44:47], v[156:159], v[192:195], v[44:47]
	v_mfma_f32_16x16x32_bf16 v[56:59], v[144:147], v[196:199], v[56:59]
	v_mfma_f32_16x16x32_bf16 v[56:59], v[148:151], v[200:203], v[56:59]
	v_mfma_f32_16x16x32_bf16 v[60:63], v[152:155], v[196:199], v[60:63]
	v_mfma_f32_16x16x32_bf16 v[60:63], v[156:159], v[200:203], v[60:63]
	s_setprio 0
	s_barrier
	s_mov_b32 m0, s56
	s_add_u32 s68, s26, s94
	s_addc_u32 s69, s27, s95
	s_add_u32 s70, s26, s94
	s_addc_u32 s71, s27, s95
	s_add_u32 s22, s26, 0x10080
	s_nop 1
	ds_read_b128 v[168:171], v175 offset:49152
	ds_read_b128 v[176:179], v175 offset:50176
	ds_read_b128 v[180:183], v175 offset:51200
	ds_read_b128 v[184:187], v175 offset:52224
	ds_read_b128 v[188:191], v175 offset:53248
	ds_read_b128 v[192:195], v175 offset:54272
	ds_read_b128 v[196:199], v175 offset:55296
	ds_read_b128 v[200:203], v175 offset:56320
	global_load_lds_dwordx4 v232, s[68:69]
	s_mov_b32 m0, s54
	s_addc_u32 s23, s27, 0
	global_load_lds_dwordx4 v164, s[70:71]
	s_mov_b32 m0, s24
	s_nop 0
	global_load_lds_dwordx4 v232, s[22:23]
	s_mov_b32 m0, s25
	s_nop 0
	global_load_lds_dwordx4 v164, s[22:23]
	s_add_u32 s68, s28, s94
	s_addc_u32 s69, s29, s95
	s_mov_b32 m0, s47
	s_nop 0
	global_load_lds_dwordx4 v160, s[68:69]
	s_add_u32 s68, s28, s94
	s_addc_u32 s69, s29, s95
	s_mov_b32 m0, s48
	s_nop 0
	global_load_lds_dwordx4 v162, s[68:69]
	s_waitcnt vmcnt(8)
	s_waitcnt lgkmcnt(0)
	s_barrier
	s_setprio 1
	s_waitcnt lgkmcnt(0)
	v_mfma_f32_16x16x32_bf16 v[64:67], v[128:131], v[168:171], v[64:67]
	v_mfma_f32_16x16x32_bf16 v[64:67], v[132:135], v[176:179], v[64:67]
	v_mfma_f32_16x16x32_bf16 v[68:71], v[136:139], v[168:171], v[68:71]
	v_mfma_f32_16x16x32_bf16 v[68:71], v[140:143], v[176:179], v[68:71]
	v_mfma_f32_16x16x32_bf16 v[80:83], v[128:131], v[180:183], v[80:83]
	v_mfma_f32_16x16x32_bf16 v[80:83], v[132:135], v[184:187], v[80:83]
	v_mfma_f32_16x16x32_bf16 v[84:87], v[136:139], v[180:183], v[84:87]
	v_mfma_f32_16x16x32_bf16 v[84:87], v[140:143], v[184:187], v[84:87]
	v_mfma_f32_16x16x32_bf16 v[96:99], v[128:131], v[188:191], v[96:99]
	v_mfma_f32_16x16x32_bf16 v[112:115], v[128:131], v[196:199], v[112:115]
	v_mfma_f32_16x16x32_bf16 v[96:99], v[132:135], v[192:195], v[96:99]
	v_mfma_f32_16x16x32_bf16 v[100:103], v[136:139], v[188:191], v[100:103]
	v_mfma_f32_16x16x32_bf16 v[112:115], v[132:135], v[200:203], v[112:115]
	v_mfma_f32_16x16x32_bf16 v[116:119], v[136:139], v[196:199], v[116:119]
	v_mfma_f32_16x16x32_bf16 v[100:103], v[140:143], v[192:195], v[100:103]
	v_mfma_f32_16x16x32_bf16 v[116:119], v[140:143], v[200:203], v[116:119]
	s_setprio 0
	s_setprio 1
	v_mfma_f32_16x16x32_bf16 v[72:75], v[144:147], v[168:171], v[72:75]
	v_mfma_f32_16x16x32_bf16 v[72:75], v[148:151], v[176:179], v[72:75]
	v_mfma_f32_16x16x32_bf16 v[76:79], v[152:155], v[168:171], v[76:79]
	v_mfma_f32_16x16x32_bf16 v[76:79], v[156:159], v[176:179], v[76:79]
	v_mfma_f32_16x16x32_bf16 v[88:91], v[144:147], v[180:183], v[88:91]
	v_mfma_f32_16x16x32_bf16 v[88:91], v[148:151], v[184:187], v[88:91]
	v_mfma_f32_16x16x32_bf16 v[92:95], v[152:155], v[180:183], v[92:95]
	v_mfma_f32_16x16x32_bf16 v[92:95], v[156:159], v[184:187], v[92:95]
	v_mfma_f32_16x16x32_bf16 v[104:107], v[144:147], v[188:191], v[104:107]
	v_mfma_f32_16x16x32_bf16 v[104:107], v[148:151], v[192:195], v[104:107]
	v_mfma_f32_16x16x32_bf16 v[108:111], v[152:155], v[188:191], v[108:111]
	v_mfma_f32_16x16x32_bf16 v[108:111], v[156:159], v[192:195], v[108:111]
	v_mfma_f32_16x16x32_bf16 v[120:123], v[144:147], v[196:199], v[120:123]
	v_mfma_f32_16x16x32_bf16 v[120:123], v[148:151], v[200:203], v[120:123]
	v_mfma_f32_16x16x32_bf16 v[124:127], v[152:155], v[196:199], v[124:127]
	v_mfma_f32_16x16x32_bf16 v[124:127], v[156:159], v[200:203], v[124:127]
	s_setprio 0
	s_barrier
	s_andn2_b64 vcc, exec, s[10:11]
	s_cbranch_vccnz .LBB0_1020
	s_barrier

.LBB0_1163:
	s_ashr_i32 s23, s22, 31
	s_lshl_b64 s[24:25], s[22:23], 19
	s_add_u32 s24, s42, s24
	s_addc_u32 s25, s43, s25
	s_and_b64 s[26:27], s[4:5], exec
	s_cselect_b32 s23, s25, s35
	s_cselect_b32 s56, s24, s34
	s_ashr_i32 s21, s20, 31
	s_lshl_b64 s[26:27], s[20:21], 19
	s_add_u32 s26, s44, s26
	s_addc_u32 s27, s45, s27
	s_and_b64 s[36:37], s[4:5], exec
	s_cselect_b32 s21, s27, s31
	s_cselect_b32 s57, s26, s30
	s_add_u32 s58, s30, 0x100
	s_addc_u32 s59, s31, 0
	s_add_u32 s30, s34, 0x40080
	s_addc_u32 s31, s35, 0
	s_mov_b32 s60, -2
	s_waitcnt vmcnt(0)
	s_add_u32 s34, s30, 0xfffc0080
	s_addc_u32 s35, s31, -1
	s_add_i32 s61, 0, 0x10000
	s_cmp_eq_u32 s60, 12
	s_cselect_b32 s37, s23, s35
	s_cselect_b32 s36, s56, s34
	s_cselect_b32 s35, s21, s59
	s_cselect_b32 s34, s57, s58
	s_add_i32 s64, 0, 0x14000
	v_add_u32_e32 v140, s61, v174
	v_add_u32_e32 v166, s64, v174
	ds_read_b128 v[128:131], v140
	ds_read_b128 v[132:135], v140 offset:1024
	ds_read_b128 v[136:139], v140 offset:2048
	ds_read_b128 v[140:143], v140 offset:3072
	ds_read_b128 v[154:157], v166
	ds_read_b128 v[158:161], v166 offset:1024
	ds_read_b128 v[162:165], v166 offset:2048
	ds_read_b128 v[166:169], v166 offset:3072
	v_lshl_add_u64 v[204:205], s[30:31], 0, v[152:153]
	s_add_i32 m0, s29, 0xc000
	ds_read_b128 v[170:173], v175
	ds_read_b128 v[176:179], v175 offset:1024
	ds_read_b128 v[180:183], v175 offset:2048
	ds_read_b128 v[184:187], v175 offset:3072
	ds_read_b128 v[188:191], v175 offset:4096
	ds_read_b128 v[192:195], v175 offset:5120
	ds_read_b128 v[196:199], v175 offset:6144
	ds_read_b128 v[200:203], v175 offset:7168
	global_load_lds_dwordx4 v152, s[30:31]
	v_lshl_add_u64 v[204:205], s[30:31], 0, v[150:151]
	s_add_i32 m0, s29, 0xe000
	s_nop 0
	global_load_lds_dwordx4 v150, s[30:31]
	s_waitcnt vmcnt(8)
	s_waitcnt lgkmcnt(0)
	s_barrier
	s_setprio 1
	s_waitcnt lgkmcnt(0)
	v_mfma_f32_16x16x32_bf16 v[124:127], v[128:131], v[170:173], 0
	v_mfma_f32_16x16x32_bf16 v[120:123], v[136:139], v[170:173], 0
	v_mfma_f32_16x16x32_bf16 v[108:111], v[128:131], v[180:183], 0
	v_mfma_f32_16x16x32_bf16 v[104:107], v[136:139], v[180:183], 0
	v_mfma_f32_16x16x32_bf16 v[92:95], v[128:131], v[188:191], 0
	v_mfma_f32_16x16x32_bf16 v[88:91], v[136:139], v[188:191], 0
	v_mfma_f32_16x16x32_bf16 v[80:83], v[128:131], v[196:199], 0
	v_mfma_f32_16x16x32_bf16 v[72:75], v[136:139], v[196:199], 0
	v_mfma_f32_16x16x32_bf16 v[124:127], v[132:135], v[176:179], v[124:127]
	v_mfma_f32_16x16x32_bf16 v[120:123], v[140:143], v[176:179], v[120:123]
	v_mfma_f32_16x16x32_bf16 v[108:111], v[132:135], v[184:187], v[108:111]
	v_mfma_f32_16x16x32_bf16 v[104:107], v[140:143], v[184:187], v[104:107]
	v_mfma_f32_16x16x32_bf16 v[92:95], v[132:135], v[192:195], v[92:95]
	v_mfma_f32_16x16x32_bf16 v[88:91], v[140:143], v[192:195], v[88:91]
	v_mfma_f32_16x16x32_bf16 v[80:83], v[132:135], v[200:203], v[80:83]
	v_mfma_f32_16x16x32_bf16 v[72:75], v[140:143], v[200:203], v[72:75]
	s_setprio 0
	s_setprio 1
	v_mfma_f32_16x16x32_bf16 v[116:119], v[154:157], v[170:173], 0
	v_mfma_f32_16x16x32_bf16 v[112:115], v[162:165], v[170:173], 0
	v_mfma_f32_16x16x32_bf16 v[100:103], v[154:157], v[180:183], 0
	v_mfma_f32_16x16x32_bf16 v[96:99], v[162:165], v[180:183], 0
	v_mfma_f32_16x16x32_bf16 v[84:87], v[154:157], v[188:191], 0
	v_mfma_f32_16x16x32_bf16 v[76:79], v[162:165], v[188:191], 0
	v_mfma_f32_16x16x32_bf16 v[68:71], v[154:157], v[196:199], 0
	v_mfma_f32_16x16x32_bf16 v[64:67], v[162:165], v[196:199], 0
	v_mfma_f32_16x16x32_bf16 v[116:119], v[158:161], v[176:179], v[116:119]
	v_mfma_f32_16x16x32_bf16 v[112:115], v[166:169], v[176:179], v[112:115]
	v_mfma_f32_16x16x32_bf16 v[100:103], v[158:161], v[184:187], v[100:103]
	v_mfma_f32_16x16x32_bf16 v[96:99], v[166:169], v[184:187], v[96:99]
	v_mfma_f32_16x16x32_bf16 v[84:87], v[158:161], v[192:195], v[84:87]
	v_mfma_f32_16x16x32_bf16 v[76:79], v[166:169], v[192:195], v[76:79]
	v_mfma_f32_16x16x32_bf16 v[68:71], v[158:161], v[200:203], v[68:71]
	v_mfma_f32_16x16x32_bf16 v[64:67], v[166:169], v[200:203], v[64:67]
	s_setprio 0
	s_barrier
	s_add_i32 s61, s61, s41
	v_lshl_add_u64 v[204:205], s[34:35], 0, v[232:233]
	s_mov_b32 m0, s61
	ds_read_b128 v[170:173], v175 offset:16384
	ds_read_b128 v[176:179], v175 offset:17408
	ds_read_b128 v[180:183], v175 offset:18432
	ds_read_b128 v[184:187], v175 offset:19456
	ds_read_b128 v[188:191], v175 offset:20480
	ds_read_b128 v[192:195], v175 offset:21504
	ds_read_b128 v[196:199], v175 offset:22528
	ds_read_b128 v[200:203], v175 offset:23552
	global_load_lds_dwordx4 v232, s[34:35]
	s_add_i32 m0, s61, 0x2000
	s_add_u32 s62, s34, 0x40000
	v_lshl_add_u64 v[206:207], s[34:35], 0, v[148:149]
	s_addc_u32 s63, s35, 0
	s_add_i32 s61, s64, s41
	global_load_lds_dwordx4 v148, s[34:35]
	s_mov_b32 m0, s61
	v_lshl_add_u64 v[210:211], s[36:37], 0, v[146:147]
	global_load_lds_dwordx4 v232, s[62:63]
	s_add_i32 m0, s61, 0x2000
	s_nop 0
	global_load_lds_dwordx4 v148, s[62:63]
	v_lshl_add_u64 v[208:209], s[36:37], 0, v[144:145]
	s_waitcnt vmcnt(6)
	s_waitcnt lgkmcnt(0)
	s_barrier
	s_setprio 1
	s_waitcnt lgkmcnt(0)
	v_mfma_f32_16x16x32_bf16 v[60:63], v[128:131], v[170:173], 0
	v_mfma_f32_16x16x32_bf16 v[56:59], v[136:139], v[170:173], 0
	v_mfma_f32_16x16x32_bf16 v[48:51], v[128:131], v[180:183], 0
	v_mfma_f32_16x16x32_bf16 v[40:43], v[136:139], v[180:183], 0
	v_mfma_f32_16x16x32_bf16 v[28:31], v[128:131], v[188:191], 0
	v_mfma_f32_16x16x32_bf16 v[24:27], v[136:139], v[188:191], 0
	v_mfma_f32_16x16x32_bf16 v[16:19], v[128:131], v[196:199], 0
	v_mfma_f32_16x16x32_bf16 v[8:11], v[136:139], v[196:199], 0
	v_mfma_f32_16x16x32_bf16 v[60:63], v[132:135], v[176:179], v[60:63]
	v_mfma_f32_16x16x32_bf16 v[56:59], v[140:143], v[176:179], v[56:59]
	v_mfma_f32_16x16x32_bf16 v[48:51], v[132:135], v[184:187], v[48:51]
	v_mfma_f32_16x16x32_bf16 v[40:43], v[140:143], v[184:187], v[40:43]
	v_mfma_f32_16x16x32_bf16 v[28:31], v[132:135], v[192:195], v[28:31]
	v_mfma_f32_16x16x32_bf16 v[24:27], v[140:143], v[192:195], v[24:27]
	v_mfma_f32_16x16x32_bf16 v[16:19], v[132:135], v[200:203], v[16:19]
	v_mfma_f32_16x16x32_bf16 v[8:11], v[140:143], v[200:203], v[8:11]
	s_setprio 0
	s_setprio 1
	v_mfma_f32_16x16x32_bf16 v[52:55], v[154:157], v[170:173], 0
	v_mfma_f32_16x16x32_bf16 v[44:47], v[162:165], v[170:173], 0
	v_mfma_f32_16x16x32_bf16 v[36:39], v[154:157], v[180:183], 0
	v_mfma_f32_16x16x32_bf16 v[32:35], v[162:165], v[180:183], 0
	v_mfma_f32_16x16x32_bf16 v[20:23], v[154:157], v[188:191], 0
	v_mfma_f32_16x16x32_bf16 v[12:15], v[162:165], v[188:191], 0
	v_mfma_f32_16x16x32_bf16 v[4:7], v[154:157], v[196:199], 0
	v_mfma_f32_16x16x32_bf16 v[0:3], v[162:165], v[196:199], 0
	v_mfma_f32_16x16x32_bf16 v[52:55], v[158:161], v[176:179], v[52:55]
	v_mfma_f32_16x16x32_bf16 v[44:47], v[166:169], v[176:179], v[44:47]
	v_mfma_f32_16x16x32_bf16 v[36:39], v[158:161], v[184:187], v[36:39]
	v_mfma_f32_16x16x32_bf16 v[32:35], v[166:169], v[184:187], v[32:35]
	v_mfma_f32_16x16x32_bf16 v[20:23], v[158:161], v[192:195], v[20:23]
	v_mfma_f32_16x16x32_bf16 v[12:15], v[166:169], v[192:195], v[12:15]
	v_mfma_f32_16x16x32_bf16 v[4:7], v[158:161], v[200:203], v[4:7]
	v_mfma_f32_16x16x32_bf16 v[0:3], v[166:169], v[200:203], v[0:3]
	s_setprio 0
	s_barrier
	s_branch .Lzmid_3
.LBB0_1164:
	s_add_u32 s34, s30, 0xfffc0080
	s_addc_u32 s35, s31, -1
	s_add_i32 s61, 0, 0x10000
	s_cmp_eq_u32 s60, 12
	s_cselect_b32 s37, s23, s35
	s_cselect_b32 s36, s56, s34
	s_cselect_b32 s35, s21, s59
	s_cselect_b32 s34, s57, s58
	s_add_i32 s64, 0, 0x14000
	v_add_u32_e32 v140, s61, v174
	v_add_u32_e32 v166, s64, v174
	ds_read_b128 v[128:131], v140
	ds_read_b128 v[132:135], v140 offset:1024
	ds_read_b128 v[136:139], v140 offset:2048
	ds_read_b128 v[140:143], v140 offset:3072
	ds_read_b128 v[154:157], v166
	ds_read_b128 v[158:161], v166 offset:1024
	ds_read_b128 v[162:165], v166 offset:2048
	ds_read_b128 v[166:169], v166 offset:3072
	v_lshl_add_u64 v[204:205], s[30:31], 0, v[152:153]
	s_add_i32 m0, s29, 0xc000
	ds_read_b128 v[170:173], v175
	ds_read_b128 v[176:179], v175 offset:1024
	ds_read_b128 v[180:183], v175 offset:2048
	ds_read_b128 v[184:187], v175 offset:3072
	ds_read_b128 v[188:191], v175 offset:4096
	ds_read_b128 v[192:195], v175 offset:5120
	ds_read_b128 v[196:199], v175 offset:6144
	ds_read_b128 v[200:203], v175 offset:7168
	global_load_lds_dwordx4 v152, s[30:31]
	v_lshl_add_u64 v[204:205], s[30:31], 0, v[150:151]
	s_add_i32 m0, s29, 0xe000
	s_nop 0
	global_load_lds_dwordx4 v150, s[30:31]
	s_waitcnt vmcnt(8)
	s_waitcnt lgkmcnt(0)
	s_barrier
	s_setprio 1
	s_waitcnt lgkmcnt(0)
	v_mfma_f32_16x16x32_bf16 v[124:127], v[128:131], v[170:173], v[124:127]
	v_mfma_f32_16x16x32_bf16 v[120:123], v[136:139], v[170:173], v[120:123]
	v_mfma_f32_16x16x32_bf16 v[108:111], v[128:131], v[180:183], v[108:111]
	v_mfma_f32_16x16x32_bf16 v[104:107], v[136:139], v[180:183], v[104:107]
	v_mfma_f32_16x16x32_bf16 v[92:95], v[128:131], v[188:191], v[92:95]
	v_mfma_f32_16x16x32_bf16 v[88:91], v[136:139], v[188:191], v[88:91]
	v_mfma_f32_16x16x32_bf16 v[80:83], v[128:131], v[196:199], v[80:83]
	v_mfma_f32_16x16x32_bf16 v[72:75], v[136:139], v[196:199], v[72:75]
	v_mfma_f32_16x16x32_bf16 v[124:127], v[132:135], v[176:179], v[124:127]
	v_mfma_f32_16x16x32_bf16 v[120:123], v[140:143], v[176:179], v[120:123]
	v_mfma_f32_16x16x32_bf16 v[108:111], v[132:135], v[184:187], v[108:111]
	v_mfma_f32_16x16x32_bf16 v[104:107], v[140:143], v[184:187], v[104:107]
	v_mfma_f32_16x16x32_bf16 v[92:95], v[132:135], v[192:195], v[92:95]
	v_mfma_f32_16x16x32_bf16 v[88:91], v[140:143], v[192:195], v[88:91]
	v_mfma_f32_16x16x32_bf16 v[80:83], v[132:135], v[200:203], v[80:83]
	v_mfma_f32_16x16x32_bf16 v[72:75], v[140:143], v[200:203], v[72:75]
	s_setprio 0
	s_setprio 1
	v_mfma_f32_16x16x32_bf16 v[116:119], v[154:157], v[170:173], v[116:119]
	v_mfma_f32_16x16x32_bf16 v[112:115], v[162:165], v[170:173], v[112:115]
	v_mfma_f32_16x16x32_bf16 v[100:103], v[154:157], v[180:183], v[100:103]
	v_mfma_f32_16x16x32_bf16 v[96:99], v[162:165], v[180:183], v[96:99]
	v_mfma_f32_16x16x32_bf16 v[84:87], v[154:157], v[188:191], v[84:87]
	v_mfma_f32_16x16x32_bf16 v[76:79], v[162:165], v[188:191], v[76:79]
	v_mfma_f32_16x16x32_bf16 v[68:71], v[154:157], v[196:199], v[68:71]
	v_mfma_f32_16x16x32_bf16 v[64:67], v[162:165], v[196:199], v[64:67]
	v_mfma_f32_16x16x32_bf16 v[116:119], v[158:161], v[176:179], v[116:119]
	v_mfma_f32_16x16x32_bf16 v[112:115], v[166:169], v[176:179], v[112:115]
	v_mfma_f32_16x16x32_bf16 v[100:103], v[158:161], v[184:187], v[100:103]
	v_mfma_f32_16x16x32_bf16 v[96:99], v[166:169], v[184:187], v[96:99]
	v_mfma_f32_16x16x32_bf16 v[84:87], v[158:161], v[192:195], v[84:87]
	v_mfma_f32_16x16x32_bf16 v[76:79], v[166:169], v[192:195], v[76:79]
	v_mfma_f32_16x16x32_bf16 v[68:71], v[158:161], v[200:203], v[68:71]
	v_mfma_f32_16x16x32_bf16 v[64:67], v[166:169], v[200:203], v[64:67]
	s_setprio 0
	s_barrier
	s_add_i32 s61, s61, s41
	v_lshl_add_u64 v[204:205], s[34:35], 0, v[232:233]
	s_mov_b32 m0, s61
	ds_read_b128 v[170:173], v175 offset:16384
	ds_read_b128 v[176:179], v175 offset:17408
	ds_read_b128 v[180:183], v175 offset:18432
	ds_read_b128 v[184:187], v175 offset:19456
	ds_read_b128 v[188:191], v175 offset:20480
	ds_read_b128 v[192:195], v175 offset:21504
	ds_read_b128 v[196:199], v175 offset:22528
	ds_read_b128 v[200:203], v175 offset:23552
	global_load_lds_dwordx4 v232, s[34:35]
	s_add_i32 m0, s61, 0x2000
	s_add_u32 s62, s34, 0x40000
	v_lshl_add_u64 v[206:207], s[34:35], 0, v[148:149]
	s_addc_u32 s63, s35, 0
	s_add_i32 s61, s64, s41
	global_load_lds_dwordx4 v148, s[34:35]
	s_mov_b32 m0, s61
	v_lshl_add_u64 v[210:211], s[36:37], 0, v[146:147]
	global_load_lds_dwordx4 v232, s[62:63]
	s_add_i32 m0, s61, 0x2000
	s_nop 0
	global_load_lds_dwordx4 v148, s[62:63]
	v_lshl_add_u64 v[208:209], s[36:37], 0, v[144:145]
	s_waitcnt vmcnt(6)
	s_waitcnt lgkmcnt(0)
	s_barrier
	s_setprio 1
	s_waitcnt lgkmcnt(0)
	v_mfma_f32_16x16x32_bf16 v[60:63], v[128:131], v[170:173], v[60:63]
	v_mfma_f32_16x16x32_bf16 v[56:59], v[136:139], v[170:173], v[56:59]
	v_mfma_f32_16x16x32_bf16 v[48:51], v[128:131], v[180:183], v[48:51]
	v_mfma_f32_16x16x32_bf16 v[40:43], v[136:139], v[180:183], v[40:43]
	v_mfma_f32_16x16x32_bf16 v[28:31], v[128:131], v[188:191], v[28:31]
	v_mfma_f32_16x16x32_bf16 v[24:27], v[136:139], v[188:191], v[24:27]
	v_mfma_f32_16x16x32_bf16 v[16:19], v[128:131], v[196:199], v[16:19]
	v_mfma_f32_16x16x32_bf16 v[8:11], v[136:139], v[196:199], v[8:11]
	v_mfma_f32_16x16x32_bf16 v[60:63], v[132:135], v[176:179], v[60:63]
	v_mfma_f32_16x16x32_bf16 v[56:59], v[140:143], v[176:179], v[56:59]
	v_mfma_f32_16x16x32_bf16 v[48:51], v[132:135], v[184:187], v[48:51]
	v_mfma_f32_16x16x32_bf16 v[40:43], v[140:143], v[184:187], v[40:43]
	v_mfma_f32_16x16x32_bf16 v[28:31], v[132:135], v[192:195], v[28:31]
	v_mfma_f32_16x16x32_bf16 v[24:27], v[140:143], v[192:195], v[24:27]
	v_mfma_f32_16x16x32_bf16 v[16:19], v[132:135], v[200:203], v[16:19]
	v_mfma_f32_16x16x32_bf16 v[8:11], v[140:143], v[200:203], v[8:11]
	s_setprio 0
	s_setprio 1
	v_mfma_f32_16x16x32_bf16 v[52:55], v[154:157], v[170:173], v[52:55]
	v_mfma_f32_16x16x32_bf16 v[44:47], v[162:165], v[170:173], v[44:47]
	v_mfma_f32_16x16x32_bf16 v[36:39], v[154:157], v[180:183], v[36:39]
	v_mfma_f32_16x16x32_bf16 v[32:35], v[162:165], v[180:183], v[32:35]
	v_mfma_f32_16x16x32_bf16 v[20:23], v[154:157], v[188:191], v[20:23]
	v_mfma_f32_16x16x32_bf16 v[12:15], v[162:165], v[188:191], v[12:15]
	v_mfma_f32_16x16x32_bf16 v[4:7], v[154:157], v[196:199], v[4:7]
	v_mfma_f32_16x16x32_bf16 v[0:3], v[162:165], v[196:199], v[0:3]
	v_mfma_f32_16x16x32_bf16 v[52:55], v[158:161], v[176:179], v[52:55]
	v_mfma_f32_16x16x32_bf16 v[44:47], v[166:169], v[176:179], v[44:47]
	v_mfma_f32_16x16x32_bf16 v[36:39], v[158:161], v[184:187], v[36:39]
	v_mfma_f32_16x16x32_bf16 v[32:35], v[166:169], v[184:187], v[32:35]
	v_mfma_f32_16x16x32_bf16 v[20:23], v[158:161], v[192:195], v[20:23]
	v_mfma_f32_16x16x32_bf16 v[12:15], v[166:169], v[192:195], v[12:15]
	v_mfma_f32_16x16x32_bf16 v[4:7], v[158:161], v[200:203], v[4:7]
	v_mfma_f32_16x16x32_bf16 v[0:3], v[166:169], v[200:203], v[0:3]
	s_setprio 0
	s_barrier
.Lzmid_3:
	s_add_i32 s61, 0, 0x18000
	s_add_i32 s62, 0, 0x1c000
	v_add_u32_e32 v140, s61, v174
	v_add_u32_e32 v166, s62, v174
	ds_read_b128 v[128:131], v140
	ds_read_b128 v[132:135], v140 offset:1024
	ds_read_b128 v[136:139], v140 offset:2048
	ds_read_b128 v[140:143], v140 offset:3072
	ds_read_b128 v[154:157], v166
	ds_read_b128 v[158:161], v166 offset:1024
	ds_read_b128 v[162:165], v166 offset:2048
	ds_read_b128 v[166:169], v166 offset:3072
	s_add_u32 s36, s36, 0x40000
	s_addc_u32 s37, s37, 0
	s_mov_b32 m0, s29
	s_nop 0
	global_load_lds_dwordx4 v[208:209], off
	s_mov_b32 m0, s46
	s_nop 0
	global_load_lds_dwordx4 v[210:211], off
	s_mov_b32 m0, s47
	ds_read_b128 v[170:173], v175 offset:32768
	ds_read_b128 v[176:179], v175 offset:33792
	ds_read_b128 v[180:183], v175 offset:34816
	ds_read_b128 v[184:187], v175 offset:35840
	ds_read_b128 v[188:191], v175 offset:36864
	ds_read_b128 v[192:195], v175 offset:37888
	ds_read_b128 v[196:199], v175 offset:38912
	ds_read_b128 v[200:203], v175 offset:39936
	global_load_lds_dwordx4 v144, s[36:37]
	s_mov_b32 m0, s48
	s_nop 0
	global_load_lds_dwordx4 v146, s[36:37]
	s_waitcnt vmcnt(8)
	s_waitcnt lgkmcnt(0)
	s_barrier
	s_setprio 1
	s_waitcnt lgkmcnt(0)
	v_mfma_f32_16x16x32_bf16 v[124:127], v[128:131], v[170:173], v[124:127]
	v_mfma_f32_16x16x32_bf16 v[120:123], v[136:139], v[170:173], v[120:123]
	v_mfma_f32_16x16x32_bf16 v[108:111], v[128:131], v[180:183], v[108:111]
	v_mfma_f32_16x16x32_bf16 v[104:107], v[136:139], v[180:183], v[104:107]
	v_mfma_f32_16x16x32_bf16 v[92:95], v[128:131], v[188:191], v[92:95]
	v_mfma_f32_16x16x32_bf16 v[88:91], v[136:139], v[188:191], v[88:91]
	v_mfma_f32_16x16x32_bf16 v[80:83], v[128:131], v[196:199], v[80:83]
	v_mfma_f32_16x16x32_bf16 v[72:75], v[136:139], v[196:199], v[72:75]
	v_mfma_f32_16x16x32_bf16 v[124:127], v[132:135], v[176:179], v[124:127]
	v_mfma_f32_16x16x32_bf16 v[120:123], v[140:143], v[176:179], v[120:123]
	v_mfma_f32_16x16x32_bf16 v[108:111], v[132:135], v[184:187], v[108:111]
	v_mfma_f32_16x16x32_bf16 v[104:107], v[140:143], v[184:187], v[104:107]
	v_mfma_f32_16x16x32_bf16 v[92:95], v[132:135], v[192:195], v[92:95]
	v_mfma_f32_16x16x32_bf16 v[88:91], v[140:143], v[192:195], v[88:91]
	v_mfma_f32_16x16x32_bf16 v[80:83], v[132:135], v[200:203], v[80:83]
	v_mfma_f32_16x16x32_bf16 v[72:75], v[140:143], v[200:203], v[72:75]
	s_setprio 0
	s_setprio 1
	v_mfma_f32_16x16x32_bf16 v[116:119], v[154:157], v[170:173], v[116:119]
	v_mfma_f32_16x16x32_bf16 v[112:115], v[162:165], v[170:173], v[112:115]
	v_mfma_f32_16x16x32_bf16 v[100:103], v[154:157], v[180:183], v[100:103]
	v_mfma_f32_16x16x32_bf16 v[96:99], v[162:165], v[180:183], v[96:99]
	v_mfma_f32_16x16x32_bf16 v[84:87], v[154:157], v[188:191], v[84:87]
	v_mfma_f32_16x16x32_bf16 v[76:79], v[162:165], v[188:191], v[76:79]
	v_mfma_f32_16x16x32_bf16 v[68:71], v[154:157], v[196:199], v[68:71]
	v_mfma_f32_16x16x32_bf16 v[64:67], v[162:165], v[196:199], v[64:67]
	v_mfma_f32_16x16x32_bf16 v[116:119], v[158:161], v[176:179], v[116:119]
	v_mfma_f32_16x16x32_bf16 v[112:115], v[166:169], v[176:179], v[112:115]
	v_mfma_f32_16x16x32_bf16 v[100:103], v[158:161], v[184:187], v[100:103]
	v_mfma_f32_16x16x32_bf16 v[96:99], v[166:169], v[184:187], v[96:99]
	v_mfma_f32_16x16x32_bf16 v[84:87], v[158:161], v[192:195], v[84:87]
	v_mfma_f32_16x16x32_bf16 v[76:79], v[166:169], v[192:195], v[76:79]
	v_mfma_f32_16x16x32_bf16 v[68:71], v[158:161], v[200:203], v[68:71]
	v_mfma_f32_16x16x32_bf16 v[64:67], v[166:169], v[200:203], v[64:67]
	s_setprio 0
	s_barrier
	s_add_i32 s36, s61, s41
	v_lshl_add_u64 v[204:205], v[204:205], 0, s[94:95]
	s_mov_b32 m0, s36
	ds_read_b128 v[170:173], v175 offset:49152
	ds_read_b128 v[176:179], v175 offset:50176
	ds_read_b128 v[180:183], v175 offset:51200
	ds_read_b128 v[184:187], v175 offset:52224
	ds_read_b128 v[188:191], v175 offset:53248
	ds_read_b128 v[192:195], v175 offset:54272
	ds_read_b128 v[196:199], v175 offset:55296
	ds_read_b128 v[200:203], v175 offset:56320
	global_load_lds_dwordx4 v[204:205], off
	s_add_i32 m0, s36, 0x2000
	s_add_u32 s34, s34, 0x40080
	v_lshl_add_u64 v[204:205], v[206:207], 0, s[94:95]
	s_addc_u32 s35, s35, 0
	s_add_i32 s36, s62, s41
	global_load_lds_dwordx4 v[204:205], off
	s_mov_b32 m0, s36
	s_nop 0
	global_load_lds_dwordx4 v232, s[34:35]
	s_add_i32 m0, s36, 0x2000
	s_nop 0
	global_load_lds_dwordx4 v148, s[34:35]
	v_lshl_add_u64 v[204:205], v[208:209], 0, s[94:95]
	s_mov_b32 m0, s51
	s_nop 0
	global_load_lds_dwordx4 v[204:205], off
	v_lshl_add_u64 v[204:205], v[210:211], 0, s[94:95]
	s_mov_b32 m0, s52
	s_nop 0
	global_load_lds_dwordx4 v[204:205], off
	s_waitcnt vmcnt(8)
	s_waitcnt lgkmcnt(0)
	s_barrier
	s_setprio 1
	s_waitcnt lgkmcnt(0)
	v_mfma_f32_16x16x32_bf16 v[60:63], v[128:131], v[170:173], v[60:63]
	v_mfma_f32_16x16x32_bf16 v[56:59], v[136:139], v[170:173], v[56:59]
	v_mfma_f32_16x16x32_bf16 v[48:51], v[128:131], v[180:183], v[48:51]
	v_mfma_f32_16x16x32_bf16 v[40:43], v[136:139], v[180:183], v[40:43]
	v_mfma_f32_16x16x32_bf16 v[28:31], v[128:131], v[188:191], v[28:31]
	v_mfma_f32_16x16x32_bf16 v[24:27], v[136:139], v[188:191], v[24:27]
	v_mfma_f32_16x16x32_bf16 v[16:19], v[128:131], v[196:199], v[16:19]
	v_mfma_f32_16x16x32_bf16 v[8:11], v[136:139], v[196:199], v[8:11]
	v_mfma_f32_16x16x32_bf16 v[60:63], v[132:135], v[176:179], v[60:63]
	v_mfma_f32_16x16x32_bf16 v[56:59], v[140:143], v[176:179], v[56:59]
	v_mfma_f32_16x16x32_bf16 v[48:51], v[132:135], v[184:187], v[48:51]
	v_mfma_f32_16x16x32_bf16 v[40:43], v[140:143], v[184:187], v[40:43]
	v_mfma_f32_16x16x32_bf16 v[28:31], v[132:135], v[192:195], v[28:31]
	v_mfma_f32_16x16x32_bf16 v[24:27], v[140:143], v[192:195], v[24:27]
	v_mfma_f32_16x16x32_bf16 v[16:19], v[132:135], v[200:203], v[16:19]
	v_mfma_f32_16x16x32_bf16 v[8:11], v[140:143], v[200:203], v[8:11]
	s_setprio 0
	s_setprio 1
	v_mfma_f32_16x16x32_bf16 v[52:55], v[154:157], v[170:173], v[52:55]
	v_mfma_f32_16x16x32_bf16 v[44:47], v[162:165], v[170:173], v[44:47]
	v_mfma_f32_16x16x32_bf16 v[36:39], v[154:157], v[180:183], v[36:39]
	v_mfma_f32_16x16x32_bf16 v[32:35], v[162:165], v[180:183], v[32:35]
	v_mfma_f32_16x16x32_bf16 v[20:23], v[154:157], v[188:191], v[20:23]
	v_mfma_f32_16x16x32_bf16 v[12:15], v[162:165], v[188:191], v[12:15]
	v_mfma_f32_16x16x32_bf16 v[4:7], v[154:157], v[196:199], v[4:7]
	v_mfma_f32_16x16x32_bf16 v[0:3], v[162:165], v[196:199], v[0:3]
	v_mfma_f32_16x16x32_bf16 v[52:55], v[158:161], v[176:179], v[52:55]
	v_mfma_f32_16x16x32_bf16 v[44:47], v[166:169], v[176:179], v[44:47]
	v_mfma_f32_16x16x32_bf16 v[36:39], v[158:161], v[184:187], v[36:39]
	v_mfma_f32_16x16x32_bf16 v[32:35], v[166:169], v[184:187], v[32:35]
	v_mfma_f32_16x16x32_bf16 v[20:23], v[158:161], v[192:195], v[20:23]
	v_mfma_f32_16x16x32_bf16 v[12:15], v[166:169], v[192:195], v[12:15]
	v_mfma_f32_16x16x32_bf16 v[4:7], v[158:161], v[200:203], v[4:7]
	v_mfma_f32_16x16x32_bf16 v[0:3], v[166:169], v[200:203], v[0:3]
	s_setprio 0
	s_barrier
	s_add_i32 s60, s60, 2
	s_add_u32 s58, s58, 0x100
	s_addc_u32 s59, s59, 0
	s_add_u32 s30, s30, 0x100
	s_addc_u32 s31, s31, 0
	s_cmp_gt_u32 s60, 13
	s_cbranch_scc0 .LBB0_1164
	s_and_b64 vcc, exec, s[18:19]
	s_cbranch_vccz .LBB0_1167
	s_barrier

.LBB0_1306:
	s_ashr_i32 s17, s16, 31
	s_lshl_b64 s[18:19], s[16:17], 19
	s_add_u32 s18, s34, s18
	s_addc_u32 s19, s35, s19
	s_and_b64 s[20:21], s[4:5], exec
	s_cselect_b32 s7, s19, s27
	s_cselect_b32 s17, s18, s26
	s_ashr_i32 s15, s14, 31
	s_lshl_b64 s[20:21], s[14:15], 19
	s_add_u32 s20, s36, s20
	s_addc_u32 s21, s37, s21
	s_and_b64 s[28:29], s[4:5], exec
	s_cselect_b32 s15, s21, s25
	s_cselect_b32 s23, s20, s24
	s_add_u32 s50, s24, 0x100
	s_addc_u32 s51, s25, 0
	s_add_u32 s24, s26, 0x40080
	s_addc_u32 s25, s27, 0
	s_mov_b32 s52, -2
	s_add_u32 s26, s24, 0xfffc0080
	s_addc_u32 s27, s25, -1
	s_add_i32 s53, 0, 0x10000
	s_cmp_eq_u32 s52, 12
	s_cselect_b32 s29, s7, s27
	s_cselect_b32 s28, s17, s26
	v_add_u32_e32 v142, s53, v144
	s_cselect_b32 s27, s15, s51
	s_cselect_b32 s26, s23, s50
	s_add_i32 s56, 0, 0x14000
	ds_read_b128 v[138:141], v142
	ds_read_b128 v[146:149], v142 offset:1024
	ds_read_b128 v[150:153], v142 offset:2048
	ds_read_b128 v[154:157], v142 offset:3072
	v_add_u32_e32 v142, s56, v144
	ds_read_b128 v[158:161], v142
	ds_read_b128 v[162:165], v142 offset:1024
	ds_read_b128 v[166:169], v142 offset:2048
	ds_read_b128 v[170:173], v142 offset:3072
	v_lshl_add_u64 v[142:143], s[24:25], 0, v[136:137]
	s_add_i32 m0, s39, 0xc000
	ds_read_b128 v[174:177], v145
	ds_read_b128 v[178:181], v145 offset:1024
	ds_read_b128 v[182:185], v145 offset:2048
	ds_read_b128 v[186:189], v145 offset:3072
	ds_read_b128 v[190:193], v145 offset:4096
	ds_read_b128 v[194:197], v145 offset:5120
	ds_read_b128 v[198:201], v145 offset:6144
	ds_read_b128 v[202:205], v145 offset:7168
	global_load_lds_dwordx4 v136, s[24:25]
	v_lshl_add_u64 v[142:143], s[24:25], 0, v[134:135]
	s_add_i32 m0, s39, 0xe000
	s_nop 0
	global_load_lds_dwordx4 v134, s[24:25]
	s_waitcnt vmcnt(8)
	s_waitcnt lgkmcnt(0)
	s_barrier
	s_setprio 1
	s_waitcnt lgkmcnt(0)
	v_mfma_f32_16x16x32_bf16 v[124:127], v[138:141], v[174:177], 0
	v_mfma_f32_16x16x32_bf16 v[120:123], v[150:153], v[174:177], 0
	v_mfma_f32_16x16x32_bf16 v[108:111], v[138:141], v[182:185], 0
	v_mfma_f32_16x16x32_bf16 v[104:107], v[150:153], v[182:185], 0
	v_mfma_f32_16x16x32_bf16 v[92:95], v[138:141], v[190:193], 0
	v_mfma_f32_16x16x32_bf16 v[88:91], v[150:153], v[190:193], 0
	v_mfma_f32_16x16x32_bf16 v[76:79], v[138:141], v[198:201], 0
	v_mfma_f32_16x16x32_bf16 v[72:75], v[150:153], v[198:201], 0
	v_mfma_f32_16x16x32_bf16 v[124:127], v[146:149], v[178:181], v[124:127]
	v_mfma_f32_16x16x32_bf16 v[120:123], v[154:157], v[178:181], v[120:123]
	v_mfma_f32_16x16x32_bf16 v[108:111], v[146:149], v[186:189], v[108:111]
	v_mfma_f32_16x16x32_bf16 v[104:107], v[154:157], v[186:189], v[104:107]
	v_mfma_f32_16x16x32_bf16 v[92:95], v[146:149], v[194:197], v[92:95]
	v_mfma_f32_16x16x32_bf16 v[88:91], v[154:157], v[194:197], v[88:91]
	v_mfma_f32_16x16x32_bf16 v[76:79], v[146:149], v[202:205], v[76:79]
	v_mfma_f32_16x16x32_bf16 v[72:75], v[154:157], v[202:205], v[72:75]
	s_setprio 0
	s_setprio 1
	v_mfma_f32_16x16x32_bf16 v[116:119], v[158:161], v[174:177], 0
	v_mfma_f32_16x16x32_bf16 v[112:115], v[166:169], v[174:177], 0
	v_mfma_f32_16x16x32_bf16 v[100:103], v[158:161], v[182:185], 0
	v_mfma_f32_16x16x32_bf16 v[96:99], v[166:169], v[182:185], 0
	v_mfma_f32_16x16x32_bf16 v[84:87], v[158:161], v[190:193], 0
	v_mfma_f32_16x16x32_bf16 v[80:83], v[166:169], v[190:193], 0
	v_mfma_f32_16x16x32_bf16 v[68:71], v[158:161], v[198:201], 0
	v_mfma_f32_16x16x32_bf16 v[64:67], v[166:169], v[198:201], 0
	v_mfma_f32_16x16x32_bf16 v[116:119], v[162:165], v[178:181], v[116:119]
	v_mfma_f32_16x16x32_bf16 v[112:115], v[170:173], v[178:181], v[112:115]
	v_mfma_f32_16x16x32_bf16 v[100:103], v[162:165], v[186:189], v[100:103]
	v_mfma_f32_16x16x32_bf16 v[96:99], v[170:173], v[186:189], v[96:99]
	v_mfma_f32_16x16x32_bf16 v[84:87], v[162:165], v[194:197], v[84:87]
	v_mfma_f32_16x16x32_bf16 v[80:83], v[170:173], v[194:197], v[80:83]
	v_mfma_f32_16x16x32_bf16 v[68:71], v[162:165], v[202:205], v[68:71]
	v_mfma_f32_16x16x32_bf16 v[64:67], v[170:173], v[202:205], v[64:67]
	s_setprio 0
	s_barrier
	s_add_i32 s53, s53, s38
	v_lshl_add_u64 v[142:143], s[26:27], 0, v[232:233]
	s_mov_b32 m0, s53
	ds_read_b128 v[174:177], v145 offset:16384
	ds_read_b128 v[178:181], v145 offset:17408
	ds_read_b128 v[182:185], v145 offset:18432
	ds_read_b128 v[186:189], v145 offset:19456
	ds_read_b128 v[190:193], v145 offset:20480
	ds_read_b128 v[194:197], v145 offset:21504
	ds_read_b128 v[198:201], v145 offset:22528
	ds_read_b128 v[202:205], v145 offset:23552
	global_load_lds_dwordx4 v232, s[26:27]
	s_add_i32 m0, s53, 0x2000
	s_add_u32 s54, s26, 0x40000
	v_lshl_add_u64 v[206:207], s[26:27], 0, v[132:133]
	s_addc_u32 s55, s27, 0
	s_add_i32 s53, s56, s38
	global_load_lds_dwordx4 v132, s[26:27]
	s_mov_b32 m0, s53
	v_lshl_add_u64 v[210:211], s[28:29], 0, v[130:131]
	global_load_lds_dwordx4 v232, s[54:55]
	s_add_i32 m0, s53, 0x2000
	s_nop 0
	global_load_lds_dwordx4 v132, s[54:55]
	v_lshl_add_u64 v[208:209], s[28:29], 0, v[128:129]
	s_waitcnt vmcnt(6)
	s_waitcnt lgkmcnt(0)
	s_barrier
	s_setprio 1
	s_waitcnt lgkmcnt(0)
	v_mfma_f32_16x16x32_bf16 v[60:63], v[138:141], v[174:177], 0
	v_mfma_f32_16x16x32_bf16 v[56:59], v[150:153], v[174:177], 0
	v_mfma_f32_16x16x32_bf16 v[44:47], v[138:141], v[182:185], 0
	v_mfma_f32_16x16x32_bf16 v[40:43], v[150:153], v[182:185], 0
	v_mfma_f32_16x16x32_bf16 v[28:31], v[138:141], v[190:193], 0
	v_mfma_f32_16x16x32_bf16 v[24:27], v[150:153], v[190:193], 0
	v_mfma_f32_16x16x32_bf16 v[12:15], v[138:141], v[198:201], 0
	v_mfma_f32_16x16x32_bf16 v[8:11], v[150:153], v[198:201], 0
	v_mfma_f32_16x16x32_bf16 v[60:63], v[146:149], v[178:181], v[60:63]
	v_mfma_f32_16x16x32_bf16 v[56:59], v[154:157], v[178:181], v[56:59]
	v_mfma_f32_16x16x32_bf16 v[44:47], v[146:149], v[186:189], v[44:47]
	v_mfma_f32_16x16x32_bf16 v[40:43], v[154:157], v[186:189], v[40:43]
	v_mfma_f32_16x16x32_bf16 v[28:31], v[146:149], v[194:197], v[28:31]
	v_mfma_f32_16x16x32_bf16 v[24:27], v[154:157], v[194:197], v[24:27]
	v_mfma_f32_16x16x32_bf16 v[12:15], v[146:149], v[202:205], v[12:15]
	v_mfma_f32_16x16x32_bf16 v[8:11], v[154:157], v[202:205], v[8:11]
	s_setprio 0
	s_setprio 1
	v_mfma_f32_16x16x32_bf16 v[52:55], v[158:161], v[174:177], 0
	v_mfma_f32_16x16x32_bf16 v[48:51], v[166:169], v[174:177], 0
	v_mfma_f32_16x16x32_bf16 v[36:39], v[158:161], v[182:185], 0
	v_mfma_f32_16x16x32_bf16 v[32:35], v[166:169], v[182:185], 0
	v_mfma_f32_16x16x32_bf16 v[20:23], v[158:161], v[190:193], 0
	v_mfma_f32_16x16x32_bf16 v[16:19], v[166:169], v[190:193], 0
	v_mfma_f32_16x16x32_bf16 v[4:7], v[158:161], v[198:201], 0
	v_mfma_f32_16x16x32_bf16 v[0:3], v[166:169], v[198:201], 0
	v_mfma_f32_16x16x32_bf16 v[52:55], v[162:165], v[178:181], v[52:55]
	v_mfma_f32_16x16x32_bf16 v[48:51], v[170:173], v[178:181], v[48:51]
	v_mfma_f32_16x16x32_bf16 v[36:39], v[162:165], v[186:189], v[36:39]
	v_mfma_f32_16x16x32_bf16 v[32:35], v[170:173], v[186:189], v[32:35]
	v_mfma_f32_16x16x32_bf16 v[20:23], v[162:165], v[194:197], v[20:23]
	v_mfma_f32_16x16x32_bf16 v[16:19], v[170:173], v[194:197], v[16:19]
	v_mfma_f32_16x16x32_bf16 v[4:7], v[162:165], v[202:205], v[4:7]
	v_mfma_f32_16x16x32_bf16 v[0:3], v[170:173], v[202:205], v[0:3]
	s_setprio 0
	s_barrier
	s_branch .Lzmid_4
.LBB0_1307:
	s_add_u32 s26, s24, 0xfffc0080
	s_addc_u32 s27, s25, -1
	s_add_i32 s53, 0, 0x10000
	s_cmp_eq_u32 s52, 12
	s_cselect_b32 s29, s7, s27
	s_cselect_b32 s28, s17, s26
	v_add_u32_e32 v142, s53, v144
	s_cselect_b32 s27, s15, s51
	s_cselect_b32 s26, s23, s50
	s_add_i32 s56, 0, 0x14000
	ds_read_b128 v[138:141], v142
	ds_read_b128 v[146:149], v142 offset:1024
	ds_read_b128 v[150:153], v142 offset:2048
	ds_read_b128 v[154:157], v142 offset:3072
	v_add_u32_e32 v142, s56, v144
	ds_read_b128 v[158:161], v142
	ds_read_b128 v[162:165], v142 offset:1024
	ds_read_b128 v[166:169], v142 offset:2048
	ds_read_b128 v[170:173], v142 offset:3072
	v_lshl_add_u64 v[142:143], s[24:25], 0, v[136:137]
	s_add_i32 m0, s39, 0xc000
	ds_read_b128 v[174:177], v145
	ds_read_b128 v[178:181], v145 offset:1024
	ds_read_b128 v[182:185], v145 offset:2048
	ds_read_b128 v[186:189], v145 offset:3072
	ds_read_b128 v[190:193], v145 offset:4096
	ds_read_b128 v[194:197], v145 offset:5120
	ds_read_b128 v[198:201], v145 offset:6144
	ds_read_b128 v[202:205], v145 offset:7168
	global_load_lds_dwordx4 v136, s[24:25]
	v_lshl_add_u64 v[142:143], s[24:25], 0, v[134:135]
	s_add_i32 m0, s39, 0xe000
	s_nop 0
	global_load_lds_dwordx4 v134, s[24:25]
	s_waitcnt vmcnt(8)
	s_waitcnt lgkmcnt(0)
	s_barrier
	s_setprio 1
	s_waitcnt lgkmcnt(0)
	v_mfma_f32_16x16x32_bf16 v[124:127], v[138:141], v[174:177], v[124:127]
	v_mfma_f32_16x16x32_bf16 v[120:123], v[150:153], v[174:177], v[120:123]
	v_mfma_f32_16x16x32_bf16 v[108:111], v[138:141], v[182:185], v[108:111]
	v_mfma_f32_16x16x32_bf16 v[104:107], v[150:153], v[182:185], v[104:107]
	v_mfma_f32_16x16x32_bf16 v[92:95], v[138:141], v[190:193], v[92:95]
	v_mfma_f32_16x16x32_bf16 v[88:91], v[150:153], v[190:193], v[88:91]
	v_mfma_f32_16x16x32_bf16 v[76:79], v[138:141], v[198:201], v[76:79]
	v_mfma_f32_16x16x32_bf16 v[72:75], v[150:153], v[198:201], v[72:75]
	v_mfma_f32_16x16x32_bf16 v[124:127], v[146:149], v[178:181], v[124:127]
	v_mfma_f32_16x16x32_bf16 v[120:123], v[154:157], v[178:181], v[120:123]
	v_mfma_f32_16x16x32_bf16 v[108:111], v[146:149], v[186:189], v[108:111]
	v_mfma_f32_16x16x32_bf16 v[104:107], v[154:157], v[186:189], v[104:107]
	v_mfma_f32_16x16x32_bf16 v[92:95], v[146:149], v[194:197], v[92:95]
	v_mfma_f32_16x16x32_bf16 v[88:91], v[154:157], v[194:197], v[88:91]
	v_mfma_f32_16x16x32_bf16 v[76:79], v[146:149], v[202:205], v[76:79]
	v_mfma_f32_16x16x32_bf16 v[72:75], v[154:157], v[202:205], v[72:75]
	s_setprio 0
	s_setprio 1
	v_mfma_f32_16x16x32_bf16 v[116:119], v[158:161], v[174:177], v[116:119]
	v_mfma_f32_16x16x32_bf16 v[112:115], v[166:169], v[174:177], v[112:115]
	v_mfma_f32_16x16x32_bf16 v[100:103], v[158:161], v[182:185], v[100:103]
	v_mfma_f32_16x16x32_bf16 v[96:99], v[166:169], v[182:185], v[96:99]
	v_mfma_f32_16x16x32_bf16 v[84:87], v[158:161], v[190:193], v[84:87]
	v_mfma_f32_16x16x32_bf16 v[80:83], v[166:169], v[190:193], v[80:83]
	v_mfma_f32_16x16x32_bf16 v[68:71], v[158:161], v[198:201], v[68:71]
	v_mfma_f32_16x16x32_bf16 v[64:67], v[166:169], v[198:201], v[64:67]
	v_mfma_f32_16x16x32_bf16 v[116:119], v[162:165], v[178:181], v[116:119]
	v_mfma_f32_16x16x32_bf16 v[112:115], v[170:173], v[178:181], v[112:115]
	v_mfma_f32_16x16x32_bf16 v[100:103], v[162:165], v[186:189], v[100:103]
	v_mfma_f32_16x16x32_bf16 v[96:99], v[170:173], v[186:189], v[96:99]
	v_mfma_f32_16x16x32_bf16 v[84:87], v[162:165], v[194:197], v[84:87]
	v_mfma_f32_16x16x32_bf16 v[80:83], v[170:173], v[194:197], v[80:83]
	v_mfma_f32_16x16x32_bf16 v[68:71], v[162:165], v[202:205], v[68:71]
	v_mfma_f32_16x16x32_bf16 v[64:67], v[170:173], v[202:205], v[64:67]
	s_setprio 0
	s_barrier
	s_add_i32 s53, s53, s38
	v_lshl_add_u64 v[142:143], s[26:27], 0, v[232:233]
	s_mov_b32 m0, s53
	ds_read_b128 v[174:177], v145 offset:16384
	ds_read_b128 v[178:181], v145 offset:17408
	ds_read_b128 v[182:185], v145 offset:18432
	ds_read_b128 v[186:189], v145 offset:19456
	ds_read_b128 v[190:193], v145 offset:20480
	ds_read_b128 v[194:197], v145 offset:21504
	ds_read_b128 v[198:201], v145 offset:22528
	ds_read_b128 v[202:205], v145 offset:23552
	global_load_lds_dwordx4 v232, s[26:27]
	s_add_i32 m0, s53, 0x2000
	s_add_u32 s54, s26, 0x40000
	v_lshl_add_u64 v[206:207], s[26:27], 0, v[132:133]
	s_addc_u32 s55, s27, 0
	s_add_i32 s53, s56, s38
	global_load_lds_dwordx4 v132, s[26:27]
	s_mov_b32 m0, s53
	v_lshl_add_u64 v[210:211], s[28:29], 0, v[130:131]
	global_load_lds_dwordx4 v232, s[54:55]
	s_add_i32 m0, s53, 0x2000
	s_nop 0
	global_load_lds_dwordx4 v132, s[54:55]
	v_lshl_add_u64 v[208:209], s[28:29], 0, v[128:129]
	s_waitcnt vmcnt(6)
	s_waitcnt lgkmcnt(0)
	s_barrier
	s_setprio 1
	s_waitcnt lgkmcnt(0)
	v_mfma_f32_16x16x32_bf16 v[60:63], v[138:141], v[174:177], v[60:63]
	v_mfma_f32_16x16x32_bf16 v[56:59], v[150:153], v[174:177], v[56:59]
	v_mfma_f32_16x16x32_bf16 v[44:47], v[138:141], v[182:185], v[44:47]
	v_mfma_f32_16x16x32_bf16 v[40:43], v[150:153], v[182:185], v[40:43]
	v_mfma_f32_16x16x32_bf16 v[28:31], v[138:141], v[190:193], v[28:31]
	v_mfma_f32_16x16x32_bf16 v[24:27], v[150:153], v[190:193], v[24:27]
	v_mfma_f32_16x16x32_bf16 v[12:15], v[138:141], v[198:201], v[12:15]
	v_mfma_f32_16x16x32_bf16 v[8:11], v[150:153], v[198:201], v[8:11]
	v_mfma_f32_16x16x32_bf16 v[60:63], v[146:149], v[178:181], v[60:63]
	v_mfma_f32_16x16x32_bf16 v[56:59], v[154:157], v[178:181], v[56:59]
	v_mfma_f32_16x16x32_bf16 v[44:47], v[146:149], v[186:189], v[44:47]
	v_mfma_f32_16x16x32_bf16 v[40:43], v[154:157], v[186:189], v[40:43]
	v_mfma_f32_16x16x32_bf16 v[28:31], v[146:149], v[194:197], v[28:31]
	v_mfma_f32_16x16x32_bf16 v[24:27], v[154:157], v[194:197], v[24:27]
	v_mfma_f32_16x16x32_bf16 v[12:15], v[146:149], v[202:205], v[12:15]
	v_mfma_f32_16x16x32_bf16 v[8:11], v[154:157], v[202:205], v[8:11]
	s_setprio 0
	s_setprio 1
	v_mfma_f32_16x16x32_bf16 v[52:55], v[158:161], v[174:177], v[52:55]
	v_mfma_f32_16x16x32_bf16 v[48:51], v[166:169], v[174:177], v[48:51]
	v_mfma_f32_16x16x32_bf16 v[36:39], v[158:161], v[182:185], v[36:39]
	v_mfma_f32_16x16x32_bf16 v[32:35], v[166:169], v[182:185], v[32:35]
	v_mfma_f32_16x16x32_bf16 v[20:23], v[158:161], v[190:193], v[20:23]
	v_mfma_f32_16x16x32_bf16 v[16:19], v[166:169], v[190:193], v[16:19]
	v_mfma_f32_16x16x32_bf16 v[4:7], v[158:161], v[198:201], v[4:7]
	v_mfma_f32_16x16x32_bf16 v[0:3], v[166:169], v[198:201], v[0:3]
	v_mfma_f32_16x16x32_bf16 v[52:55], v[162:165], v[178:181], v[52:55]
	v_mfma_f32_16x16x32_bf16 v[48:51], v[170:173], v[178:181], v[48:51]
	v_mfma_f32_16x16x32_bf16 v[36:39], v[162:165], v[186:189], v[36:39]
	v_mfma_f32_16x16x32_bf16 v[32:35], v[170:173], v[186:189], v[32:35]
	v_mfma_f32_16x16x32_bf16 v[20:23], v[162:165], v[194:197], v[20:23]
	v_mfma_f32_16x16x32_bf16 v[16:19], v[170:173], v[194:197], v[16:19]
	v_mfma_f32_16x16x32_bf16 v[4:7], v[162:165], v[202:205], v[4:7]
	v_mfma_f32_16x16x32_bf16 v[0:3], v[170:173], v[202:205], v[0:3]
	s_setprio 0
	s_barrier
.Lzmid_4:
	s_add_i32 s53, 0, 0x18000
	s_add_i32 s54, 0, 0x1c000
	v_add_u32_e32 v154, s53, v144
	v_add_u32_e32 v170, s54, v144
	ds_read_b128 v[138:141], v154
	ds_read_b128 v[146:149], v154 offset:1024
	ds_read_b128 v[150:153], v154 offset:2048
	ds_read_b128 v[154:157], v154 offset:3072
	ds_read_b128 v[158:161], v170
	ds_read_b128 v[162:165], v170 offset:1024
	ds_read_b128 v[166:169], v170 offset:2048
	ds_read_b128 v[170:173], v170 offset:3072
	s_add_u32 s28, s28, 0x40000
	s_addc_u32 s29, s29, 0
	s_mov_b32 m0, s39
	s_nop 0
	global_load_lds_dwordx4 v[208:209], off
	s_mov_b32 m0, s40
	s_nop 0
	global_load_lds_dwordx4 v[210:211], off
	s_mov_b32 m0, s41
	ds_read_b128 v[174:177], v145 offset:32768
	ds_read_b128 v[178:181], v145 offset:33792
	ds_read_b128 v[182:185], v145 offset:34816
	ds_read_b128 v[186:189], v145 offset:35840
	ds_read_b128 v[190:193], v145 offset:36864
	ds_read_b128 v[194:197], v145 offset:37888
	ds_read_b128 v[198:201], v145 offset:38912
	ds_read_b128 v[202:205], v145 offset:39936
	global_load_lds_dwordx4 v128, s[28:29]
	s_mov_b32 m0, s42
	s_nop 0
	global_load_lds_dwordx4 v130, s[28:29]
	s_waitcnt vmcnt(8)
	s_waitcnt lgkmcnt(0)
	s_barrier
	s_setprio 1
	s_waitcnt lgkmcnt(0)
	v_mfma_f32_16x16x32_bf16 v[124:127], v[138:141], v[174:177], v[124:127]
	v_mfma_f32_16x16x32_bf16 v[120:123], v[150:153], v[174:177], v[120:123]
	v_mfma_f32_16x16x32_bf16 v[108:111], v[138:141], v[182:185], v[108:111]
	v_mfma_f32_16x16x32_bf16 v[104:107], v[150:153], v[182:185], v[104:107]
	v_mfma_f32_16x16x32_bf16 v[92:95], v[138:141], v[190:193], v[92:95]
	v_mfma_f32_16x16x32_bf16 v[88:91], v[150:153], v[190:193], v[88:91]
	v_mfma_f32_16x16x32_bf16 v[76:79], v[138:141], v[198:201], v[76:79]
	v_mfma_f32_16x16x32_bf16 v[72:75], v[150:153], v[198:201], v[72:75]
	v_mfma_f32_16x16x32_bf16 v[124:127], v[146:149], v[178:181], v[124:127]
	v_mfma_f32_16x16x32_bf16 v[120:123], v[154:157], v[178:181], v[120:123]
	v_mfma_f32_16x16x32_bf16 v[108:111], v[146:149], v[186:189], v[108:111]
	v_mfma_f32_16x16x32_bf16 v[104:107], v[154:157], v[186:189], v[104:107]
	v_mfma_f32_16x16x32_bf16 v[92:95], v[146:149], v[194:197], v[92:95]
	v_mfma_f32_16x16x32_bf16 v[88:91], v[154:157], v[194:197], v[88:91]
	v_mfma_f32_16x16x32_bf16 v[76:79], v[146:149], v[202:205], v[76:79]
	v_mfma_f32_16x16x32_bf16 v[72:75], v[154:157], v[202:205], v[72:75]
	s_setprio 0
	s_setprio 1
	v_mfma_f32_16x16x32_bf16 v[116:119], v[158:161], v[174:177], v[116:119]
	v_mfma_f32_16x16x32_bf16 v[112:115], v[166:169], v[174:177], v[112:115]
	v_mfma_f32_16x16x32_bf16 v[100:103], v[158:161], v[182:185], v[100:103]
	v_mfma_f32_16x16x32_bf16 v[96:99], v[166:169], v[182:185], v[96:99]
	v_mfma_f32_16x16x32_bf16 v[84:87], v[158:161], v[190:193], v[84:87]
	v_mfma_f32_16x16x32_bf16 v[80:83], v[166:169], v[190:193], v[80:83]
	v_mfma_f32_16x16x32_bf16 v[68:71], v[158:161], v[198:201], v[68:71]
	v_mfma_f32_16x16x32_bf16 v[64:67], v[166:169], v[198:201], v[64:67]
	v_mfma_f32_16x16x32_bf16 v[116:119], v[162:165], v[178:181], v[116:119]
	v_mfma_f32_16x16x32_bf16 v[112:115], v[170:173], v[178:181], v[112:115]
	v_mfma_f32_16x16x32_bf16 v[100:103], v[162:165], v[186:189], v[100:103]
	v_mfma_f32_16x16x32_bf16 v[96:99], v[170:173], v[186:189], v[96:99]
	v_mfma_f32_16x16x32_bf16 v[84:87], v[162:165], v[194:197], v[84:87]
	v_mfma_f32_16x16x32_bf16 v[80:83], v[170:173], v[194:197], v[80:83]
	v_mfma_f32_16x16x32_bf16 v[68:71], v[162:165], v[202:205], v[68:71]
	v_mfma_f32_16x16x32_bf16 v[64:67], v[170:173], v[202:205], v[64:67]
	s_setprio 0
	s_barrier
	s_add_i32 s28, s53, s38
	v_lshl_add_u64 v[142:143], v[142:143], 0, s[94:95]
	s_mov_b32 m0, s28
	ds_read_b128 v[174:177], v145 offset:49152
	ds_read_b128 v[178:181], v145 offset:50176
	ds_read_b128 v[182:185], v145 offset:51200
	ds_read_b128 v[186:189], v145 offset:52224
	ds_read_b128 v[190:193], v145 offset:53248
	ds_read_b128 v[194:197], v145 offset:54272
	ds_read_b128 v[198:201], v145 offset:55296
	ds_read_b128 v[202:205], v145 offset:56320
	global_load_lds_dwordx4 v[142:143], off
	s_add_i32 m0, s28, 0x2000
	s_add_u32 s26, s26, 0x40080
	v_lshl_add_u64 v[142:143], v[206:207], 0, s[94:95]
	s_addc_u32 s27, s27, 0
	s_add_i32 s28, s54, s38
	global_load_lds_dwordx4 v[142:143], off
	s_mov_b32 m0, s28
	s_nop 0
	global_load_lds_dwordx4 v232, s[26:27]
	s_add_i32 m0, s28, 0x2000
	s_nop 0
	global_load_lds_dwordx4 v132, s[26:27]
	v_lshl_add_u64 v[142:143], v[208:209], 0, s[94:95]
	s_mov_b32 m0, s45
	s_nop 0
	global_load_lds_dwordx4 v[142:143], off
	v_lshl_add_u64 v[142:143], v[210:211], 0, s[94:95]
	s_mov_b32 m0, s46
	s_nop 0
	global_load_lds_dwordx4 v[142:143], off
	s_waitcnt vmcnt(8)
	s_waitcnt lgkmcnt(0)
	s_barrier
	s_setprio 1
	s_waitcnt lgkmcnt(0)
	v_mfma_f32_16x16x32_bf16 v[60:63], v[138:141], v[174:177], v[60:63]
	v_mfma_f32_16x16x32_bf16 v[56:59], v[150:153], v[174:177], v[56:59]
	v_mfma_f32_16x16x32_bf16 v[44:47], v[138:141], v[182:185], v[44:47]
	v_mfma_f32_16x16x32_bf16 v[40:43], v[150:153], v[182:185], v[40:43]
	v_mfma_f32_16x16x32_bf16 v[28:31], v[138:141], v[190:193], v[28:31]
	v_mfma_f32_16x16x32_bf16 v[24:27], v[150:153], v[190:193], v[24:27]
	v_mfma_f32_16x16x32_bf16 v[12:15], v[138:141], v[198:201], v[12:15]
	v_mfma_f32_16x16x32_bf16 v[8:11], v[150:153], v[198:201], v[8:11]
	v_mfma_f32_16x16x32_bf16 v[60:63], v[146:149], v[178:181], v[60:63]
	v_mfma_f32_16x16x32_bf16 v[56:59], v[154:157], v[178:181], v[56:59]
	v_mfma_f32_16x16x32_bf16 v[44:47], v[146:149], v[186:189], v[44:47]
	v_mfma_f32_16x16x32_bf16 v[40:43], v[154:157], v[186:189], v[40:43]
	v_mfma_f32_16x16x32_bf16 v[28:31], v[146:149], v[194:197], v[28:31]
	v_mfma_f32_16x16x32_bf16 v[24:27], v[154:157], v[194:197], v[24:27]
	v_mfma_f32_16x16x32_bf16 v[12:15], v[146:149], v[202:205], v[12:15]
	v_mfma_f32_16x16x32_bf16 v[8:11], v[154:157], v[202:205], v[8:11]
	s_setprio 0
	s_setprio 1
	v_mfma_f32_16x16x32_bf16 v[52:55], v[158:161], v[174:177], v[52:55]
	v_mfma_f32_16x16x32_bf16 v[48:51], v[166:169], v[174:177], v[48:51]
	v_mfma_f32_16x16x32_bf16 v[36:39], v[158:161], v[182:185], v[36:39]
	v_mfma_f32_16x16x32_bf16 v[32:35], v[166:169], v[182:185], v[32:35]
	v_mfma_f32_16x16x32_bf16 v[20:23], v[158:161], v[190:193], v[20:23]
	v_mfma_f32_16x16x32_bf16 v[16:19], v[166:169], v[190:193], v[16:19]
	v_mfma_f32_16x16x32_bf16 v[4:7], v[158:161], v[198:201], v[4:7]
	v_mfma_f32_16x16x32_bf16 v[0:3], v[166:169], v[198:201], v[0:3]
	v_mfma_f32_16x16x32_bf16 v[52:55], v[162:165], v[178:181], v[52:55]
	v_mfma_f32_16x16x32_bf16 v[48:51], v[170:173], v[178:181], v[48:51]
	v_mfma_f32_16x16x32_bf16 v[36:39], v[162:165], v[186:189], v[36:39]
	v_mfma_f32_16x16x32_bf16 v[32:35], v[170:173], v[186:189], v[32:35]
	v_mfma_f32_16x16x32_bf16 v[20:23], v[162:165], v[194:197], v[20:23]
	v_mfma_f32_16x16x32_bf16 v[16:19], v[170:173], v[194:197], v[16:19]
	v_mfma_f32_16x16x32_bf16 v[4:7], v[162:165], v[202:205], v[4:7]
	v_mfma_f32_16x16x32_bf16 v[0:3], v[170:173], v[202:205], v[0:3]
	s_setprio 0
	s_barrier
	s_add_i32 s52, s52, 2
	s_add_u32 s50, s50, 0x100
	s_addc_u32 s51, s51, 0
	s_add_u32 s24, s24, 0x100
	s_addc_u32 s25, s25, 0
	s_cmp_gt_u32 s52, 13
	s_cbranch_scc0 .LBB0_1307
	s_and_b64 vcc, exec, s[12:13]
	s_cbranch_vccz .LBB0_1310
	s_barrier

.LBB0_1491:
	s_ashr_i32 s23, s22, 31
	s_lshl_b64 s[24:25], s[22:23], 21
	s_add_u32 s24, s70, s24
	s_addc_u32 s25, s71, s25
	s_and_b64 s[26:27], s[4:5], exec
	s_cselect_b32 s23, s25, s35
	s_cselect_b32 s56, s24, s34
	s_ashr_i32 s21, s20, 31
	s_lshl_b64 s[26:27], s[20:21], 21
	s_add_u32 s26, s72, s26
	s_addc_u32 s27, s76, s27
	s_and_b64 s[36:37], s[4:5], exec
	s_cselect_b32 s21, s27, s31
	s_cselect_b32 s57, s26, s30
	s_add_u32 s58, s30, 0x100
	s_addc_u32 s59, s31, 0
	s_add_u32 s30, s34, 0x100080
	s_addc_u32 s31, s35, 0
	s_mov_b32 s60, -2
	s_waitcnt vmcnt(0)
	s_add_u32 s34, s30, 0xfff00080
	s_addc_u32 s35, s31, -1
	s_add_i32 s61, 0, 0x10000
	s_cmp_eq_u32 s60, 60
	s_cselect_b32 s37, s23, s35
	s_cselect_b32 s36, s56, s34
	s_cselect_b32 s35, s21, s59
	s_cselect_b32 s34, s57, s58
	s_add_i32 s64, 0, 0x14000
	v_add_u32_e32 v100, s61, v220
	v_add_u32_e32 v156, s64, v220
	ds_read_b128 v[88:91], v100
	ds_read_b128 v[92:95], v100 offset:1024
	ds_read_b128 v[96:99], v100 offset:2048
	ds_read_b128 v[100:103], v100 offset:3072
	ds_read_b128 v[144:147], v156
	ds_read_b128 v[148:151], v156 offset:1024
	ds_read_b128 v[152:155], v156 offset:2048
	ds_read_b128 v[156:159], v156 offset:3072
	v_lshl_add_u64 v[202:203], s[30:31], 0, v[188:189]
	s_add_i32 m0, s78, 0xc000
	ds_read_b128 v[160:163], v221
	ds_read_b128 v[164:167], v221 offset:1024
	ds_read_b128 v[168:171], v221 offset:2048
	ds_read_b128 v[172:175], v221 offset:3072
	ds_read_b128 v[176:179], v221 offset:4096
	ds_read_b128 v[190:193], v221 offset:5120
	ds_read_b128 v[194:197], v221 offset:6144
	ds_read_b128 v[198:201], v221 offset:7168
	global_load_lds_dwordx4 v188, s[30:31]
	v_lshl_add_u64 v[202:203], s[30:31], 0, v[186:187]
	s_add_i32 m0, s78, 0xe000
	s_nop 0
	global_load_lds_dwordx4 v186, s[30:31]
	s_waitcnt vmcnt(8)
	s_waitcnt lgkmcnt(0)
	s_barrier
	s_setprio 1
	s_waitcnt lgkmcnt(0)
	v_mfma_f32_16x16x32_bf16 v[140:143], v[88:91], v[160:163], 0
	v_mfma_f32_16x16x32_bf16 v[136:139], v[96:99], v[160:163], 0
	v_mfma_f32_16x16x32_bf16 v[124:127], v[88:91], v[168:171], 0
	v_mfma_f32_16x16x32_bf16 v[120:123], v[96:99], v[168:171], 0
	v_mfma_f32_16x16x32_bf16 v[108:111], v[88:91], v[176:179], 0
	v_mfma_f32_16x16x32_bf16 v[104:107], v[96:99], v[176:179], 0
	v_mfma_f32_16x16x32_bf16 v[76:79], v[88:91], v[194:197], 0
	v_mfma_f32_16x16x32_bf16 v[72:75], v[96:99], v[194:197], 0
	v_mfma_f32_16x16x32_bf16 v[140:143], v[92:95], v[164:167], v[140:143]
	v_mfma_f32_16x16x32_bf16 v[136:139], v[100:103], v[164:167], v[136:139]
	v_mfma_f32_16x16x32_bf16 v[124:127], v[92:95], v[172:175], v[124:127]
	v_mfma_f32_16x16x32_bf16 v[120:123], v[100:103], v[172:175], v[120:123]
	v_mfma_f32_16x16x32_bf16 v[108:111], v[92:95], v[190:193], v[108:111]
	v_mfma_f32_16x16x32_bf16 v[104:107], v[100:103], v[190:193], v[104:107]
	v_mfma_f32_16x16x32_bf16 v[76:79], v[92:95], v[198:201], v[76:79]
	v_mfma_f32_16x16x32_bf16 v[72:75], v[100:103], v[198:201], v[72:75]
	s_setprio 0
	s_setprio 1
	v_mfma_f32_16x16x32_bf16 v[132:135], v[144:147], v[160:163], 0
	v_mfma_f32_16x16x32_bf16 v[128:131], v[152:155], v[160:163], 0
	v_mfma_f32_16x16x32_bf16 v[116:119], v[144:147], v[168:171], 0
	v_mfma_f32_16x16x32_bf16 v[112:115], v[152:155], v[168:171], 0
	v_mfma_f32_16x16x32_bf16 v[84:87], v[144:147], v[176:179], 0
	v_mfma_f32_16x16x32_bf16 v[80:83], v[152:155], v[176:179], 0
	v_mfma_f32_16x16x32_bf16 v[68:71], v[144:147], v[194:197], 0
	v_mfma_f32_16x16x32_bf16 v[64:67], v[152:155], v[194:197], 0
	v_mfma_f32_16x16x32_bf16 v[132:135], v[148:151], v[164:167], v[132:135]
	v_mfma_f32_16x16x32_bf16 v[128:131], v[156:159], v[164:167], v[128:131]
	v_mfma_f32_16x16x32_bf16 v[116:119], v[148:151], v[172:175], v[116:119]
	v_mfma_f32_16x16x32_bf16 v[112:115], v[156:159], v[172:175], v[112:115]
	v_mfma_f32_16x16x32_bf16 v[84:87], v[148:151], v[190:193], v[84:87]
	v_mfma_f32_16x16x32_bf16 v[80:83], v[156:159], v[190:193], v[80:83]
	v_mfma_f32_16x16x32_bf16 v[68:71], v[148:151], v[198:201], v[68:71]
	v_mfma_f32_16x16x32_bf16 v[64:67], v[156:159], v[198:201], v[64:67]
	s_setprio 0
	s_barrier
	s_add_i32 s61, s61, s77
	v_lshl_add_u64 v[202:203], s[34:35], 0, v[232:233]
	s_mov_b32 m0, s61
	ds_read_b128 v[160:163], v221 offset:16384
	ds_read_b128 v[164:167], v221 offset:17408
	ds_read_b128 v[168:171], v221 offset:18432
	ds_read_b128 v[172:175], v221 offset:19456
	ds_read_b128 v[176:179], v221 offset:20480
	ds_read_b128 v[190:193], v221 offset:21504
	ds_read_b128 v[194:197], v221 offset:22528
	ds_read_b128 v[198:201], v221 offset:23552
	global_load_lds_dwordx4 v232, s[34:35]
	s_add_i32 m0, s61, 0x2000
	s_add_u32 s62, s34, 0x100000
	v_lshl_add_u64 v[204:205], s[34:35], 0, v[184:185]
	s_addc_u32 s63, s35, 0
	s_add_i32 s61, s64, s77
	global_load_lds_dwordx4 v184, s[34:35]
	s_mov_b32 m0, s61
	v_lshl_add_u64 v[208:209], s[36:37], 0, v[182:183]
	global_load_lds_dwordx4 v232, s[62:63]
	s_add_i32 m0, s61, 0x2000
	s_nop 0
	global_load_lds_dwordx4 v184, s[62:63]
	v_lshl_add_u64 v[206:207], s[36:37], 0, v[180:181]
	s_waitcnt vmcnt(6)
	s_waitcnt lgkmcnt(0)
	s_barrier
	s_setprio 1
	s_waitcnt lgkmcnt(0)
	v_mfma_f32_16x16x32_bf16 v[60:63], v[88:91], v[160:163], 0
	v_mfma_f32_16x16x32_bf16 v[56:59], v[96:99], v[160:163], 0
	v_mfma_f32_16x16x32_bf16 v[44:47], v[88:91], v[168:171], 0
	v_mfma_f32_16x16x32_bf16 v[40:43], v[96:99], v[168:171], 0
	v_mfma_f32_16x16x32_bf16 v[28:31], v[88:91], v[176:179], 0
	v_mfma_f32_16x16x32_bf16 v[24:27], v[96:99], v[176:179], 0
	v_mfma_f32_16x16x32_bf16 v[12:15], v[88:91], v[194:197], 0
	v_mfma_f32_16x16x32_bf16 v[8:11], v[96:99], v[194:197], 0
	v_mfma_f32_16x16x32_bf16 v[60:63], v[92:95], v[164:167], v[60:63]
	v_mfma_f32_16x16x32_bf16 v[56:59], v[100:103], v[164:167], v[56:59]
	v_mfma_f32_16x16x32_bf16 v[44:47], v[92:95], v[172:175], v[44:47]
	v_mfma_f32_16x16x32_bf16 v[40:43], v[100:103], v[172:175], v[40:43]
	v_mfma_f32_16x16x32_bf16 v[28:31], v[92:95], v[190:193], v[28:31]
	v_mfma_f32_16x16x32_bf16 v[24:27], v[100:103], v[190:193], v[24:27]
	v_mfma_f32_16x16x32_bf16 v[12:15], v[92:95], v[198:201], v[12:15]
	v_mfma_f32_16x16x32_bf16 v[8:11], v[100:103], v[198:201], v[8:11]
	s_setprio 0
	s_setprio 1
	v_mfma_f32_16x16x32_bf16 v[52:55], v[144:147], v[160:163], 0
	v_mfma_f32_16x16x32_bf16 v[48:51], v[152:155], v[160:163], 0
	v_mfma_f32_16x16x32_bf16 v[36:39], v[144:147], v[168:171], 0
	v_mfma_f32_16x16x32_bf16 v[32:35], v[152:155], v[168:171], 0
	v_mfma_f32_16x16x32_bf16 v[20:23], v[144:147], v[176:179], 0
	v_mfma_f32_16x16x32_bf16 v[16:19], v[152:155], v[176:179], 0
	v_mfma_f32_16x16x32_bf16 v[4:7], v[144:147], v[194:197], 0
	v_mfma_f32_16x16x32_bf16 v[0:3], v[152:155], v[194:197], 0
	v_mfma_f32_16x16x32_bf16 v[52:55], v[148:151], v[164:167], v[52:55]
	v_mfma_f32_16x16x32_bf16 v[48:51], v[156:159], v[164:167], v[48:51]
	v_mfma_f32_16x16x32_bf16 v[36:39], v[148:151], v[172:175], v[36:39]
	v_mfma_f32_16x16x32_bf16 v[32:35], v[156:159], v[172:175], v[32:35]
	v_mfma_f32_16x16x32_bf16 v[20:23], v[148:151], v[190:193], v[20:23]
	v_mfma_f32_16x16x32_bf16 v[16:19], v[156:159], v[190:193], v[16:19]
	v_mfma_f32_16x16x32_bf16 v[4:7], v[148:151], v[198:201], v[4:7]
	v_mfma_f32_16x16x32_bf16 v[0:3], v[156:159], v[198:201], v[0:3]
	s_setprio 0
	s_barrier
	s_branch .Lzmid_6
.LBB0_1492:
	s_add_u32 s34, s30, 0xfff00080
	s_addc_u32 s35, s31, -1
	s_add_i32 s61, 0, 0x10000
	s_cmp_eq_u32 s60, 60
	s_cselect_b32 s37, s23, s35
	s_cselect_b32 s36, s56, s34
	s_cselect_b32 s35, s21, s59
	s_cselect_b32 s34, s57, s58
	s_add_i32 s64, 0, 0x14000
	v_add_u32_e32 v100, s61, v220
	v_add_u32_e32 v156, s64, v220
	ds_read_b128 v[88:91], v100
	ds_read_b128 v[92:95], v100 offset:1024
	ds_read_b128 v[96:99], v100 offset:2048
	ds_read_b128 v[100:103], v100 offset:3072
	ds_read_b128 v[144:147], v156
	ds_read_b128 v[148:151], v156 offset:1024
	ds_read_b128 v[152:155], v156 offset:2048
	ds_read_b128 v[156:159], v156 offset:3072
	v_lshl_add_u64 v[202:203], s[30:31], 0, v[188:189]
	s_add_i32 m0, s78, 0xc000
	ds_read_b128 v[160:163], v221
	ds_read_b128 v[164:167], v221 offset:1024
	ds_read_b128 v[168:171], v221 offset:2048
	ds_read_b128 v[172:175], v221 offset:3072
	ds_read_b128 v[176:179], v221 offset:4096
	ds_read_b128 v[190:193], v221 offset:5120
	ds_read_b128 v[194:197], v221 offset:6144
	ds_read_b128 v[198:201], v221 offset:7168
	global_load_lds_dwordx4 v188, s[30:31]
	v_lshl_add_u64 v[202:203], s[30:31], 0, v[186:187]
	s_add_i32 m0, s78, 0xe000
	s_nop 0
	global_load_lds_dwordx4 v186, s[30:31]
	s_waitcnt vmcnt(8)
	s_waitcnt lgkmcnt(0)
	s_barrier
	s_setprio 1
	s_waitcnt lgkmcnt(0)
	v_mfma_f32_16x16x32_bf16 v[140:143], v[88:91], v[160:163], v[140:143]
	v_mfma_f32_16x16x32_bf16 v[136:139], v[96:99], v[160:163], v[136:139]
	v_mfma_f32_16x16x32_bf16 v[124:127], v[88:91], v[168:171], v[124:127]
	v_mfma_f32_16x16x32_bf16 v[120:123], v[96:99], v[168:171], v[120:123]
	v_mfma_f32_16x16x32_bf16 v[108:111], v[88:91], v[176:179], v[108:111]
	v_mfma_f32_16x16x32_bf16 v[104:107], v[96:99], v[176:179], v[104:107]
	v_mfma_f32_16x16x32_bf16 v[76:79], v[88:91], v[194:197], v[76:79]
	v_mfma_f32_16x16x32_bf16 v[72:75], v[96:99], v[194:197], v[72:75]
	v_mfma_f32_16x16x32_bf16 v[140:143], v[92:95], v[164:167], v[140:143]
	v_mfma_f32_16x16x32_bf16 v[136:139], v[100:103], v[164:167], v[136:139]
	v_mfma_f32_16x16x32_bf16 v[124:127], v[92:95], v[172:175], v[124:127]
	v_mfma_f32_16x16x32_bf16 v[120:123], v[100:103], v[172:175], v[120:123]
	v_mfma_f32_16x16x32_bf16 v[108:111], v[92:95], v[190:193], v[108:111]
	v_mfma_f32_16x16x32_bf16 v[104:107], v[100:103], v[190:193], v[104:107]
	v_mfma_f32_16x16x32_bf16 v[76:79], v[92:95], v[198:201], v[76:79]
	v_mfma_f32_16x16x32_bf16 v[72:75], v[100:103], v[198:201], v[72:75]
	s_setprio 0
	s_setprio 1
	v_mfma_f32_16x16x32_bf16 v[132:135], v[144:147], v[160:163], v[132:135]
	v_mfma_f32_16x16x32_bf16 v[128:131], v[152:155], v[160:163], v[128:131]
	v_mfma_f32_16x16x32_bf16 v[116:119], v[144:147], v[168:171], v[116:119]
	v_mfma_f32_16x16x32_bf16 v[112:115], v[152:155], v[168:171], v[112:115]
	v_mfma_f32_16x16x32_bf16 v[84:87], v[144:147], v[176:179], v[84:87]
	v_mfma_f32_16x16x32_bf16 v[80:83], v[152:155], v[176:179], v[80:83]
	v_mfma_f32_16x16x32_bf16 v[68:71], v[144:147], v[194:197], v[68:71]
	v_mfma_f32_16x16x32_bf16 v[64:67], v[152:155], v[194:197], v[64:67]
	v_mfma_f32_16x16x32_bf16 v[132:135], v[148:151], v[164:167], v[132:135]
	v_mfma_f32_16x16x32_bf16 v[128:131], v[156:159], v[164:167], v[128:131]
	v_mfma_f32_16x16x32_bf16 v[116:119], v[148:151], v[172:175], v[116:119]
	v_mfma_f32_16x16x32_bf16 v[112:115], v[156:159], v[172:175], v[112:115]
	v_mfma_f32_16x16x32_bf16 v[84:87], v[148:151], v[190:193], v[84:87]
	v_mfma_f32_16x16x32_bf16 v[80:83], v[156:159], v[190:193], v[80:83]
	v_mfma_f32_16x16x32_bf16 v[68:71], v[148:151], v[198:201], v[68:71]
	v_mfma_f32_16x16x32_bf16 v[64:67], v[156:159], v[198:201], v[64:67]
	s_setprio 0
	s_barrier
	s_add_i32 s61, s61, s77
	v_lshl_add_u64 v[202:203], s[34:35], 0, v[232:233]
	s_mov_b32 m0, s61
	ds_read_b128 v[160:163], v221 offset:16384
	ds_read_b128 v[164:167], v221 offset:17408
	ds_read_b128 v[168:171], v221 offset:18432
	ds_read_b128 v[172:175], v221 offset:19456
	ds_read_b128 v[176:179], v221 offset:20480
	ds_read_b128 v[190:193], v221 offset:21504
	ds_read_b128 v[194:197], v221 offset:22528
	ds_read_b128 v[198:201], v221 offset:23552
	global_load_lds_dwordx4 v232, s[34:35]
	s_add_i32 m0, s61, 0x2000
	s_add_u32 s62, s34, 0x100000
	v_lshl_add_u64 v[204:205], s[34:35], 0, v[184:185]
	s_addc_u32 s63, s35, 0
	s_add_i32 s61, s64, s77
	global_load_lds_dwordx4 v184, s[34:35]
	s_mov_b32 m0, s61
	v_lshl_add_u64 v[208:209], s[36:37], 0, v[182:183]
	global_load_lds_dwordx4 v232, s[62:63]
	s_add_i32 m0, s61, 0x2000
	s_nop 0
	global_load_lds_dwordx4 v184, s[62:63]
	v_lshl_add_u64 v[206:207], s[36:37], 0, v[180:181]
	s_waitcnt vmcnt(6)
	s_waitcnt lgkmcnt(0)
	s_barrier
	s_setprio 1
	s_waitcnt lgkmcnt(0)
	v_mfma_f32_16x16x32_bf16 v[60:63], v[88:91], v[160:163], v[60:63]
	v_mfma_f32_16x16x32_bf16 v[56:59], v[96:99], v[160:163], v[56:59]
	v_mfma_f32_16x16x32_bf16 v[44:47], v[88:91], v[168:171], v[44:47]
	v_mfma_f32_16x16x32_bf16 v[40:43], v[96:99], v[168:171], v[40:43]
	v_mfma_f32_16x16x32_bf16 v[28:31], v[88:91], v[176:179], v[28:31]
	v_mfma_f32_16x16x32_bf16 v[24:27], v[96:99], v[176:179], v[24:27]
	v_mfma_f32_16x16x32_bf16 v[12:15], v[88:91], v[194:197], v[12:15]
	v_mfma_f32_16x16x32_bf16 v[8:11], v[96:99], v[194:197], v[8:11]
	v_mfma_f32_16x16x32_bf16 v[60:63], v[92:95], v[164:167], v[60:63]
	v_mfma_f32_16x16x32_bf16 v[56:59], v[100:103], v[164:167], v[56:59]
	v_mfma_f32_16x16x32_bf16 v[44:47], v[92:95], v[172:175], v[44:47]
	v_mfma_f32_16x16x32_bf16 v[40:43], v[100:103], v[172:175], v[40:43]
	v_mfma_f32_16x16x32_bf16 v[28:31], v[92:95], v[190:193], v[28:31]
	v_mfma_f32_16x16x32_bf16 v[24:27], v[100:103], v[190:193], v[24:27]
	v_mfma_f32_16x16x32_bf16 v[12:15], v[92:95], v[198:201], v[12:15]
	v_mfma_f32_16x16x32_bf16 v[8:11], v[100:103], v[198:201], v[8:11]
	s_setprio 0
	s_setprio 1
	v_mfma_f32_16x16x32_bf16 v[52:55], v[144:147], v[160:163], v[52:55]
	v_mfma_f32_16x16x32_bf16 v[48:51], v[152:155], v[160:163], v[48:51]
	v_mfma_f32_16x16x32_bf16 v[36:39], v[144:147], v[168:171], v[36:39]
	v_mfma_f32_16x16x32_bf16 v[32:35], v[152:155], v[168:171], v[32:35]
	v_mfma_f32_16x16x32_bf16 v[20:23], v[144:147], v[176:179], v[20:23]
	v_mfma_f32_16x16x32_bf16 v[16:19], v[152:155], v[176:179], v[16:19]
	v_mfma_f32_16x16x32_bf16 v[4:7], v[144:147], v[194:197], v[4:7]
	v_mfma_f32_16x16x32_bf16 v[0:3], v[152:155], v[194:197], v[0:3]
	v_mfma_f32_16x16x32_bf16 v[52:55], v[148:151], v[164:167], v[52:55]
	v_mfma_f32_16x16x32_bf16 v[48:51], v[156:159], v[164:167], v[48:51]
	v_mfma_f32_16x16x32_bf16 v[36:39], v[148:151], v[172:175], v[36:39]
	v_mfma_f32_16x16x32_bf16 v[32:35], v[156:159], v[172:175], v[32:35]
	v_mfma_f32_16x16x32_bf16 v[20:23], v[148:151], v[190:193], v[20:23]
	v_mfma_f32_16x16x32_bf16 v[16:19], v[156:159], v[190:193], v[16:19]
	v_mfma_f32_16x16x32_bf16 v[4:7], v[148:151], v[198:201], v[4:7]
	v_mfma_f32_16x16x32_bf16 v[0:3], v[156:159], v[198:201], v[0:3]
	s_setprio 0
	s_barrier
.Lzmid_6:
	s_add_i32 s61, 0, 0x18000
	s_add_i32 s62, 0, 0x1c000
	v_add_u32_e32 v100, s61, v220
	v_add_u32_e32 v156, s62, v220
	ds_read_b128 v[88:91], v100
	ds_read_b128 v[92:95], v100 offset:1024
	ds_read_b128 v[96:99], v100 offset:2048
	ds_read_b128 v[100:103], v100 offset:3072
	ds_read_b128 v[144:147], v156
	ds_read_b128 v[148:151], v156 offset:1024
	ds_read_b128 v[152:155], v156 offset:2048
	ds_read_b128 v[156:159], v156 offset:3072
	s_add_u32 s36, s36, 0x100000
	s_addc_u32 s37, s37, 0
	s_mov_b32 m0, s78
	s_nop 0
	global_load_lds_dwordx4 v[206:207], off
	s_mov_b32 m0, s79
	s_nop 0
	global_load_lds_dwordx4 v[208:209], off
	s_mov_b32 m0, s80
	ds_read_b128 v[160:163], v221 offset:32768
	ds_read_b128 v[164:167], v221 offset:33792
	ds_read_b128 v[168:171], v221 offset:34816
	ds_read_b128 v[172:175], v221 offset:35840
	ds_read_b128 v[176:179], v221 offset:36864
	ds_read_b128 v[190:193], v221 offset:37888
	ds_read_b128 v[194:197], v221 offset:38912
	ds_read_b128 v[198:201], v221 offset:39936
	global_load_lds_dwordx4 v180, s[36:37]
	s_mov_b32 m0, s81
	s_nop 0
	global_load_lds_dwordx4 v182, s[36:37]
	s_waitcnt vmcnt(8)
	s_waitcnt lgkmcnt(0)
	s_barrier
	s_setprio 1
	s_waitcnt lgkmcnt(0)
	v_mfma_f32_16x16x32_bf16 v[140:143], v[88:91], v[160:163], v[140:143]
	v_mfma_f32_16x16x32_bf16 v[136:139], v[96:99], v[160:163], v[136:139]
	v_mfma_f32_16x16x32_bf16 v[124:127], v[88:91], v[168:171], v[124:127]
	v_mfma_f32_16x16x32_bf16 v[120:123], v[96:99], v[168:171], v[120:123]
	v_mfma_f32_16x16x32_bf16 v[108:111], v[88:91], v[176:179], v[108:111]
	v_mfma_f32_16x16x32_bf16 v[104:107], v[96:99], v[176:179], v[104:107]
	v_mfma_f32_16x16x32_bf16 v[76:79], v[88:91], v[194:197], v[76:79]
	v_mfma_f32_16x16x32_bf16 v[72:75], v[96:99], v[194:197], v[72:75]
	v_mfma_f32_16x16x32_bf16 v[140:143], v[92:95], v[164:167], v[140:143]
	v_mfma_f32_16x16x32_bf16 v[136:139], v[100:103], v[164:167], v[136:139]
	v_mfma_f32_16x16x32_bf16 v[124:127], v[92:95], v[172:175], v[124:127]
	v_mfma_f32_16x16x32_bf16 v[120:123], v[100:103], v[172:175], v[120:123]
	v_mfma_f32_16x16x32_bf16 v[108:111], v[92:95], v[190:193], v[108:111]
	v_mfma_f32_16x16x32_bf16 v[104:107], v[100:103], v[190:193], v[104:107]
	v_mfma_f32_16x16x32_bf16 v[76:79], v[92:95], v[198:201], v[76:79]
	v_mfma_f32_16x16x32_bf16 v[72:75], v[100:103], v[198:201], v[72:75]
	s_setprio 0
	s_setprio 1
	v_mfma_f32_16x16x32_bf16 v[132:135], v[144:147], v[160:163], v[132:135]
	v_mfma_f32_16x16x32_bf16 v[128:131], v[152:155], v[160:163], v[128:131]
	v_mfma_f32_16x16x32_bf16 v[116:119], v[144:147], v[168:171], v[116:119]
	v_mfma_f32_16x16x32_bf16 v[112:115], v[152:155], v[168:171], v[112:115]
	v_mfma_f32_16x16x32_bf16 v[84:87], v[144:147], v[176:179], v[84:87]
	v_mfma_f32_16x16x32_bf16 v[80:83], v[152:155], v[176:179], v[80:83]
	v_mfma_f32_16x16x32_bf16 v[68:71], v[144:147], v[194:197], v[68:71]
	v_mfma_f32_16x16x32_bf16 v[64:67], v[152:155], v[194:197], v[64:67]
	v_mfma_f32_16x16x32_bf16 v[132:135], v[148:151], v[164:167], v[132:135]
	v_mfma_f32_16x16x32_bf16 v[128:131], v[156:159], v[164:167], v[128:131]
	v_mfma_f32_16x16x32_bf16 v[116:119], v[148:151], v[172:175], v[116:119]
	v_mfma_f32_16x16x32_bf16 v[112:115], v[156:159], v[172:175], v[112:115]
	v_mfma_f32_16x16x32_bf16 v[84:87], v[148:151], v[190:193], v[84:87]
	v_mfma_f32_16x16x32_bf16 v[80:83], v[156:159], v[190:193], v[80:83]
	v_mfma_f32_16x16x32_bf16 v[68:71], v[148:151], v[198:201], v[68:71]
	v_mfma_f32_16x16x32_bf16 v[64:67], v[156:159], v[198:201], v[64:67]
	s_setprio 0
	s_barrier
	s_add_i32 s36, s61, s77
	v_lshl_add_u64 v[202:203], v[202:203], 0, s[94:95]
	s_mov_b32 m0, s36
	ds_read_b128 v[160:163], v221 offset:49152
	ds_read_b128 v[164:167], v221 offset:50176
	ds_read_b128 v[168:171], v221 offset:51200
	ds_read_b128 v[172:175], v221 offset:52224
	ds_read_b128 v[176:179], v221 offset:53248
	ds_read_b128 v[190:193], v221 offset:54272
	ds_read_b128 v[194:197], v221 offset:55296
	ds_read_b128 v[198:201], v221 offset:56320
	global_load_lds_dwordx4 v[202:203], off
	s_add_i32 m0, s36, 0x2000
	s_add_u32 s34, s34, 0x100080
	v_lshl_add_u64 v[202:203], v[204:205], 0, s[94:95]
	s_addc_u32 s35, s35, 0
	s_add_i32 s36, s62, s77
	global_load_lds_dwordx4 v[202:203], off
	s_mov_b32 m0, s36
	s_nop 0
	global_load_lds_dwordx4 v232, s[34:35]
	s_add_i32 m0, s36, 0x2000
	s_nop 0
	global_load_lds_dwordx4 v184, s[34:35]
	v_lshl_add_u64 v[202:203], v[206:207], 0, s[94:95]
	s_mov_b32 m0, s52
	s_nop 0
	global_load_lds_dwordx4 v[202:203], off
	v_lshl_add_u64 v[202:203], v[208:209], 0, s[94:95]
	s_mov_b32 m0, s53
	s_nop 0
	global_load_lds_dwordx4 v[202:203], off
	s_waitcnt vmcnt(8)
	s_waitcnt lgkmcnt(0)
	s_barrier
	s_setprio 1
	s_waitcnt lgkmcnt(0)
	v_mfma_f32_16x16x32_bf16 v[60:63], v[88:91], v[160:163], v[60:63]
	v_mfma_f32_16x16x32_bf16 v[56:59], v[96:99], v[160:163], v[56:59]
	v_mfma_f32_16x16x32_bf16 v[44:47], v[88:91], v[168:171], v[44:47]
	v_mfma_f32_16x16x32_bf16 v[40:43], v[96:99], v[168:171], v[40:43]
	v_mfma_f32_16x16x32_bf16 v[28:31], v[88:91], v[176:179], v[28:31]
	v_mfma_f32_16x16x32_bf16 v[24:27], v[96:99], v[176:179], v[24:27]
	v_mfma_f32_16x16x32_bf16 v[12:15], v[88:91], v[194:197], v[12:15]
	v_mfma_f32_16x16x32_bf16 v[8:11], v[96:99], v[194:197], v[8:11]
	v_mfma_f32_16x16x32_bf16 v[60:63], v[92:95], v[164:167], v[60:63]
	v_mfma_f32_16x16x32_bf16 v[56:59], v[100:103], v[164:167], v[56:59]
	v_mfma_f32_16x16x32_bf16 v[44:47], v[92:95], v[172:175], v[44:47]
	v_mfma_f32_16x16x32_bf16 v[40:43], v[100:103], v[172:175], v[40:43]
	v_mfma_f32_16x16x32_bf16 v[28:31], v[92:95], v[190:193], v[28:31]
	v_mfma_f32_16x16x32_bf16 v[24:27], v[100:103], v[190:193], v[24:27]
	v_mfma_f32_16x16x32_bf16 v[12:15], v[92:95], v[198:201], v[12:15]
	v_mfma_f32_16x16x32_bf16 v[8:11], v[100:103], v[198:201], v[8:11]
	s_setprio 0
	s_setprio 1
	v_mfma_f32_16x16x32_bf16 v[52:55], v[144:147], v[160:163], v[52:55]
	v_mfma_f32_16x16x32_bf16 v[48:51], v[152:155], v[160:163], v[48:51]
	v_mfma_f32_16x16x32_bf16 v[36:39], v[144:147], v[168:171], v[36:39]
	v_mfma_f32_16x16x32_bf16 v[32:35], v[152:155], v[168:171], v[32:35]
	v_mfma_f32_16x16x32_bf16 v[20:23], v[144:147], v[176:179], v[20:23]
	v_mfma_f32_16x16x32_bf16 v[16:19], v[152:155], v[176:179], v[16:19]
	v_mfma_f32_16x16x32_bf16 v[4:7], v[144:147], v[194:197], v[4:7]
	v_mfma_f32_16x16x32_bf16 v[0:3], v[152:155], v[194:197], v[0:3]
	v_mfma_f32_16x16x32_bf16 v[52:55], v[148:151], v[164:167], v[52:55]
	v_mfma_f32_16x16x32_bf16 v[48:51], v[156:159], v[164:167], v[48:51]
	v_mfma_f32_16x16x32_bf16 v[36:39], v[148:151], v[172:175], v[36:39]
	v_mfma_f32_16x16x32_bf16 v[32:35], v[156:159], v[172:175], v[32:35]
	v_mfma_f32_16x16x32_bf16 v[20:23], v[148:151], v[190:193], v[20:23]
	v_mfma_f32_16x16x32_bf16 v[16:19], v[156:159], v[190:193], v[16:19]
	v_mfma_f32_16x16x32_bf16 v[4:7], v[148:151], v[198:201], v[4:7]
	v_mfma_f32_16x16x32_bf16 v[0:3], v[156:159], v[198:201], v[0:3]
	s_setprio 0
	s_barrier
	s_add_i32 s60, s60, 2
	s_add_u32 s58, s58, 0x100
	s_addc_u32 s59, s59, 0
	s_add_u32 s30, s30, 0x100
	s_addc_u32 s31, s31, 0
	s_cmp_gt_u32 s60, 61
	s_cbranch_scc0 .LBB0_1492
	s_and_b64 vcc, exec, s[18:19]
	s_cbranch_vccz .LBB0_1495
	s_barrier
